# strategy 9 (loop-edge rotation): next chunk's producer global loads issued before the chunk barrier instead of at the loop head; drained at loop exit
# speedup vs baseline: 1.0032x; 1.0032x over previous
.Lret2_gw2:
	s_mov_b32 s20, 0xffff0000
	s_mov_b32 s21, -1
	v_mov_b32_e32 v41, v26
	v_mul_f32_e32 v41, v41, v41
	v_mul_f32_e32 v41, v41, v41
	v_mul_f32_e32 v41, v41, v41
	v_mul_f32_e32 v41, v41, v41
	v_mul_f32_e32 v41, v41, v41
	v_mul_f32_e32 v41, v41, v41
	v_mul_f32_e32 v41, v41, v41
	v_mul_f32_e32 v41, v41, v41
	global_load_dword v84, v32, s[10:11]
	global_load_dword v85, v32, s[10:11] offset:-1024
	global_load_dword v86, v33, s[10:11]
	global_load_dword v87, v33, s[10:11] offset:-1024
	global_load_dword v88, v34, s[10:11]
	global_load_dword v90, v35, s[12:13]
	global_load_dword v91, v35, s[12:13] offset:4
	s_add_u32 s10, s10, 0x18000
	s_addc_u32 s11, s11, 0
	s_add_u32 s12, s12, 0x4000
	s_addc_u32 s13, s13, 0
	s_waitcnt vmcnt(0)
	v_lshlrev_b32_e32 v108, 16, v84
	v_lshlrev_b32_e32 v109, 16, v85
	v_and_b32_e32 v110, s17, v84
	v_and_b32_e32 v111, s17, v85
	v_lshlrev_b32_e32 v112, 16, v86
	v_lshlrev_b32_e32 v113, 16, v87
	v_and_b32_e32 v114, s17, v86
	v_and_b32_e32 v115, s17, v87
	v_lshlrev_b32_e32 v116, 16, v88
	v_and_b32_e32 v117, s17, v88
	v_rcp_f32_e32 v25, v24
	v_mul_f32_e32 v113, v24, v113
	v_mul_f32_e32 v115, v24, v115
	v_mul_f32_e32 v109, 0x3db504f3, v109
	v_mul_f32_e32 v111, 0x3db504f3, v111
	v_cndmask_b32_e64 v27, 1.0, v25, s[20:21]
	v_mul_f32_e32 v24, v24, v26
	v_mul_f32_e32 v116, v27, v116
	v_mul_f32_e32 v117, v27, v117
	ds_write_b128 v29, v[108:111] offset:256
	ds_write_b128 v29, v[112:115] offset:8448
	ds_write_b64 v30, v[90:91] offset:256
	ds_write_b64 v31, v[116:117] offset:256
	global_load_dword v84, v32, s[10:11]
	global_load_dword v85, v32, s[10:11] offset:-1024
	global_load_dword v86, v33, s[10:11]
	global_load_dword v87, v33, s[10:11] offset:-1024
	global_load_dword v88, v34, s[10:11]
	global_load_dword v90, v35, s[12:13]
	global_load_dword v91, v35, s[12:13] offset:4
	s_add_u32 s10, s10, 0x18000
	s_addc_u32 s11, s11, 0
	s_add_u32 s12, s12, 0x4000
	s_addc_u32 s13, s13, 0
	s_waitcnt vmcnt(0)
	v_lshlrev_b32_e32 v108, 16, v84
	v_lshlrev_b32_e32 v109, 16, v85
	v_and_b32_e32 v110, s17, v84
	v_and_b32_e32 v111, s17, v85
	v_lshlrev_b32_e32 v112, 16, v86
	v_lshlrev_b32_e32 v113, 16, v87
	v_and_b32_e32 v114, s17, v86
	v_and_b32_e32 v115, s17, v87
	v_lshlrev_b32_e32 v116, 16, v88
	v_and_b32_e32 v117, s17, v88
	v_rcp_f32_e32 v25, v24
	v_mul_f32_e32 v113, v24, v113
	v_mul_f32_e32 v115, v24, v115
	v_mul_f32_e32 v109, 0x3db504f3, v109
	v_mul_f32_e32 v111, 0x3db504f3, v111
	v_cndmask_b32_e64 v27, 1.0, v25, s[20:21]
	v_mul_f32_e32 v24, v24, v26
	v_mul_f32_e32 v116, v27, v116
	v_mul_f32_e32 v117, v27, v117
	ds_write_b128 v29, v[108:111] offset:24832
	ds_write_b128 v29, v[112:115] offset:33024
	ds_write_b64 v30, v[90:91] offset:24832
	ds_write_b64 v31, v[116:117] offset:24832
	global_load_dword v84, v32, s[10:11]
	global_load_dword v85, v32, s[10:11] offset:-1024
	global_load_dword v86, v33, s[10:11]
	global_load_dword v87, v33, s[10:11] offset:-1024
	global_load_dword v88, v34, s[10:11]
	global_load_dword v90, v35, s[12:13]
	global_load_dword v91, v35, s[12:13] offset:4
	s_add_u32 s10, s10, 0x18000
	s_addc_u32 s11, s11, 0
	s_add_u32 s12, s12, 0x4000
	s_addc_u32 s13, s13, 0
	v_add_u32_e32 v22, 0x8000, v2
	v_add_u32_e32 v23, 0x8000, v3
	v_mov_b32_e32 v6, 0
	v_mov_b32_e32 v7, 0
	v_mov_b32_e32 v8, 0
	v_mov_b32_e32 v9, 0
	v_mov_b32_e32 v10, 0
	v_mov_b32_e32 v11, 0
	v_mov_b32_e32 v12, 0
	v_mov_b32_e32 v13, 0
	v_mov_b32_e32 v14, 0
	v_mov_b32_e32 v15, 0
	v_mov_b32_e32 v16, 0
	v_mov_b32_e32 v17, 0
	v_mov_b32_e32 v18, 0
	v_mov_b32_e32 v19, 0
	v_mov_b32_e32 v20, 0
	v_mov_b32_e32 v21, 0
	s_mov_b32 s16, 0
	s_mov_b32 s2, 0x01010101
	s_mov_b32 s3, 0x01010101
	v_and_b32_e32 v28, 8, v198
	v_lshrrev_b32_e32 v28, 2, v28
	v_add_u32_e32 v28, v46, v28
	s_waitcnt vmcnt(0) lgkmcnt(0)
	s_barrier
	ds_read_b64 v[64:65], v3 offset:20736
	ds_read_b128 v[48:51], v2 offset:8448
	ds_read_b128 v[52:55], v2 offset:8704
	ds_read_b128 v[56:59], v2 offset:8960
	ds_read_b128 v[60:63], v2 offset:9216
.Lret2_loop:
	s_waitcnt lgkmcnt(3)
	v_pk_fma_f32 v[6:7], v[64:65], v[48:49], v[6:7] op_sel_hi:[1,0,1]
	v_pk_mul_f32 v[38:39], v[6:7], v[48:49] op_sel:[0,1] op_sel_hi:[1,1]
	v_pk_fma_f32 v[8:9], v[64:65], v[50:51], v[8:9] op_sel_hi:[1,0,1]
	v_pk_fma_f32 v[38:39], v[8:9], v[50:51], v[38:39] op_sel:[0,1,0] op_sel_hi:[1,1,1]
	s_waitcnt lgkmcnt(2)
	v_pk_fma_f32 v[10:11], v[64:65], v[52:53], v[10:11] op_sel_hi:[1,0,1]
	v_pk_fma_f32 v[38:39], v[10:11], v[52:53], v[38:39] op_sel:[0,1,0] op_sel_hi:[1,1,1]
	v_pk_fma_f32 v[12:13], v[64:65], v[54:55], v[12:13] op_sel_hi:[1,0,1]
	v_pk_fma_f32 v[38:39], v[12:13], v[54:55], v[38:39] op_sel:[0,1,0] op_sel_hi:[1,1,1]
	s_waitcnt lgkmcnt(1)
	v_pk_fma_f32 v[14:15], v[64:65], v[56:57], v[14:15] op_sel_hi:[1,0,1]
	v_pk_fma_f32 v[38:39], v[14:15], v[56:57], v[38:39] op_sel:[0,1,0] op_sel_hi:[1,1,1]
	v_pk_fma_f32 v[16:17], v[64:65], v[58:59], v[16:17] op_sel_hi:[1,0,1]
	v_pk_fma_f32 v[38:39], v[16:17], v[58:59], v[38:39] op_sel:[0,1,0] op_sel_hi:[1,1,1]
	s_waitcnt lgkmcnt(0)
	v_pk_fma_f32 v[18:19], v[64:65], v[60:61], v[18:19] op_sel_hi:[1,0,1]
	v_pk_fma_f32 v[38:39], v[18:19], v[60:61], v[38:39] op_sel:[0,1,0] op_sel_hi:[1,1,1]
	v_pk_fma_f32 v[20:21], v[64:65], v[62:63], v[20:21] op_sel_hi:[1,0,1]
	v_pk_fma_f32 v[38:39], v[20:21], v[62:63], v[38:39] op_sel:[0,1,0] op_sel_hi:[1,1,1]
	s_add_u32 s14, s14, 0x1000
	s_addc_u32 s15, s15, 0
	v_add_f32_dpp v38, v38, v38 row_ror:8 row_mask:0xf bank_mask:0x3 bound_ctrl:1
	v_add_f32_dpp v38, v39, v39 row_ror:8 row_mask:0xf bank_mask:0xc bound_ctrl:1
	ds_read_b64 v[82:83], v3 offset:20992
	ds_read_b128 v[66:69], v2 offset:9472
	v_add_f32_dpp v38, v38, v38 row_half_mirror row_mask:0xf bank_mask:0xf bound_ctrl:1
	ds_read_b128 v[70:73], v2 offset:9728
	ds_read_b128 v[74:77], v2 offset:9984
	v_add_f32_dpp v38, v38, v38 quad_perm:[1,0,3,2] row_mask:0xf bank_mask:0xf bound_ctrl:1
	ds_read_b128 v[78:81], v2 offset:10240
	s_nop 0
	v_add_f32_dpp v38, v38, v38 quad_perm:[2,3,0,1] row_mask:0xf bank_mask:0xf bound_ctrl:1
	v_cvt_pk_bf16_f32 v47, v38, v38
	s_mov_b64 exec, s[2:3]
	global_store_short v28, v47, s[14:15] offset:-4096
	s_mov_b64 exec, -1
	s_waitcnt lgkmcnt(3)
	v_pk_fma_f32 v[6:7], v[82:83], v[66:67], v[6:7] op_sel_hi:[1,0,1]
	v_pk_mul_f32 v[38:39], v[6:7], v[66:67] op_sel:[0,1] op_sel_hi:[1,1]
	v_pk_fma_f32 v[8:9], v[82:83], v[68:69], v[8:9] op_sel_hi:[1,0,1]
	v_pk_fma_f32 v[38:39], v[8:9], v[68:69], v[38:39] op_sel:[0,1,0] op_sel_hi:[1,1,1]
	s_waitcnt lgkmcnt(2)
	v_pk_fma_f32 v[10:11], v[82:83], v[70:71], v[10:11] op_sel_hi:[1,0,1]
	v_pk_fma_f32 v[38:39], v[10:11], v[70:71], v[38:39] op_sel:[0,1,0] op_sel_hi:[1,1,1]
	v_pk_fma_f32 v[12:13], v[82:83], v[72:73], v[12:13] op_sel_hi:[1,0,1]
	v_pk_fma_f32 v[38:39], v[12:13], v[72:73], v[38:39] op_sel:[0,1,0] op_sel_hi:[1,1,1]
	s_waitcnt lgkmcnt(1)
	v_pk_fma_f32 v[14:15], v[82:83], v[74:75], v[14:15] op_sel_hi:[1,0,1]
	v_pk_fma_f32 v[38:39], v[14:15], v[74:75], v[38:39] op_sel:[0,1,0] op_sel_hi:[1,1,1]
	v_pk_fma_f32 v[16:17], v[82:83], v[76:77], v[16:17] op_sel_hi:[1,0,1]
	v_pk_fma_f32 v[38:39], v[16:17], v[76:77], v[38:39] op_sel:[0,1,0] op_sel_hi:[1,1,1]
	s_waitcnt lgkmcnt(0)
	v_pk_fma_f32 v[18:19], v[82:83], v[78:79], v[18:19] op_sel_hi:[1,0,1]
	v_pk_fma_f32 v[38:39], v[18:19], v[78:79], v[38:39] op_sel:[0,1,0] op_sel_hi:[1,1,1]
	v_pk_fma_f32 v[20:21], v[82:83], v[80:81], v[20:21] op_sel_hi:[1,0,1]
	v_pk_fma_f32 v[38:39], v[20:21], v[80:81], v[38:39] op_sel:[0,1,0] op_sel_hi:[1,1,1]
	s_add_u32 s14, s14, 0x1000
	s_addc_u32 s15, s15, 0
	v_add_f32_dpp v38, v38, v38 row_ror:8 row_mask:0xf bank_mask:0x3 bound_ctrl:1
	v_add_f32_dpp v38, v39, v39 row_ror:8 row_mask:0xf bank_mask:0xc bound_ctrl:1
	ds_read_b64 v[64:65], v3 offset:21248
	ds_read_b128 v[48:51], v2 offset:10496
	v_add_f32_dpp v38, v38, v38 row_half_mirror row_mask:0xf bank_mask:0xf bound_ctrl:1
	ds_read_b128 v[52:55], v2 offset:10752
	ds_read_b128 v[56:59], v2 offset:11008
	v_add_f32_dpp v38, v38, v38 quad_perm:[1,0,3,2] row_mask:0xf bank_mask:0xf bound_ctrl:1
	ds_read_b128 v[60:63], v2 offset:11264
	s_nop 0
	v_add_f32_dpp v38, v38, v38 quad_perm:[2,3,0,1] row_mask:0xf bank_mask:0xf bound_ctrl:1
	v_cvt_pk_bf16_f32 v47, v38, v38
	s_mov_b64 exec, s[2:3]
	global_store_short v28, v47, s[14:15] offset:-4096
	s_mov_b64 exec, -1
	s_waitcnt lgkmcnt(3)
	v_pk_fma_f32 v[6:7], v[64:65], v[48:49], v[6:7] op_sel_hi:[1,0,1]
	v_pk_mul_f32 v[38:39], v[6:7], v[48:49] op_sel:[0,1] op_sel_hi:[1,1]
	v_pk_fma_f32 v[8:9], v[64:65], v[50:51], v[8:9] op_sel_hi:[1,0,1]
	v_pk_fma_f32 v[38:39], v[8:9], v[50:51], v[38:39] op_sel:[0,1,0] op_sel_hi:[1,1,1]
	s_waitcnt lgkmcnt(2)
	v_pk_fma_f32 v[10:11], v[64:65], v[52:53], v[10:11] op_sel_hi:[1,0,1]
	v_pk_fma_f32 v[38:39], v[10:11], v[52:53], v[38:39] op_sel:[0,1,0] op_sel_hi:[1,1,1]
	v_pk_fma_f32 v[12:13], v[64:65], v[54:55], v[12:13] op_sel_hi:[1,0,1]
	v_pk_fma_f32 v[38:39], v[12:13], v[54:55], v[38:39] op_sel:[0,1,0] op_sel_hi:[1,1,1]
	s_waitcnt lgkmcnt(1)
	v_pk_fma_f32 v[14:15], v[64:65], v[56:57], v[14:15] op_sel_hi:[1,0,1]
	v_pk_fma_f32 v[38:39], v[14:15], v[56:57], v[38:39] op_sel:[0,1,0] op_sel_hi:[1,1,1]
	v_pk_fma_f32 v[16:17], v[64:65], v[58:59], v[16:17] op_sel_hi:[1,0,1]
	v_pk_fma_f32 v[38:39], v[16:17], v[58:59], v[38:39] op_sel:[0,1,0] op_sel_hi:[1,1,1]
	s_waitcnt lgkmcnt(0)
	v_pk_fma_f32 v[18:19], v[64:65], v[60:61], v[18:19] op_sel_hi:[1,0,1]
	v_pk_fma_f32 v[38:39], v[18:19], v[60:61], v[38:39] op_sel:[0,1,0] op_sel_hi:[1,1,1]
	v_pk_fma_f32 v[20:21], v[64:65], v[62:63], v[20:21] op_sel_hi:[1,0,1]
	v_pk_fma_f32 v[38:39], v[20:21], v[62:63], v[38:39] op_sel:[0,1,0] op_sel_hi:[1,1,1]
	s_add_u32 s14, s14, 0x1000
	s_addc_u32 s15, s15, 0
	v_add_f32_dpp v38, v38, v38 row_ror:8 row_mask:0xf bank_mask:0x3 bound_ctrl:1
	v_add_f32_dpp v38, v39, v39 row_ror:8 row_mask:0xf bank_mask:0xc bound_ctrl:1
	ds_read_b64 v[82:83], v3 offset:21504
	ds_read_b128 v[66:69], v2 offset:11520
	v_add_f32_dpp v38, v38, v38 row_half_mirror row_mask:0xf bank_mask:0xf bound_ctrl:1
	ds_read_b128 v[70:73], v2 offset:11776
	ds_read_b128 v[74:77], v2 offset:12032
	v_add_f32_dpp v38, v38, v38 quad_perm:[1,0,3,2] row_mask:0xf bank_mask:0xf bound_ctrl:1
	ds_read_b128 v[78:81], v2 offset:12288
	s_nop 0
	v_add_f32_dpp v38, v38, v38 quad_perm:[2,3,0,1] row_mask:0xf bank_mask:0xf bound_ctrl:1
	v_cvt_pk_bf16_f32 v47, v38, v38
	s_mov_b64 exec, s[2:3]
	global_store_short v28, v47, s[14:15] offset:-4096
	s_mov_b64 exec, -1
	s_waitcnt lgkmcnt(3)
	v_pk_fma_f32 v[6:7], v[82:83], v[66:67], v[6:7] op_sel_hi:[1,0,1]
	v_pk_mul_f32 v[38:39], v[6:7], v[66:67] op_sel:[0,1] op_sel_hi:[1,1]
	v_pk_fma_f32 v[8:9], v[82:83], v[68:69], v[8:9] op_sel_hi:[1,0,1]
	v_pk_fma_f32 v[38:39], v[8:9], v[68:69], v[38:39] op_sel:[0,1,0] op_sel_hi:[1,1,1]
	s_waitcnt lgkmcnt(2)
	v_pk_fma_f32 v[10:11], v[82:83], v[70:71], v[10:11] op_sel_hi:[1,0,1]
	v_pk_fma_f32 v[38:39], v[10:11], v[70:71], v[38:39] op_sel:[0,1,0] op_sel_hi:[1,1,1]
	v_pk_fma_f32 v[12:13], v[82:83], v[72:73], v[12:13] op_sel_hi:[1,0,1]
	v_pk_fma_f32 v[38:39], v[12:13], v[72:73], v[38:39] op_sel:[0,1,0] op_sel_hi:[1,1,1]
	s_waitcnt lgkmcnt(1)
	v_pk_fma_f32 v[14:15], v[82:83], v[74:75], v[14:15] op_sel_hi:[1,0,1]
	v_pk_fma_f32 v[38:39], v[14:15], v[74:75], v[38:39] op_sel:[0,1,0] op_sel_hi:[1,1,1]
	v_pk_fma_f32 v[16:17], v[82:83], v[76:77], v[16:17] op_sel_hi:[1,0,1]
	v_pk_fma_f32 v[38:39], v[16:17], v[76:77], v[38:39] op_sel:[0,1,0] op_sel_hi:[1,1,1]
	s_waitcnt lgkmcnt(0)
	v_pk_fma_f32 v[18:19], v[82:83], v[78:79], v[18:19] op_sel_hi:[1,0,1]
	v_pk_fma_f32 v[38:39], v[18:19], v[78:79], v[38:39] op_sel:[0,1,0] op_sel_hi:[1,1,1]
	v_pk_fma_f32 v[20:21], v[82:83], v[80:81], v[20:21] op_sel_hi:[1,0,1]
	v_pk_fma_f32 v[38:39], v[20:21], v[80:81], v[38:39] op_sel:[0,1,0] op_sel_hi:[1,1,1]
	s_add_u32 s14, s14, 0x1000
	s_addc_u32 s15, s15, 0
	v_add_f32_dpp v38, v38, v38 row_ror:8 row_mask:0xf bank_mask:0x3 bound_ctrl:1
	v_add_f32_dpp v38, v39, v39 row_ror:8 row_mask:0xf bank_mask:0xc bound_ctrl:1
	ds_read_b64 v[64:65], v3 offset:21760
	ds_read_b128 v[48:51], v2 offset:12544
	v_add_f32_dpp v38, v38, v38 row_half_mirror row_mask:0xf bank_mask:0xf bound_ctrl:1
	ds_read_b128 v[52:55], v2 offset:12800
	ds_read_b128 v[56:59], v2 offset:13056
	v_add_f32_dpp v38, v38, v38 quad_perm:[1,0,3,2] row_mask:0xf bank_mask:0xf bound_ctrl:1
	ds_read_b128 v[60:63], v2 offset:13312
	s_nop 0
	v_add_f32_dpp v38, v38, v38 quad_perm:[2,3,0,1] row_mask:0xf bank_mask:0xf bound_ctrl:1
	v_cvt_pk_bf16_f32 v47, v38, v38
	s_mov_b64 exec, s[2:3]
	global_store_short v28, v47, s[14:15] offset:-4096
	s_mov_b64 exec, -1
	s_waitcnt lgkmcnt(3)
	v_pk_fma_f32 v[6:7], v[64:65], v[48:49], v[6:7] op_sel_hi:[1,0,1]
	v_pk_mul_f32 v[38:39], v[6:7], v[48:49] op_sel:[0,1] op_sel_hi:[1,1]
	v_pk_fma_f32 v[8:9], v[64:65], v[50:51], v[8:9] op_sel_hi:[1,0,1]
	v_pk_fma_f32 v[38:39], v[8:9], v[50:51], v[38:39] op_sel:[0,1,0] op_sel_hi:[1,1,1]
	s_waitcnt lgkmcnt(2)
	v_pk_fma_f32 v[10:11], v[64:65], v[52:53], v[10:11] op_sel_hi:[1,0,1]
	v_pk_fma_f32 v[38:39], v[10:11], v[52:53], v[38:39] op_sel:[0,1,0] op_sel_hi:[1,1,1]
	v_pk_fma_f32 v[12:13], v[64:65], v[54:55], v[12:13] op_sel_hi:[1,0,1]
	v_pk_fma_f32 v[38:39], v[12:13], v[54:55], v[38:39] op_sel:[0,1,0] op_sel_hi:[1,1,1]
	s_waitcnt lgkmcnt(1)
	v_pk_fma_f32 v[14:15], v[64:65], v[56:57], v[14:15] op_sel_hi:[1,0,1]
	v_pk_fma_f32 v[38:39], v[14:15], v[56:57], v[38:39] op_sel:[0,1,0] op_sel_hi:[1,1,1]
	v_pk_fma_f32 v[16:17], v[64:65], v[58:59], v[16:17] op_sel_hi:[1,0,1]
	v_pk_fma_f32 v[38:39], v[16:17], v[58:59], v[38:39] op_sel:[0,1,0] op_sel_hi:[1,1,1]
	s_waitcnt lgkmcnt(0)
	v_pk_fma_f32 v[18:19], v[64:65], v[60:61], v[18:19] op_sel_hi:[1,0,1]
	v_pk_fma_f32 v[38:39], v[18:19], v[60:61], v[38:39] op_sel:[0,1,0] op_sel_hi:[1,1,1]
	v_pk_fma_f32 v[20:21], v[64:65], v[62:63], v[20:21] op_sel_hi:[1,0,1]
	v_pk_fma_f32 v[38:39], v[20:21], v[62:63], v[38:39] op_sel:[0,1,0] op_sel_hi:[1,1,1]
	s_add_u32 s14, s14, 0x1000
	s_addc_u32 s15, s15, 0
	v_add_f32_dpp v38, v38, v38 row_ror:8 row_mask:0xf bank_mask:0x3 bound_ctrl:1
	v_add_f32_dpp v38, v39, v39 row_ror:8 row_mask:0xf bank_mask:0xc bound_ctrl:1
	ds_read_b64 v[82:83], v3 offset:22016
	ds_read_b128 v[66:69], v2 offset:13568
	v_add_f32_dpp v38, v38, v38 row_half_mirror row_mask:0xf bank_mask:0xf bound_ctrl:1
	ds_read_b128 v[70:73], v2 offset:13824
	ds_read_b128 v[74:77], v2 offset:14080
	v_add_f32_dpp v38, v38, v38 quad_perm:[1,0,3,2] row_mask:0xf bank_mask:0xf bound_ctrl:1
	ds_read_b128 v[78:81], v2 offset:14336
	s_nop 0
	v_add_f32_dpp v38, v38, v38 quad_perm:[2,3,0,1] row_mask:0xf bank_mask:0xf bound_ctrl:1
	v_cvt_pk_bf16_f32 v47, v38, v38
	s_mov_b64 exec, s[2:3]
	global_store_short v28, v47, s[14:15] offset:-4096
	s_mov_b64 exec, -1
	s_waitcnt lgkmcnt(3)
	v_pk_fma_f32 v[6:7], v[82:83], v[66:67], v[6:7] op_sel_hi:[1,0,1]
	v_pk_mul_f32 v[38:39], v[6:7], v[66:67] op_sel:[0,1] op_sel_hi:[1,1]
	v_pk_fma_f32 v[8:9], v[82:83], v[68:69], v[8:9] op_sel_hi:[1,0,1]
	v_pk_fma_f32 v[38:39], v[8:9], v[68:69], v[38:39] op_sel:[0,1,0] op_sel_hi:[1,1,1]
	s_waitcnt lgkmcnt(2)
	v_pk_fma_f32 v[10:11], v[82:83], v[70:71], v[10:11] op_sel_hi:[1,0,1]
	v_pk_fma_f32 v[38:39], v[10:11], v[70:71], v[38:39] op_sel:[0,1,0] op_sel_hi:[1,1,1]
	v_pk_fma_f32 v[12:13], v[82:83], v[72:73], v[12:13] op_sel_hi:[1,0,1]
	v_pk_fma_f32 v[38:39], v[12:13], v[72:73], v[38:39] op_sel:[0,1,0] op_sel_hi:[1,1,1]
	s_waitcnt lgkmcnt(1)
	v_pk_fma_f32 v[14:15], v[82:83], v[74:75], v[14:15] op_sel_hi:[1,0,1]
	v_pk_fma_f32 v[38:39], v[14:15], v[74:75], v[38:39] op_sel:[0,1,0] op_sel_hi:[1,1,1]
	v_pk_fma_f32 v[16:17], v[82:83], v[76:77], v[16:17] op_sel_hi:[1,0,1]
	v_pk_fma_f32 v[38:39], v[16:17], v[76:77], v[38:39] op_sel:[0,1,0] op_sel_hi:[1,1,1]
	s_waitcnt lgkmcnt(0)
	v_pk_fma_f32 v[18:19], v[82:83], v[78:79], v[18:19] op_sel_hi:[1,0,1]
	v_pk_fma_f32 v[38:39], v[18:19], v[78:79], v[38:39] op_sel:[0,1,0] op_sel_hi:[1,1,1]
	v_pk_fma_f32 v[20:21], v[82:83], v[80:81], v[20:21] op_sel_hi:[1,0,1]
	v_pk_fma_f32 v[38:39], v[20:21], v[80:81], v[38:39] op_sel:[0,1,0] op_sel_hi:[1,1,1]
	s_add_u32 s14, s14, 0x1000
	s_addc_u32 s15, s15, 0
	v_add_f32_dpp v38, v38, v38 row_ror:8 row_mask:0xf bank_mask:0x3 bound_ctrl:1
	v_add_f32_dpp v38, v39, v39 row_ror:8 row_mask:0xf bank_mask:0xc bound_ctrl:1
	ds_read_b64 v[64:65], v3 offset:22272
	ds_read_b128 v[48:51], v2 offset:14592
	v_add_f32_dpp v38, v38, v38 row_half_mirror row_mask:0xf bank_mask:0xf bound_ctrl:1
	ds_read_b128 v[52:55], v2 offset:14848
	ds_read_b128 v[56:59], v2 offset:15104
	v_add_f32_dpp v38, v38, v38 quad_perm:[1,0,3,2] row_mask:0xf bank_mask:0xf bound_ctrl:1
	ds_read_b128 v[60:63], v2 offset:15360
	s_nop 0
	v_add_f32_dpp v38, v38, v38 quad_perm:[2,3,0,1] row_mask:0xf bank_mask:0xf bound_ctrl:1
	v_cvt_pk_bf16_f32 v47, v38, v38
	s_mov_b64 exec, s[2:3]
	global_store_short v28, v47, s[14:15] offset:-4096
	s_mov_b64 exec, -1
	s_waitcnt lgkmcnt(3)
	v_pk_fma_f32 v[6:7], v[64:65], v[48:49], v[6:7] op_sel_hi:[1,0,1]
	v_pk_mul_f32 v[38:39], v[6:7], v[48:49] op_sel:[0,1] op_sel_hi:[1,1]
	v_pk_fma_f32 v[8:9], v[64:65], v[50:51], v[8:9] op_sel_hi:[1,0,1]
	v_pk_fma_f32 v[38:39], v[8:9], v[50:51], v[38:39] op_sel:[0,1,0] op_sel_hi:[1,1,1]
	s_waitcnt lgkmcnt(2)
	v_pk_fma_f32 v[10:11], v[64:65], v[52:53], v[10:11] op_sel_hi:[1,0,1]
	v_pk_fma_f32 v[38:39], v[10:11], v[52:53], v[38:39] op_sel:[0,1,0] op_sel_hi:[1,1,1]
	v_pk_fma_f32 v[12:13], v[64:65], v[54:55], v[12:13] op_sel_hi:[1,0,1]
	v_pk_fma_f32 v[38:39], v[12:13], v[54:55], v[38:39] op_sel:[0,1,0] op_sel_hi:[1,1,1]
	s_waitcnt lgkmcnt(1)
	v_pk_fma_f32 v[14:15], v[64:65], v[56:57], v[14:15] op_sel_hi:[1,0,1]
	v_pk_fma_f32 v[38:39], v[14:15], v[56:57], v[38:39] op_sel:[0,1,0] op_sel_hi:[1,1,1]
	v_pk_fma_f32 v[16:17], v[64:65], v[58:59], v[16:17] op_sel_hi:[1,0,1]
	v_pk_fma_f32 v[38:39], v[16:17], v[58:59], v[38:39] op_sel:[0,1,0] op_sel_hi:[1,1,1]
	s_waitcnt lgkmcnt(0)
	v_pk_fma_f32 v[18:19], v[64:65], v[60:61], v[18:19] op_sel_hi:[1,0,1]
	v_pk_fma_f32 v[38:39], v[18:19], v[60:61], v[38:39] op_sel:[0,1,0] op_sel_hi:[1,1,1]
	v_pk_fma_f32 v[20:21], v[64:65], v[62:63], v[20:21] op_sel_hi:[1,0,1]
	v_pk_fma_f32 v[38:39], v[20:21], v[62:63], v[38:39] op_sel:[0,1,0] op_sel_hi:[1,1,1]
	s_add_u32 s14, s14, 0x1000
	s_addc_u32 s15, s15, 0
	v_add_f32_dpp v38, v38, v38 row_ror:8 row_mask:0xf bank_mask:0x3 bound_ctrl:1
	v_add_f32_dpp v38, v39, v39 row_ror:8 row_mask:0xf bank_mask:0xc bound_ctrl:1
	ds_read_b64 v[82:83], v3 offset:22528
	ds_read_b128 v[66:69], v2 offset:15616
	v_add_f32_dpp v38, v38, v38 row_half_mirror row_mask:0xf bank_mask:0xf bound_ctrl:1
	ds_read_b128 v[70:73], v2 offset:15872
	ds_read_b128 v[74:77], v2 offset:16128
	v_add_f32_dpp v38, v38, v38 quad_perm:[1,0,3,2] row_mask:0xf bank_mask:0xf bound_ctrl:1
	ds_read_b128 v[78:81], v2 offset:16384
	s_nop 0
	v_add_f32_dpp v38, v38, v38 quad_perm:[2,3,0,1] row_mask:0xf bank_mask:0xf bound_ctrl:1
	v_cvt_pk_bf16_f32 v47, v38, v38
	s_mov_b64 exec, s[2:3]
	global_store_short v28, v47, s[14:15] offset:-4096
	s_mov_b64 exec, -1
	s_waitcnt lgkmcnt(3)
	v_pk_fma_f32 v[6:7], v[82:83], v[66:67], v[6:7] op_sel_hi:[1,0,1]
	v_pk_mul_f32 v[38:39], v[6:7], v[66:67] op_sel:[0,1] op_sel_hi:[1,1]
	v_pk_fma_f32 v[8:9], v[82:83], v[68:69], v[8:9] op_sel_hi:[1,0,1]
	v_pk_fma_f32 v[38:39], v[8:9], v[68:69], v[38:39] op_sel:[0,1,0] op_sel_hi:[1,1,1]
	s_waitcnt lgkmcnt(2)
	v_pk_fma_f32 v[10:11], v[82:83], v[70:71], v[10:11] op_sel_hi:[1,0,1]
	v_pk_fma_f32 v[38:39], v[10:11], v[70:71], v[38:39] op_sel:[0,1,0] op_sel_hi:[1,1,1]
	v_pk_fma_f32 v[12:13], v[82:83], v[72:73], v[12:13] op_sel_hi:[1,0,1]
	v_pk_fma_f32 v[38:39], v[12:13], v[72:73], v[38:39] op_sel:[0,1,0] op_sel_hi:[1,1,1]
	s_waitcnt lgkmcnt(1)
	v_pk_fma_f32 v[14:15], v[82:83], v[74:75], v[14:15] op_sel_hi:[1,0,1]
	v_pk_fma_f32 v[38:39], v[14:15], v[74:75], v[38:39] op_sel:[0,1,0] op_sel_hi:[1,1,1]
	v_pk_fma_f32 v[16:17], v[82:83], v[76:77], v[16:17] op_sel_hi:[1,0,1]
	v_pk_fma_f32 v[38:39], v[16:17], v[76:77], v[38:39] op_sel:[0,1,0] op_sel_hi:[1,1,1]
	s_waitcnt lgkmcnt(0)
	v_pk_fma_f32 v[18:19], v[82:83], v[78:79], v[18:19] op_sel_hi:[1,0,1]
	v_pk_fma_f32 v[38:39], v[18:19], v[78:79], v[38:39] op_sel:[0,1,0] op_sel_hi:[1,1,1]
	v_pk_fma_f32 v[20:21], v[82:83], v[80:81], v[20:21] op_sel_hi:[1,0,1]
	v_pk_fma_f32 v[38:39], v[20:21], v[80:81], v[38:39] op_sel:[0,1,0] op_sel_hi:[1,1,1]
	s_add_u32 s14, s14, 0x1000
	s_addc_u32 s15, s15, 0
	v_add_f32_dpp v38, v38, v38 row_ror:8 row_mask:0xf bank_mask:0x3 bound_ctrl:1
	v_add_f32_dpp v38, v39, v39 row_ror:8 row_mask:0xf bank_mask:0xc bound_ctrl:1
	ds_read_b64 v[64:65], v3 offset:45312
	ds_read_b128 v[48:51], v2 offset:33024
	v_add_f32_dpp v38, v38, v38 row_half_mirror row_mask:0xf bank_mask:0xf bound_ctrl:1
	ds_read_b128 v[52:55], v2 offset:33280
	ds_read_b128 v[56:59], v2 offset:33536
	v_add_f32_dpp v38, v38, v38 quad_perm:[1,0,3,2] row_mask:0xf bank_mask:0xf bound_ctrl:1
	ds_read_b128 v[60:63], v2 offset:33792
	s_nop 0
	v_add_f32_dpp v38, v38, v38 quad_perm:[2,3,0,1] row_mask:0xf bank_mask:0xf bound_ctrl:1
	v_cvt_pk_bf16_f32 v47, v38, v38
	s_mov_b64 exec, s[2:3]
	global_store_short v28, v47, s[14:15] offset:-4096
	s_mov_b64 exec, -1
	s_waitcnt vmcnt(8)
	v_lshlrev_b32_e32 v108, 16, v84
	v_lshlrev_b32_e32 v109, 16, v85
	v_and_b32_e32 v110, s17, v84
	v_and_b32_e32 v111, s17, v85
	v_lshlrev_b32_e32 v112, 16, v86
	v_lshlrev_b32_e32 v113, 16, v87
	v_and_b32_e32 v114, s17, v86
	v_and_b32_e32 v115, s17, v87
	v_lshlrev_b32_e32 v116, 16, v88
	v_and_b32_e32 v117, s17, v88
	v_rcp_f32_e32 v25, v24
	v_mul_f32_e32 v113, v24, v113
	v_mul_f32_e32 v115, v24, v115
	v_mul_f32_e32 v109, 0x3db504f3, v109
	v_mul_f32_e32 v111, 0x3db504f3, v111
	v_cndmask_b32_e64 v27, 1.0, v25, s[20:21]
	v_mul_f32_e32 v24, v24, v26
	v_mul_f32_e32 v116, v27, v116
	v_mul_f32_e32 v117, v27, v117
	ds_write_b128 v29, v[108:111] offset:49408
	ds_write_b128 v29, v[112:115] offset:57600
	ds_write_b64 v30, v[90:91] offset:49408
	ds_write_b64 v31, v[116:117] offset:49408
	s_add_i32 s16, s16, 8
	s_waitcnt lgkmcnt(0)
	global_load_dword v84, v32, s[10:11]
	global_load_dword v85, v32, s[10:11] offset:-1024
	global_load_dword v86, v33, s[10:11]
	global_load_dword v87, v33, s[10:11] offset:-1024
	global_load_dword v88, v34, s[10:11]
	global_load_dword v90, v35, s[12:13]
	global_load_dword v91, v35, s[12:13] offset:4
	s_add_u32 s10, s10, 0x18000
	s_addc_u32 s11, s11, 0
	s_add_u32 s12, s12, 0x4000
	s_addc_u32 s13, s13, 0
	s_barrier
	s_cmpk_lt_u32 s16, 0x800
	s_cbranch_scc0 .Lret2_done
	s_waitcnt lgkmcnt(3)
	v_pk_fma_f32 v[6:7], v[64:65], v[48:49], v[6:7] op_sel_hi:[1,0,1]
	v_pk_mul_f32 v[38:39], v[6:7], v[48:49] op_sel:[0,1] op_sel_hi:[1,1]
	v_pk_fma_f32 v[8:9], v[64:65], v[50:51], v[8:9] op_sel_hi:[1,0,1]
	v_pk_fma_f32 v[38:39], v[8:9], v[50:51], v[38:39] op_sel:[0,1,0] op_sel_hi:[1,1,1]
	s_waitcnt lgkmcnt(2)
	v_pk_fma_f32 v[10:11], v[64:65], v[52:53], v[10:11] op_sel_hi:[1,0,1]
	v_pk_fma_f32 v[38:39], v[10:11], v[52:53], v[38:39] op_sel:[0,1,0] op_sel_hi:[1,1,1]
	v_pk_fma_f32 v[12:13], v[64:65], v[54:55], v[12:13] op_sel_hi:[1,0,1]
	v_pk_fma_f32 v[38:39], v[12:13], v[54:55], v[38:39] op_sel:[0,1,0] op_sel_hi:[1,1,1]
	s_waitcnt lgkmcnt(1)
	v_pk_fma_f32 v[14:15], v[64:65], v[56:57], v[14:15] op_sel_hi:[1,0,1]
	v_pk_fma_f32 v[38:39], v[14:15], v[56:57], v[38:39] op_sel:[0,1,0] op_sel_hi:[1,1,1]
	v_pk_fma_f32 v[16:17], v[64:65], v[58:59], v[16:17] op_sel_hi:[1,0,1]
	v_pk_fma_f32 v[38:39], v[16:17], v[58:59], v[38:39] op_sel:[0,1,0] op_sel_hi:[1,1,1]
	s_waitcnt lgkmcnt(0)
	v_pk_fma_f32 v[18:19], v[64:65], v[60:61], v[18:19] op_sel_hi:[1,0,1]
	v_pk_fma_f32 v[38:39], v[18:19], v[60:61], v[38:39] op_sel:[0,1,0] op_sel_hi:[1,1,1]
	v_pk_fma_f32 v[20:21], v[64:65], v[62:63], v[20:21] op_sel_hi:[1,0,1]
	v_pk_fma_f32 v[38:39], v[20:21], v[62:63], v[38:39] op_sel:[0,1,0] op_sel_hi:[1,1,1]
	s_add_u32 s14, s14, 0x1000
	s_addc_u32 s15, s15, 0
	v_add_f32_dpp v38, v38, v38 row_ror:8 row_mask:0xf bank_mask:0x3 bound_ctrl:1
	v_add_f32_dpp v38, v39, v39 row_ror:8 row_mask:0xf bank_mask:0xc bound_ctrl:1
	ds_read_b64 v[82:83], v3 offset:45568
	ds_read_b128 v[66:69], v2 offset:34048
	v_add_f32_dpp v38, v38, v38 row_half_mirror row_mask:0xf bank_mask:0xf bound_ctrl:1
	ds_read_b128 v[70:73], v2 offset:34304
	ds_read_b128 v[74:77], v2 offset:34560
	v_add_f32_dpp v38, v38, v38 quad_perm:[1,0,3,2] row_mask:0xf bank_mask:0xf bound_ctrl:1
	ds_read_b128 v[78:81], v2 offset:34816
	s_nop 0
	v_add_f32_dpp v38, v38, v38 quad_perm:[2,3,0,1] row_mask:0xf bank_mask:0xf bound_ctrl:1
	v_cvt_pk_bf16_f32 v47, v38, v38
	s_mov_b64 exec, s[2:3]
	global_store_short v28, v47, s[14:15] offset:-4096
	s_mov_b64 exec, -1
	s_waitcnt lgkmcnt(3)
	v_pk_fma_f32 v[6:7], v[82:83], v[66:67], v[6:7] op_sel_hi:[1,0,1]
	v_pk_mul_f32 v[38:39], v[6:7], v[66:67] op_sel:[0,1] op_sel_hi:[1,1]
	v_pk_fma_f32 v[8:9], v[82:83], v[68:69], v[8:9] op_sel_hi:[1,0,1]
	v_pk_fma_f32 v[38:39], v[8:9], v[68:69], v[38:39] op_sel:[0,1,0] op_sel_hi:[1,1,1]
	s_waitcnt lgkmcnt(2)
	v_pk_fma_f32 v[10:11], v[82:83], v[70:71], v[10:11] op_sel_hi:[1,0,1]
	v_pk_fma_f32 v[38:39], v[10:11], v[70:71], v[38:39] op_sel:[0,1,0] op_sel_hi:[1,1,1]
	v_pk_fma_f32 v[12:13], v[82:83], v[72:73], v[12:13] op_sel_hi:[1,0,1]
	v_pk_fma_f32 v[38:39], v[12:13], v[72:73], v[38:39] op_sel:[0,1,0] op_sel_hi:[1,1,1]
	s_waitcnt lgkmcnt(1)
	v_pk_fma_f32 v[14:15], v[82:83], v[74:75], v[14:15] op_sel_hi:[1,0,1]
	v_pk_fma_f32 v[38:39], v[14:15], v[74:75], v[38:39] op_sel:[0,1,0] op_sel_hi:[1,1,1]
	v_pk_fma_f32 v[16:17], v[82:83], v[76:77], v[16:17] op_sel_hi:[1,0,1]
	v_pk_fma_f32 v[38:39], v[16:17], v[76:77], v[38:39] op_sel:[0,1,0] op_sel_hi:[1,1,1]
	s_waitcnt lgkmcnt(0)
	v_pk_fma_f32 v[18:19], v[82:83], v[78:79], v[18:19] op_sel_hi:[1,0,1]
	v_pk_fma_f32 v[38:39], v[18:19], v[78:79], v[38:39] op_sel:[0,1,0] op_sel_hi:[1,1,1]
	v_pk_fma_f32 v[20:21], v[82:83], v[80:81], v[20:21] op_sel_hi:[1,0,1]
	v_pk_fma_f32 v[38:39], v[20:21], v[80:81], v[38:39] op_sel:[0,1,0] op_sel_hi:[1,1,1]
	s_add_u32 s14, s14, 0x1000
	s_addc_u32 s15, s15, 0
	v_add_f32_dpp v38, v38, v38 row_ror:8 row_mask:0xf bank_mask:0x3 bound_ctrl:1
	v_add_f32_dpp v38, v39, v39 row_ror:8 row_mask:0xf bank_mask:0xc bound_ctrl:1
	ds_read_b64 v[64:65], v3 offset:45824
	ds_read_b128 v[48:51], v2 offset:35072
	v_add_f32_dpp v38, v38, v38 row_half_mirror row_mask:0xf bank_mask:0xf bound_ctrl:1
	ds_read_b128 v[52:55], v2 offset:35328
	ds_read_b128 v[56:59], v2 offset:35584
	v_add_f32_dpp v38, v38, v38 quad_perm:[1,0,3,2] row_mask:0xf bank_mask:0xf bound_ctrl:1
	ds_read_b128 v[60:63], v2 offset:35840
	s_nop 0
	v_add_f32_dpp v38, v38, v38 quad_perm:[2,3,0,1] row_mask:0xf bank_mask:0xf bound_ctrl:1
	v_cvt_pk_bf16_f32 v47, v38, v38
	s_mov_b64 exec, s[2:3]
	global_store_short v28, v47, s[14:15] offset:-4096
	s_mov_b64 exec, -1
	s_waitcnt lgkmcnt(3)
	v_pk_fma_f32 v[6:7], v[64:65], v[48:49], v[6:7] op_sel_hi:[1,0,1]
	v_pk_mul_f32 v[38:39], v[6:7], v[48:49] op_sel:[0,1] op_sel_hi:[1,1]
	v_pk_fma_f32 v[8:9], v[64:65], v[50:51], v[8:9] op_sel_hi:[1,0,1]
	v_pk_fma_f32 v[38:39], v[8:9], v[50:51], v[38:39] op_sel:[0,1,0] op_sel_hi:[1,1,1]
	s_waitcnt lgkmcnt(2)
	v_pk_fma_f32 v[10:11], v[64:65], v[52:53], v[10:11] op_sel_hi:[1,0,1]
	v_pk_fma_f32 v[38:39], v[10:11], v[52:53], v[38:39] op_sel:[0,1,0] op_sel_hi:[1,1,1]
	v_pk_fma_f32 v[12:13], v[64:65], v[54:55], v[12:13] op_sel_hi:[1,0,1]
	v_pk_fma_f32 v[38:39], v[12:13], v[54:55], v[38:39] op_sel:[0,1,0] op_sel_hi:[1,1,1]
	s_waitcnt lgkmcnt(1)
	v_pk_fma_f32 v[14:15], v[64:65], v[56:57], v[14:15] op_sel_hi:[1,0,1]
	v_pk_fma_f32 v[38:39], v[14:15], v[56:57], v[38:39] op_sel:[0,1,0] op_sel_hi:[1,1,1]
	v_pk_fma_f32 v[16:17], v[64:65], v[58:59], v[16:17] op_sel_hi:[1,0,1]
	v_pk_fma_f32 v[38:39], v[16:17], v[58:59], v[38:39] op_sel:[0,1,0] op_sel_hi:[1,1,1]
	s_waitcnt lgkmcnt(0)
	v_pk_fma_f32 v[18:19], v[64:65], v[60:61], v[18:19] op_sel_hi:[1,0,1]
	v_pk_fma_f32 v[38:39], v[18:19], v[60:61], v[38:39] op_sel:[0,1,0] op_sel_hi:[1,1,1]
	v_pk_fma_f32 v[20:21], v[64:65], v[62:63], v[20:21] op_sel_hi:[1,0,1]
	v_pk_fma_f32 v[38:39], v[20:21], v[62:63], v[38:39] op_sel:[0,1,0] op_sel_hi:[1,1,1]
	s_add_u32 s14, s14, 0x1000
	s_addc_u32 s15, s15, 0
	v_add_f32_dpp v38, v38, v38 row_ror:8 row_mask:0xf bank_mask:0x3 bound_ctrl:1
	v_add_f32_dpp v38, v39, v39 row_ror:8 row_mask:0xf bank_mask:0xc bound_ctrl:1
	ds_read_b64 v[82:83], v3 offset:46080
	ds_read_b128 v[66:69], v2 offset:36096
	v_add_f32_dpp v38, v38, v38 row_half_mirror row_mask:0xf bank_mask:0xf bound_ctrl:1
	ds_read_b128 v[70:73], v2 offset:36352
	ds_read_b128 v[74:77], v2 offset:36608
	v_add_f32_dpp v38, v38, v38 quad_perm:[1,0,3,2] row_mask:0xf bank_mask:0xf bound_ctrl:1
	ds_read_b128 v[78:81], v2 offset:36864
	s_nop 0
	v_add_f32_dpp v38, v38, v38 quad_perm:[2,3,0,1] row_mask:0xf bank_mask:0xf bound_ctrl:1
	v_cvt_pk_bf16_f32 v47, v38, v38
	s_mov_b64 exec, s[2:3]
	global_store_short v28, v47, s[14:15] offset:-4096
	s_mov_b64 exec, -1
	s_waitcnt lgkmcnt(3)
	v_pk_fma_f32 v[6:7], v[82:83], v[66:67], v[6:7] op_sel_hi:[1,0,1]
	v_pk_mul_f32 v[38:39], v[6:7], v[66:67] op_sel:[0,1] op_sel_hi:[1,1]
	v_pk_fma_f32 v[8:9], v[82:83], v[68:69], v[8:9] op_sel_hi:[1,0,1]
	v_pk_fma_f32 v[38:39], v[8:9], v[68:69], v[38:39] op_sel:[0,1,0] op_sel_hi:[1,1,1]
	s_waitcnt lgkmcnt(2)
	v_pk_fma_f32 v[10:11], v[82:83], v[70:71], v[10:11] op_sel_hi:[1,0,1]
	v_pk_fma_f32 v[38:39], v[10:11], v[70:71], v[38:39] op_sel:[0,1,0] op_sel_hi:[1,1,1]
	v_pk_fma_f32 v[12:13], v[82:83], v[72:73], v[12:13] op_sel_hi:[1,0,1]
	v_pk_fma_f32 v[38:39], v[12:13], v[72:73], v[38:39] op_sel:[0,1,0] op_sel_hi:[1,1,1]
	s_waitcnt lgkmcnt(1)
	v_pk_fma_f32 v[14:15], v[82:83], v[74:75], v[14:15] op_sel_hi:[1,0,1]
	v_pk_fma_f32 v[38:39], v[14:15], v[74:75], v[38:39] op_sel:[0,1,0] op_sel_hi:[1,1,1]
	v_pk_fma_f32 v[16:17], v[82:83], v[76:77], v[16:17] op_sel_hi:[1,0,1]
	v_pk_fma_f32 v[38:39], v[16:17], v[76:77], v[38:39] op_sel:[0,1,0] op_sel_hi:[1,1,1]
	s_waitcnt lgkmcnt(0)
	v_pk_fma_f32 v[18:19], v[82:83], v[78:79], v[18:19] op_sel_hi:[1,0,1]
	v_pk_fma_f32 v[38:39], v[18:19], v[78:79], v[38:39] op_sel:[0,1,0] op_sel_hi:[1,1,1]
	v_pk_fma_f32 v[20:21], v[82:83], v[80:81], v[20:21] op_sel_hi:[1,0,1]
	v_pk_fma_f32 v[38:39], v[20:21], v[80:81], v[38:39] op_sel:[0,1,0] op_sel_hi:[1,1,1]
	s_add_u32 s14, s14, 0x1000
	s_addc_u32 s15, s15, 0
	v_add_f32_dpp v38, v38, v38 row_ror:8 row_mask:0xf bank_mask:0x3 bound_ctrl:1
	v_add_f32_dpp v38, v39, v39 row_ror:8 row_mask:0xf bank_mask:0xc bound_ctrl:1
	ds_read_b64 v[64:65], v3 offset:46336
	ds_read_b128 v[48:51], v2 offset:37120
	v_add_f32_dpp v38, v38, v38 row_half_mirror row_mask:0xf bank_mask:0xf bound_ctrl:1
	ds_read_b128 v[52:55], v2 offset:37376
	ds_read_b128 v[56:59], v2 offset:37632
	v_add_f32_dpp v38, v38, v38 quad_perm:[1,0,3,2] row_mask:0xf bank_mask:0xf bound_ctrl:1
	ds_read_b128 v[60:63], v2 offset:37888
	s_nop 0
	v_add_f32_dpp v38, v38, v38 quad_perm:[2,3,0,1] row_mask:0xf bank_mask:0xf bound_ctrl:1
	v_cvt_pk_bf16_f32 v47, v38, v38
	s_mov_b64 exec, s[2:3]
	global_store_short v28, v47, s[14:15] offset:-4096
	s_mov_b64 exec, -1
	s_waitcnt lgkmcnt(3)
	v_pk_fma_f32 v[6:7], v[64:65], v[48:49], v[6:7] op_sel_hi:[1,0,1]
	v_pk_mul_f32 v[38:39], v[6:7], v[48:49] op_sel:[0,1] op_sel_hi:[1,1]
	v_pk_fma_f32 v[8:9], v[64:65], v[50:51], v[8:9] op_sel_hi:[1,0,1]
	v_pk_fma_f32 v[38:39], v[8:9], v[50:51], v[38:39] op_sel:[0,1,0] op_sel_hi:[1,1,1]
	s_waitcnt lgkmcnt(2)
	v_pk_fma_f32 v[10:11], v[64:65], v[52:53], v[10:11] op_sel_hi:[1,0,1]
	v_pk_fma_f32 v[38:39], v[10:11], v[52:53], v[38:39] op_sel:[0,1,0] op_sel_hi:[1,1,1]
	v_pk_fma_f32 v[12:13], v[64:65], v[54:55], v[12:13] op_sel_hi:[1,0,1]
	v_pk_fma_f32 v[38:39], v[12:13], v[54:55], v[38:39] op_sel:[0,1,0] op_sel_hi:[1,1,1]
	s_waitcnt lgkmcnt(1)
	v_pk_fma_f32 v[14:15], v[64:65], v[56:57], v[14:15] op_sel_hi:[1,0,1]
	v_pk_fma_f32 v[38:39], v[14:15], v[56:57], v[38:39] op_sel:[0,1,0] op_sel_hi:[1,1,1]
	v_pk_fma_f32 v[16:17], v[64:65], v[58:59], v[16:17] op_sel_hi:[1,0,1]
	v_pk_fma_f32 v[38:39], v[16:17], v[58:59], v[38:39] op_sel:[0,1,0] op_sel_hi:[1,1,1]
	s_waitcnt lgkmcnt(0)
	v_pk_fma_f32 v[18:19], v[64:65], v[60:61], v[18:19] op_sel_hi:[1,0,1]
	v_pk_fma_f32 v[38:39], v[18:19], v[60:61], v[38:39] op_sel:[0,1,0] op_sel_hi:[1,1,1]
	v_pk_fma_f32 v[20:21], v[64:65], v[62:63], v[20:21] op_sel_hi:[1,0,1]
	v_pk_fma_f32 v[38:39], v[20:21], v[62:63], v[38:39] op_sel:[0,1,0] op_sel_hi:[1,1,1]
	s_add_u32 s14, s14, 0x1000
	s_addc_u32 s15, s15, 0
	v_add_f32_dpp v38, v38, v38 row_ror:8 row_mask:0xf bank_mask:0x3 bound_ctrl:1
	v_add_f32_dpp v38, v39, v39 row_ror:8 row_mask:0xf bank_mask:0xc bound_ctrl:1
	ds_read_b64 v[82:83], v3 offset:46592
	ds_read_b128 v[66:69], v2 offset:38144
	v_add_f32_dpp v38, v38, v38 row_half_mirror row_mask:0xf bank_mask:0xf bound_ctrl:1
	ds_read_b128 v[70:73], v2 offset:38400
	ds_read_b128 v[74:77], v2 offset:38656
	v_add_f32_dpp v38, v38, v38 quad_perm:[1,0,3,2] row_mask:0xf bank_mask:0xf bound_ctrl:1
	ds_read_b128 v[78:81], v2 offset:38912
	s_nop 0
	v_add_f32_dpp v38, v38, v38 quad_perm:[2,3,0,1] row_mask:0xf bank_mask:0xf bound_ctrl:1
	v_cvt_pk_bf16_f32 v47, v38, v38
	s_mov_b64 exec, s[2:3]
	global_store_short v28, v47, s[14:15] offset:-4096
	s_mov_b64 exec, -1
	s_waitcnt lgkmcnt(3)
	v_pk_fma_f32 v[6:7], v[82:83], v[66:67], v[6:7] op_sel_hi:[1,0,1]
	v_pk_mul_f32 v[38:39], v[6:7], v[66:67] op_sel:[0,1] op_sel_hi:[1,1]
	v_pk_fma_f32 v[8:9], v[82:83], v[68:69], v[8:9] op_sel_hi:[1,0,1]
	v_pk_fma_f32 v[38:39], v[8:9], v[68:69], v[38:39] op_sel:[0,1,0] op_sel_hi:[1,1,1]
	s_waitcnt lgkmcnt(2)
	v_pk_fma_f32 v[10:11], v[82:83], v[70:71], v[10:11] op_sel_hi:[1,0,1]
	v_pk_fma_f32 v[38:39], v[10:11], v[70:71], v[38:39] op_sel:[0,1,0] op_sel_hi:[1,1,1]
	v_pk_fma_f32 v[12:13], v[82:83], v[72:73], v[12:13] op_sel_hi:[1,0,1]
	v_pk_fma_f32 v[38:39], v[12:13], v[72:73], v[38:39] op_sel:[0,1,0] op_sel_hi:[1,1,1]
	s_waitcnt lgkmcnt(1)
	v_pk_fma_f32 v[14:15], v[82:83], v[74:75], v[14:15] op_sel_hi:[1,0,1]
	v_pk_fma_f32 v[38:39], v[14:15], v[74:75], v[38:39] op_sel:[0,1,0] op_sel_hi:[1,1,1]
	v_pk_fma_f32 v[16:17], v[82:83], v[76:77], v[16:17] op_sel_hi:[1,0,1]
	v_pk_fma_f32 v[38:39], v[16:17], v[76:77], v[38:39] op_sel:[0,1,0] op_sel_hi:[1,1,1]
	s_waitcnt lgkmcnt(0)
	v_pk_fma_f32 v[18:19], v[82:83], v[78:79], v[18:19] op_sel_hi:[1,0,1]
	v_pk_fma_f32 v[38:39], v[18:19], v[78:79], v[38:39] op_sel:[0,1,0] op_sel_hi:[1,1,1]
	v_pk_fma_f32 v[20:21], v[82:83], v[80:81], v[20:21] op_sel_hi:[1,0,1]
	v_pk_fma_f32 v[38:39], v[20:21], v[80:81], v[38:39] op_sel:[0,1,0] op_sel_hi:[1,1,1]
	s_add_u32 s14, s14, 0x1000
	s_addc_u32 s15, s15, 0
	v_add_f32_dpp v38, v38, v38 row_ror:8 row_mask:0xf bank_mask:0x3 bound_ctrl:1
	v_add_f32_dpp v38, v39, v39 row_ror:8 row_mask:0xf bank_mask:0xc bound_ctrl:1
	ds_read_b64 v[64:65], v3 offset:46848
	ds_read_b128 v[48:51], v2 offset:39168
	v_add_f32_dpp v38, v38, v38 row_half_mirror row_mask:0xf bank_mask:0xf bound_ctrl:1
	ds_read_b128 v[52:55], v2 offset:39424
	ds_read_b128 v[56:59], v2 offset:39680
	v_add_f32_dpp v38, v38, v38 quad_perm:[1,0,3,2] row_mask:0xf bank_mask:0xf bound_ctrl:1
	ds_read_b128 v[60:63], v2 offset:39936
	s_nop 0
	v_add_f32_dpp v38, v38, v38 quad_perm:[2,3,0,1] row_mask:0xf bank_mask:0xf bound_ctrl:1
	v_cvt_pk_bf16_f32 v47, v38, v38
	s_mov_b64 exec, s[2:3]
	global_store_short v28, v47, s[14:15] offset:-4096
	s_mov_b64 exec, -1
	s_waitcnt lgkmcnt(3)
	v_pk_fma_f32 v[6:7], v[64:65], v[48:49], v[6:7] op_sel_hi:[1,0,1]
	v_pk_mul_f32 v[38:39], v[6:7], v[48:49] op_sel:[0,1] op_sel_hi:[1,1]
	v_pk_fma_f32 v[8:9], v[64:65], v[50:51], v[8:9] op_sel_hi:[1,0,1]
	v_pk_fma_f32 v[38:39], v[8:9], v[50:51], v[38:39] op_sel:[0,1,0] op_sel_hi:[1,1,1]
	s_waitcnt lgkmcnt(2)
	v_pk_fma_f32 v[10:11], v[64:65], v[52:53], v[10:11] op_sel_hi:[1,0,1]
	v_pk_fma_f32 v[38:39], v[10:11], v[52:53], v[38:39] op_sel:[0,1,0] op_sel_hi:[1,1,1]
	v_pk_fma_f32 v[12:13], v[64:65], v[54:55], v[12:13] op_sel_hi:[1,0,1]
	v_pk_fma_f32 v[38:39], v[12:13], v[54:55], v[38:39] op_sel:[0,1,0] op_sel_hi:[1,1,1]
	s_waitcnt lgkmcnt(1)
	v_pk_fma_f32 v[14:15], v[64:65], v[56:57], v[14:15] op_sel_hi:[1,0,1]
	v_pk_fma_f32 v[38:39], v[14:15], v[56:57], v[38:39] op_sel:[0,1,0] op_sel_hi:[1,1,1]
	v_pk_fma_f32 v[16:17], v[64:65], v[58:59], v[16:17] op_sel_hi:[1,0,1]
	v_pk_fma_f32 v[38:39], v[16:17], v[58:59], v[38:39] op_sel:[0,1,0] op_sel_hi:[1,1,1]
	s_waitcnt lgkmcnt(0)
	v_pk_fma_f32 v[18:19], v[64:65], v[60:61], v[18:19] op_sel_hi:[1,0,1]
	v_pk_fma_f32 v[38:39], v[18:19], v[60:61], v[38:39] op_sel:[0,1,0] op_sel_hi:[1,1,1]
	v_pk_fma_f32 v[20:21], v[64:65], v[62:63], v[20:21] op_sel_hi:[1,0,1]
	v_pk_fma_f32 v[38:39], v[20:21], v[62:63], v[38:39] op_sel:[0,1,0] op_sel_hi:[1,1,1]
	s_add_u32 s14, s14, 0x1000
	s_addc_u32 s15, s15, 0
	v_add_f32_dpp v38, v38, v38 row_ror:8 row_mask:0xf bank_mask:0x3 bound_ctrl:1
	v_add_f32_dpp v38, v39, v39 row_ror:8 row_mask:0xf bank_mask:0xc bound_ctrl:1
	ds_read_b64 v[82:83], v3 offset:47104
	ds_read_b128 v[66:69], v2 offset:40192
	v_add_f32_dpp v38, v38, v38 row_half_mirror row_mask:0xf bank_mask:0xf bound_ctrl:1
	ds_read_b128 v[70:73], v2 offset:40448
	ds_read_b128 v[74:77], v2 offset:40704
	v_add_f32_dpp v38, v38, v38 quad_perm:[1,0,3,2] row_mask:0xf bank_mask:0xf bound_ctrl:1
	ds_read_b128 v[78:81], v2 offset:40960
	s_nop 0
	v_add_f32_dpp v38, v38, v38 quad_perm:[2,3,0,1] row_mask:0xf bank_mask:0xf bound_ctrl:1
	v_cvt_pk_bf16_f32 v47, v38, v38
	s_mov_b64 exec, s[2:3]
	global_store_short v28, v47, s[14:15] offset:-4096
	s_mov_b64 exec, -1
	s_waitcnt lgkmcnt(3)
	v_pk_fma_f32 v[6:7], v[82:83], v[66:67], v[6:7] op_sel_hi:[1,0,1]
	v_pk_mul_f32 v[38:39], v[6:7], v[66:67] op_sel:[0,1] op_sel_hi:[1,1]
	v_pk_fma_f32 v[8:9], v[82:83], v[68:69], v[8:9] op_sel_hi:[1,0,1]
	v_pk_fma_f32 v[38:39], v[8:9], v[68:69], v[38:39] op_sel:[0,1,0] op_sel_hi:[1,1,1]
	s_waitcnt lgkmcnt(2)
	v_pk_fma_f32 v[10:11], v[82:83], v[70:71], v[10:11] op_sel_hi:[1,0,1]
	v_pk_fma_f32 v[38:39], v[10:11], v[70:71], v[38:39] op_sel:[0,1,0] op_sel_hi:[1,1,1]
	v_pk_fma_f32 v[12:13], v[82:83], v[72:73], v[12:13] op_sel_hi:[1,0,1]
	v_pk_fma_f32 v[38:39], v[12:13], v[72:73], v[38:39] op_sel:[0,1,0] op_sel_hi:[1,1,1]
	s_waitcnt lgkmcnt(1)
	v_pk_fma_f32 v[14:15], v[82:83], v[74:75], v[14:15] op_sel_hi:[1,0,1]
	v_pk_fma_f32 v[38:39], v[14:15], v[74:75], v[38:39] op_sel:[0,1,0] op_sel_hi:[1,1,1]
	v_pk_fma_f32 v[16:17], v[82:83], v[76:77], v[16:17] op_sel_hi:[1,0,1]
	v_pk_fma_f32 v[38:39], v[16:17], v[76:77], v[38:39] op_sel:[0,1,0] op_sel_hi:[1,1,1]
	s_waitcnt lgkmcnt(0)
	v_pk_fma_f32 v[18:19], v[82:83], v[78:79], v[18:19] op_sel_hi:[1,0,1]
	v_pk_fma_f32 v[38:39], v[18:19], v[78:79], v[38:39] op_sel:[0,1,0] op_sel_hi:[1,1,1]
	v_pk_fma_f32 v[20:21], v[82:83], v[80:81], v[20:21] op_sel_hi:[1,0,1]
	v_pk_fma_f32 v[38:39], v[20:21], v[80:81], v[38:39] op_sel:[0,1,0] op_sel_hi:[1,1,1]
	s_add_u32 s14, s14, 0x1000
	s_addc_u32 s15, s15, 0
	v_add_f32_dpp v38, v38, v38 row_ror:8 row_mask:0xf bank_mask:0x3 bound_ctrl:1
	v_add_f32_dpp v38, v39, v39 row_ror:8 row_mask:0xf bank_mask:0xc bound_ctrl:1
	ds_read_b64 v[64:65], v23 offset:37120
	ds_read_b128 v[48:51], v2 offset:57600
	v_add_f32_dpp v38, v38, v38 row_half_mirror row_mask:0xf bank_mask:0xf bound_ctrl:1
	ds_read_b128 v[52:55], v2 offset:57856
	ds_read_b128 v[56:59], v2 offset:58112
	v_add_f32_dpp v38, v38, v38 quad_perm:[1,0,3,2] row_mask:0xf bank_mask:0xf bound_ctrl:1
	ds_read_b128 v[60:63], v2 offset:58368
	s_nop 0
	v_add_f32_dpp v38, v38, v38 quad_perm:[2,3,0,1] row_mask:0xf bank_mask:0xf bound_ctrl:1
	v_cvt_pk_bf16_f32 v47, v38, v38
	s_mov_b64 exec, s[2:3]
	global_store_short v28, v47, s[14:15] offset:-4096
	s_mov_b64 exec, -1
	s_waitcnt vmcnt(8)
	v_lshlrev_b32_e32 v108, 16, v84
	v_lshlrev_b32_e32 v109, 16, v85
	v_and_b32_e32 v110, s17, v84
	v_and_b32_e32 v111, s17, v85
	v_lshlrev_b32_e32 v112, 16, v86
	v_lshlrev_b32_e32 v113, 16, v87
	v_and_b32_e32 v114, s17, v86
	v_and_b32_e32 v115, s17, v87
	v_lshlrev_b32_e32 v116, 16, v88
	v_and_b32_e32 v117, s17, v88
	v_rcp_f32_e32 v25, v24
	v_mul_f32_e32 v113, v24, v113
	v_mul_f32_e32 v115, v24, v115
	v_mul_f32_e32 v109, 0x3db504f3, v109
	v_mul_f32_e32 v111, 0x3db504f3, v111
	v_cndmask_b32_e64 v27, 1.0, v25, s[20:21]
	v_mul_f32_e32 v24, v24, v26
	v_mul_f32_e32 v116, v27, v116
	v_mul_f32_e32 v117, v27, v117
	ds_write_b128 v29, v[108:111] offset:256
	ds_write_b128 v29, v[112:115] offset:8448
	ds_write_b64 v30, v[90:91] offset:256
	ds_write_b64 v31, v[116:117] offset:256
	s_add_i32 s16, s16, 8
	s_waitcnt lgkmcnt(0)
	global_load_dword v84, v32, s[10:11]
	global_load_dword v85, v32, s[10:11] offset:-1024
	global_load_dword v86, v33, s[10:11]
	global_load_dword v87, v33, s[10:11] offset:-1024
	global_load_dword v88, v34, s[10:11]
	global_load_dword v90, v35, s[12:13]
	global_load_dword v91, v35, s[12:13] offset:4
	s_add_u32 s10, s10, 0x18000
	s_addc_u32 s11, s11, 0
	s_add_u32 s12, s12, 0x4000
	s_addc_u32 s13, s13, 0
	s_barrier
	s_cmpk_lt_u32 s16, 0x800
	s_cbranch_scc0 .Lret2_done
	s_waitcnt lgkmcnt(3)
	v_pk_fma_f32 v[6:7], v[64:65], v[48:49], v[6:7] op_sel_hi:[1,0,1]
	v_pk_mul_f32 v[38:39], v[6:7], v[48:49] op_sel:[0,1] op_sel_hi:[1,1]
	v_pk_fma_f32 v[8:9], v[64:65], v[50:51], v[8:9] op_sel_hi:[1,0,1]
	v_pk_fma_f32 v[38:39], v[8:9], v[50:51], v[38:39] op_sel:[0,1,0] op_sel_hi:[1,1,1]
	s_waitcnt lgkmcnt(2)
	v_pk_fma_f32 v[10:11], v[64:65], v[52:53], v[10:11] op_sel_hi:[1,0,1]
	v_pk_fma_f32 v[38:39], v[10:11], v[52:53], v[38:39] op_sel:[0,1,0] op_sel_hi:[1,1,1]
	v_pk_fma_f32 v[12:13], v[64:65], v[54:55], v[12:13] op_sel_hi:[1,0,1]
	v_pk_fma_f32 v[38:39], v[12:13], v[54:55], v[38:39] op_sel:[0,1,0] op_sel_hi:[1,1,1]
	s_waitcnt lgkmcnt(1)
	v_pk_fma_f32 v[14:15], v[64:65], v[56:57], v[14:15] op_sel_hi:[1,0,1]
	v_pk_fma_f32 v[38:39], v[14:15], v[56:57], v[38:39] op_sel:[0,1,0] op_sel_hi:[1,1,1]
	v_pk_fma_f32 v[16:17], v[64:65], v[58:59], v[16:17] op_sel_hi:[1,0,1]
	v_pk_fma_f32 v[38:39], v[16:17], v[58:59], v[38:39] op_sel:[0,1,0] op_sel_hi:[1,1,1]
	s_waitcnt lgkmcnt(0)
	v_pk_fma_f32 v[18:19], v[64:65], v[60:61], v[18:19] op_sel_hi:[1,0,1]
	v_pk_fma_f32 v[38:39], v[18:19], v[60:61], v[38:39] op_sel:[0,1,0] op_sel_hi:[1,1,1]
	v_pk_fma_f32 v[20:21], v[64:65], v[62:63], v[20:21] op_sel_hi:[1,0,1]
	v_pk_fma_f32 v[38:39], v[20:21], v[62:63], v[38:39] op_sel:[0,1,0] op_sel_hi:[1,1,1]
	s_add_u32 s14, s14, 0x1000
	s_addc_u32 s15, s15, 0
	v_add_f32_dpp v38, v38, v38 row_ror:8 row_mask:0xf bank_mask:0x3 bound_ctrl:1
	v_add_f32_dpp v38, v39, v39 row_ror:8 row_mask:0xf bank_mask:0xc bound_ctrl:1
	ds_read_b64 v[82:83], v23 offset:37376
	ds_read_b128 v[66:69], v2 offset:58624
	v_add_f32_dpp v38, v38, v38 row_half_mirror row_mask:0xf bank_mask:0xf bound_ctrl:1
	ds_read_b128 v[70:73], v2 offset:58880
	ds_read_b128 v[74:77], v2 offset:59136
	v_add_f32_dpp v38, v38, v38 quad_perm:[1,0,3,2] row_mask:0xf bank_mask:0xf bound_ctrl:1
	ds_read_b128 v[78:81], v2 offset:59392
	s_nop 0
	v_add_f32_dpp v38, v38, v38 quad_perm:[2,3,0,1] row_mask:0xf bank_mask:0xf bound_ctrl:1
	v_cvt_pk_bf16_f32 v47, v38, v38
	s_mov_b64 exec, s[2:3]
	global_store_short v28, v47, s[14:15] offset:-4096
	s_mov_b64 exec, -1
	s_waitcnt lgkmcnt(3)
	v_pk_fma_f32 v[6:7], v[82:83], v[66:67], v[6:7] op_sel_hi:[1,0,1]
	v_pk_mul_f32 v[38:39], v[6:7], v[66:67] op_sel:[0,1] op_sel_hi:[1,1]
	v_pk_fma_f32 v[8:9], v[82:83], v[68:69], v[8:9] op_sel_hi:[1,0,1]
	v_pk_fma_f32 v[38:39], v[8:9], v[68:69], v[38:39] op_sel:[0,1,0] op_sel_hi:[1,1,1]
	s_waitcnt lgkmcnt(2)
	v_pk_fma_f32 v[10:11], v[82:83], v[70:71], v[10:11] op_sel_hi:[1,0,1]
	v_pk_fma_f32 v[38:39], v[10:11], v[70:71], v[38:39] op_sel:[0,1,0] op_sel_hi:[1,1,1]
	v_pk_fma_f32 v[12:13], v[82:83], v[72:73], v[12:13] op_sel_hi:[1,0,1]
	v_pk_fma_f32 v[38:39], v[12:13], v[72:73], v[38:39] op_sel:[0,1,0] op_sel_hi:[1,1,1]
	s_waitcnt lgkmcnt(1)
	v_pk_fma_f32 v[14:15], v[82:83], v[74:75], v[14:15] op_sel_hi:[1,0,1]
	v_pk_fma_f32 v[38:39], v[14:15], v[74:75], v[38:39] op_sel:[0,1,0] op_sel_hi:[1,1,1]
	v_pk_fma_f32 v[16:17], v[82:83], v[76:77], v[16:17] op_sel_hi:[1,0,1]
	v_pk_fma_f32 v[38:39], v[16:17], v[76:77], v[38:39] op_sel:[0,1,0] op_sel_hi:[1,1,1]
	s_waitcnt lgkmcnt(0)
	v_pk_fma_f32 v[18:19], v[82:83], v[78:79], v[18:19] op_sel_hi:[1,0,1]
	v_pk_fma_f32 v[38:39], v[18:19], v[78:79], v[38:39] op_sel:[0,1,0] op_sel_hi:[1,1,1]
	v_pk_fma_f32 v[20:21], v[82:83], v[80:81], v[20:21] op_sel_hi:[1,0,1]
	v_pk_fma_f32 v[38:39], v[20:21], v[80:81], v[38:39] op_sel:[0,1,0] op_sel_hi:[1,1,1]
	s_add_u32 s14, s14, 0x1000
	s_addc_u32 s15, s15, 0
	v_add_f32_dpp v38, v38, v38 row_ror:8 row_mask:0xf bank_mask:0x3 bound_ctrl:1
	v_add_f32_dpp v38, v39, v39 row_ror:8 row_mask:0xf bank_mask:0xc bound_ctrl:1
	ds_read_b64 v[64:65], v23 offset:37632
	ds_read_b128 v[48:51], v2 offset:59648
	v_add_f32_dpp v38, v38, v38 row_half_mirror row_mask:0xf bank_mask:0xf bound_ctrl:1
	ds_read_b128 v[52:55], v2 offset:59904
	ds_read_b128 v[56:59], v2 offset:60160
	v_add_f32_dpp v38, v38, v38 quad_perm:[1,0,3,2] row_mask:0xf bank_mask:0xf bound_ctrl:1
	ds_read_b128 v[60:63], v2 offset:60416
	s_nop 0
	v_add_f32_dpp v38, v38, v38 quad_perm:[2,3,0,1] row_mask:0xf bank_mask:0xf bound_ctrl:1
	v_cvt_pk_bf16_f32 v47, v38, v38
	s_mov_b64 exec, s[2:3]
	global_store_short v28, v47, s[14:15] offset:-4096
	s_mov_b64 exec, -1
	s_waitcnt lgkmcnt(3)
	v_pk_fma_f32 v[6:7], v[64:65], v[48:49], v[6:7] op_sel_hi:[1,0,1]
	v_pk_mul_f32 v[38:39], v[6:7], v[48:49] op_sel:[0,1] op_sel_hi:[1,1]
	v_pk_fma_f32 v[8:9], v[64:65], v[50:51], v[8:9] op_sel_hi:[1,0,1]
	v_pk_fma_f32 v[38:39], v[8:9], v[50:51], v[38:39] op_sel:[0,1,0] op_sel_hi:[1,1,1]
	s_waitcnt lgkmcnt(2)
	v_pk_fma_f32 v[10:11], v[64:65], v[52:53], v[10:11] op_sel_hi:[1,0,1]
	v_pk_fma_f32 v[38:39], v[10:11], v[52:53], v[38:39] op_sel:[0,1,0] op_sel_hi:[1,1,1]
	v_pk_fma_f32 v[12:13], v[64:65], v[54:55], v[12:13] op_sel_hi:[1,0,1]
	v_pk_fma_f32 v[38:39], v[12:13], v[54:55], v[38:39] op_sel:[0,1,0] op_sel_hi:[1,1,1]
	s_waitcnt lgkmcnt(1)
	v_pk_fma_f32 v[14:15], v[64:65], v[56:57], v[14:15] op_sel_hi:[1,0,1]
	v_pk_fma_f32 v[38:39], v[14:15], v[56:57], v[38:39] op_sel:[0,1,0] op_sel_hi:[1,1,1]
	v_pk_fma_f32 v[16:17], v[64:65], v[58:59], v[16:17] op_sel_hi:[1,0,1]
	v_pk_fma_f32 v[38:39], v[16:17], v[58:59], v[38:39] op_sel:[0,1,0] op_sel_hi:[1,1,1]
	s_waitcnt lgkmcnt(0)
	v_pk_fma_f32 v[18:19], v[64:65], v[60:61], v[18:19] op_sel_hi:[1,0,1]
	v_pk_fma_f32 v[38:39], v[18:19], v[60:61], v[38:39] op_sel:[0,1,0] op_sel_hi:[1,1,1]
	v_pk_fma_f32 v[20:21], v[64:65], v[62:63], v[20:21] op_sel_hi:[1,0,1]
	v_pk_fma_f32 v[38:39], v[20:21], v[62:63], v[38:39] op_sel:[0,1,0] op_sel_hi:[1,1,1]
	s_add_u32 s14, s14, 0x1000
	s_addc_u32 s15, s15, 0
	v_add_f32_dpp v38, v38, v38 row_ror:8 row_mask:0xf bank_mask:0x3 bound_ctrl:1
	v_add_f32_dpp v38, v39, v39 row_ror:8 row_mask:0xf bank_mask:0xc bound_ctrl:1
	ds_read_b64 v[82:83], v23 offset:37888
	ds_read_b128 v[66:69], v2 offset:60672
	v_add_f32_dpp v38, v38, v38 row_half_mirror row_mask:0xf bank_mask:0xf bound_ctrl:1
	ds_read_b128 v[70:73], v2 offset:60928
	ds_read_b128 v[74:77], v2 offset:61184
	v_add_f32_dpp v38, v38, v38 quad_perm:[1,0,3,2] row_mask:0xf bank_mask:0xf bound_ctrl:1
	ds_read_b128 v[78:81], v2 offset:61440
	s_nop 0
	v_add_f32_dpp v38, v38, v38 quad_perm:[2,3,0,1] row_mask:0xf bank_mask:0xf bound_ctrl:1
	v_cvt_pk_bf16_f32 v47, v38, v38
	s_mov_b64 exec, s[2:3]
	global_store_short v28, v47, s[14:15] offset:-4096
	s_mov_b64 exec, -1
	s_waitcnt lgkmcnt(3)
	v_pk_fma_f32 v[6:7], v[82:83], v[66:67], v[6:7] op_sel_hi:[1,0,1]
	v_pk_mul_f32 v[38:39], v[6:7], v[66:67] op_sel:[0,1] op_sel_hi:[1,1]
	v_pk_fma_f32 v[8:9], v[82:83], v[68:69], v[8:9] op_sel_hi:[1,0,1]
	v_pk_fma_f32 v[38:39], v[8:9], v[68:69], v[38:39] op_sel:[0,1,0] op_sel_hi:[1,1,1]
	s_waitcnt lgkmcnt(2)
	v_pk_fma_f32 v[10:11], v[82:83], v[70:71], v[10:11] op_sel_hi:[1,0,1]
	v_pk_fma_f32 v[38:39], v[10:11], v[70:71], v[38:39] op_sel:[0,1,0] op_sel_hi:[1,1,1]
	v_pk_fma_f32 v[12:13], v[82:83], v[72:73], v[12:13] op_sel_hi:[1,0,1]
	v_pk_fma_f32 v[38:39], v[12:13], v[72:73], v[38:39] op_sel:[0,1,0] op_sel_hi:[1,1,1]
	s_waitcnt lgkmcnt(1)
	v_pk_fma_f32 v[14:15], v[82:83], v[74:75], v[14:15] op_sel_hi:[1,0,1]
	v_pk_fma_f32 v[38:39], v[14:15], v[74:75], v[38:39] op_sel:[0,1,0] op_sel_hi:[1,1,1]
	v_pk_fma_f32 v[16:17], v[82:83], v[76:77], v[16:17] op_sel_hi:[1,0,1]
	v_pk_fma_f32 v[38:39], v[16:17], v[76:77], v[38:39] op_sel:[0,1,0] op_sel_hi:[1,1,1]
	s_waitcnt lgkmcnt(0)
	v_pk_fma_f32 v[18:19], v[82:83], v[78:79], v[18:19] op_sel_hi:[1,0,1]
	v_pk_fma_f32 v[38:39], v[18:19], v[78:79], v[38:39] op_sel:[0,1,0] op_sel_hi:[1,1,1]
	v_pk_fma_f32 v[20:21], v[82:83], v[80:81], v[20:21] op_sel_hi:[1,0,1]
	v_pk_fma_f32 v[38:39], v[20:21], v[80:81], v[38:39] op_sel:[0,1,0] op_sel_hi:[1,1,1]
	s_add_u32 s14, s14, 0x1000
	s_addc_u32 s15, s15, 0
	v_add_f32_dpp v38, v38, v38 row_ror:8 row_mask:0xf bank_mask:0x3 bound_ctrl:1
	v_add_f32_dpp v38, v39, v39 row_ror:8 row_mask:0xf bank_mask:0xc bound_ctrl:1
	ds_read_b64 v[64:65], v23 offset:38144
	ds_read_b128 v[48:51], v2 offset:61696
	v_add_f32_dpp v38, v38, v38 row_half_mirror row_mask:0xf bank_mask:0xf bound_ctrl:1
	ds_read_b128 v[52:55], v2 offset:61952
	ds_read_b128 v[56:59], v2 offset:62208
	v_add_f32_dpp v38, v38, v38 quad_perm:[1,0,3,2] row_mask:0xf bank_mask:0xf bound_ctrl:1
	ds_read_b128 v[60:63], v2 offset:62464
	s_nop 0
	v_add_f32_dpp v38, v38, v38 quad_perm:[2,3,0,1] row_mask:0xf bank_mask:0xf bound_ctrl:1
	v_cvt_pk_bf16_f32 v47, v38, v38
	s_mov_b64 exec, s[2:3]
	global_store_short v28, v47, s[14:15] offset:-4096
	s_mov_b64 exec, -1
	s_waitcnt lgkmcnt(3)
	v_pk_fma_f32 v[6:7], v[64:65], v[48:49], v[6:7] op_sel_hi:[1,0,1]
	v_pk_mul_f32 v[38:39], v[6:7], v[48:49] op_sel:[0,1] op_sel_hi:[1,1]
	v_pk_fma_f32 v[8:9], v[64:65], v[50:51], v[8:9] op_sel_hi:[1,0,1]
	v_pk_fma_f32 v[38:39], v[8:9], v[50:51], v[38:39] op_sel:[0,1,0] op_sel_hi:[1,1,1]
	s_waitcnt lgkmcnt(2)
	v_pk_fma_f32 v[10:11], v[64:65], v[52:53], v[10:11] op_sel_hi:[1,0,1]
	v_pk_fma_f32 v[38:39], v[10:11], v[52:53], v[38:39] op_sel:[0,1,0] op_sel_hi:[1,1,1]
	v_pk_fma_f32 v[12:13], v[64:65], v[54:55], v[12:13] op_sel_hi:[1,0,1]
	v_pk_fma_f32 v[38:39], v[12:13], v[54:55], v[38:39] op_sel:[0,1,0] op_sel_hi:[1,1,1]
	s_waitcnt lgkmcnt(1)
	v_pk_fma_f32 v[14:15], v[64:65], v[56:57], v[14:15] op_sel_hi:[1,0,1]
	v_pk_fma_f32 v[38:39], v[14:15], v[56:57], v[38:39] op_sel:[0,1,0] op_sel_hi:[1,1,1]
	v_pk_fma_f32 v[16:17], v[64:65], v[58:59], v[16:17] op_sel_hi:[1,0,1]
	v_pk_fma_f32 v[38:39], v[16:17], v[58:59], v[38:39] op_sel:[0,1,0] op_sel_hi:[1,1,1]
	s_waitcnt lgkmcnt(0)
	v_pk_fma_f32 v[18:19], v[64:65], v[60:61], v[18:19] op_sel_hi:[1,0,1]
	v_pk_fma_f32 v[38:39], v[18:19], v[60:61], v[38:39] op_sel:[0,1,0] op_sel_hi:[1,1,1]
	v_pk_fma_f32 v[20:21], v[64:65], v[62:63], v[20:21] op_sel_hi:[1,0,1]
	v_pk_fma_f32 v[38:39], v[20:21], v[62:63], v[38:39] op_sel:[0,1,0] op_sel_hi:[1,1,1]
	s_add_u32 s14, s14, 0x1000
	s_addc_u32 s15, s15, 0
	v_add_f32_dpp v38, v38, v38 row_ror:8 row_mask:0xf bank_mask:0x3 bound_ctrl:1
	v_add_f32_dpp v38, v39, v39 row_ror:8 row_mask:0xf bank_mask:0xc bound_ctrl:1
	ds_read_b64 v[82:83], v23 offset:38400
	ds_read_b128 v[66:69], v2 offset:62720
	v_add_f32_dpp v38, v38, v38 row_half_mirror row_mask:0xf bank_mask:0xf bound_ctrl:1
	ds_read_b128 v[70:73], v2 offset:62976
	ds_read_b128 v[74:77], v2 offset:63232
	v_add_f32_dpp v38, v38, v38 quad_perm:[1,0,3,2] row_mask:0xf bank_mask:0xf bound_ctrl:1
	ds_read_b128 v[78:81], v2 offset:63488
	s_nop 0
	v_add_f32_dpp v38, v38, v38 quad_perm:[2,3,0,1] row_mask:0xf bank_mask:0xf bound_ctrl:1
	v_cvt_pk_bf16_f32 v47, v38, v38
	s_mov_b64 exec, s[2:3]
	global_store_short v28, v47, s[14:15] offset:-4096
	s_mov_b64 exec, -1
	s_waitcnt lgkmcnt(3)
	v_pk_fma_f32 v[6:7], v[82:83], v[66:67], v[6:7] op_sel_hi:[1,0,1]
	v_pk_mul_f32 v[38:39], v[6:7], v[66:67] op_sel:[0,1] op_sel_hi:[1,1]
	v_pk_fma_f32 v[8:9], v[82:83], v[68:69], v[8:9] op_sel_hi:[1,0,1]
	v_pk_fma_f32 v[38:39], v[8:9], v[68:69], v[38:39] op_sel:[0,1,0] op_sel_hi:[1,1,1]
	s_waitcnt lgkmcnt(2)
	v_pk_fma_f32 v[10:11], v[82:83], v[70:71], v[10:11] op_sel_hi:[1,0,1]
	v_pk_fma_f32 v[38:39], v[10:11], v[70:71], v[38:39] op_sel:[0,1,0] op_sel_hi:[1,1,1]
	v_pk_fma_f32 v[12:13], v[82:83], v[72:73], v[12:13] op_sel_hi:[1,0,1]
	v_pk_fma_f32 v[38:39], v[12:13], v[72:73], v[38:39] op_sel:[0,1,0] op_sel_hi:[1,1,1]
	s_waitcnt lgkmcnt(1)
	v_pk_fma_f32 v[14:15], v[82:83], v[74:75], v[14:15] op_sel_hi:[1,0,1]
	v_pk_fma_f32 v[38:39], v[14:15], v[74:75], v[38:39] op_sel:[0,1,0] op_sel_hi:[1,1,1]
	v_pk_fma_f32 v[16:17], v[82:83], v[76:77], v[16:17] op_sel_hi:[1,0,1]
	v_pk_fma_f32 v[38:39], v[16:17], v[76:77], v[38:39] op_sel:[0,1,0] op_sel_hi:[1,1,1]
	s_waitcnt lgkmcnt(0)
	v_pk_fma_f32 v[18:19], v[82:83], v[78:79], v[18:19] op_sel_hi:[1,0,1]
	v_pk_fma_f32 v[38:39], v[18:19], v[78:79], v[38:39] op_sel:[0,1,0] op_sel_hi:[1,1,1]
	v_pk_fma_f32 v[20:21], v[82:83], v[80:81], v[20:21] op_sel_hi:[1,0,1]
	v_pk_fma_f32 v[38:39], v[20:21], v[80:81], v[38:39] op_sel:[0,1,0] op_sel_hi:[1,1,1]
	s_add_u32 s14, s14, 0x1000
	s_addc_u32 s15, s15, 0
	v_add_f32_dpp v38, v38, v38 row_ror:8 row_mask:0xf bank_mask:0x3 bound_ctrl:1
	v_add_f32_dpp v38, v39, v39 row_ror:8 row_mask:0xf bank_mask:0xc bound_ctrl:1
	ds_read_b64 v[64:65], v23 offset:38656
	ds_read_b128 v[48:51], v2 offset:63744
	v_add_f32_dpp v38, v38, v38 row_half_mirror row_mask:0xf bank_mask:0xf bound_ctrl:1
	ds_read_b128 v[52:55], v2 offset:64000
	ds_read_b128 v[56:59], v2 offset:64256
	v_add_f32_dpp v38, v38, v38 quad_perm:[1,0,3,2] row_mask:0xf bank_mask:0xf bound_ctrl:1
	ds_read_b128 v[60:63], v2 offset:64512
	s_nop 0
	v_add_f32_dpp v38, v38, v38 quad_perm:[2,3,0,1] row_mask:0xf bank_mask:0xf bound_ctrl:1
	v_cvt_pk_bf16_f32 v47, v38, v38
	s_mov_b64 exec, s[2:3]
	global_store_short v28, v47, s[14:15] offset:-4096
	s_mov_b64 exec, -1
	s_waitcnt lgkmcnt(3)
	v_pk_fma_f32 v[6:7], v[64:65], v[48:49], v[6:7] op_sel_hi:[1,0,1]
	v_pk_mul_f32 v[38:39], v[6:7], v[48:49] op_sel:[0,1] op_sel_hi:[1,1]
	v_pk_fma_f32 v[8:9], v[64:65], v[50:51], v[8:9] op_sel_hi:[1,0,1]
	v_pk_fma_f32 v[38:39], v[8:9], v[50:51], v[38:39] op_sel:[0,1,0] op_sel_hi:[1,1,1]
	s_waitcnt lgkmcnt(2)
	v_pk_fma_f32 v[10:11], v[64:65], v[52:53], v[10:11] op_sel_hi:[1,0,1]
	v_pk_fma_f32 v[38:39], v[10:11], v[52:53], v[38:39] op_sel:[0,1,0] op_sel_hi:[1,1,1]
	v_pk_fma_f32 v[12:13], v[64:65], v[54:55], v[12:13] op_sel_hi:[1,0,1]
	v_pk_fma_f32 v[38:39], v[12:13], v[54:55], v[38:39] op_sel:[0,1,0] op_sel_hi:[1,1,1]
	s_waitcnt lgkmcnt(1)
	v_pk_fma_f32 v[14:15], v[64:65], v[56:57], v[14:15] op_sel_hi:[1,0,1]
	v_pk_fma_f32 v[38:39], v[14:15], v[56:57], v[38:39] op_sel:[0,1,0] op_sel_hi:[1,1,1]
	v_pk_fma_f32 v[16:17], v[64:65], v[58:59], v[16:17] op_sel_hi:[1,0,1]
	v_pk_fma_f32 v[38:39], v[16:17], v[58:59], v[38:39] op_sel:[0,1,0] op_sel_hi:[1,1,1]
	s_waitcnt lgkmcnt(0)
	v_pk_fma_f32 v[18:19], v[64:65], v[60:61], v[18:19] op_sel_hi:[1,0,1]
	v_pk_fma_f32 v[38:39], v[18:19], v[60:61], v[38:39] op_sel:[0,1,0] op_sel_hi:[1,1,1]
	v_pk_fma_f32 v[20:21], v[64:65], v[62:63], v[20:21] op_sel_hi:[1,0,1]
	v_pk_fma_f32 v[38:39], v[20:21], v[62:63], v[38:39] op_sel:[0,1,0] op_sel_hi:[1,1,1]
	s_add_u32 s14, s14, 0x1000
	s_addc_u32 s15, s15, 0
	v_add_f32_dpp v38, v38, v38 row_ror:8 row_mask:0xf bank_mask:0x3 bound_ctrl:1
	v_add_f32_dpp v38, v39, v39 row_ror:8 row_mask:0xf bank_mask:0xc bound_ctrl:1
	ds_read_b64 v[82:83], v23 offset:38912
	ds_read_b128 v[66:69], v2 offset:64768
	v_add_f32_dpp v38, v38, v38 row_half_mirror row_mask:0xf bank_mask:0xf bound_ctrl:1
	ds_read_b128 v[70:73], v2 offset:65024
	ds_read_b128 v[74:77], v2 offset:65280
	v_add_f32_dpp v38, v38, v38 quad_perm:[1,0,3,2] row_mask:0xf bank_mask:0xf bound_ctrl:1
	ds_read_b128 v[78:81], v22 offset:32768
	s_nop 0
	v_add_f32_dpp v38, v38, v38 quad_perm:[2,3,0,1] row_mask:0xf bank_mask:0xf bound_ctrl:1
	v_cvt_pk_bf16_f32 v47, v38, v38
	s_mov_b64 exec, s[2:3]
	global_store_short v28, v47, s[14:15] offset:-4096
	s_mov_b64 exec, -1
	s_waitcnt lgkmcnt(3)
	v_pk_fma_f32 v[6:7], v[82:83], v[66:67], v[6:7] op_sel_hi:[1,0,1]
	v_pk_mul_f32 v[38:39], v[6:7], v[66:67] op_sel:[0,1] op_sel_hi:[1,1]
	v_pk_fma_f32 v[8:9], v[82:83], v[68:69], v[8:9] op_sel_hi:[1,0,1]
	v_pk_fma_f32 v[38:39], v[8:9], v[68:69], v[38:39] op_sel:[0,1,0] op_sel_hi:[1,1,1]
	s_waitcnt lgkmcnt(2)
	v_pk_fma_f32 v[10:11], v[82:83], v[70:71], v[10:11] op_sel_hi:[1,0,1]
	v_pk_fma_f32 v[38:39], v[10:11], v[70:71], v[38:39] op_sel:[0,1,0] op_sel_hi:[1,1,1]
	v_pk_fma_f32 v[12:13], v[82:83], v[72:73], v[12:13] op_sel_hi:[1,0,1]
	v_pk_fma_f32 v[38:39], v[12:13], v[72:73], v[38:39] op_sel:[0,1,0] op_sel_hi:[1,1,1]
	s_waitcnt lgkmcnt(1)
	v_pk_fma_f32 v[14:15], v[82:83], v[74:75], v[14:15] op_sel_hi:[1,0,1]
	v_pk_fma_f32 v[38:39], v[14:15], v[74:75], v[38:39] op_sel:[0,1,0] op_sel_hi:[1,1,1]
	v_pk_fma_f32 v[16:17], v[82:83], v[76:77], v[16:17] op_sel_hi:[1,0,1]
	v_pk_fma_f32 v[38:39], v[16:17], v[76:77], v[38:39] op_sel:[0,1,0] op_sel_hi:[1,1,1]
	s_waitcnt lgkmcnt(0)
	v_pk_fma_f32 v[18:19], v[82:83], v[78:79], v[18:19] op_sel_hi:[1,0,1]
	v_pk_fma_f32 v[38:39], v[18:19], v[78:79], v[38:39] op_sel:[0,1,0] op_sel_hi:[1,1,1]
	v_pk_fma_f32 v[20:21], v[82:83], v[80:81], v[20:21] op_sel_hi:[1,0,1]
	v_pk_fma_f32 v[38:39], v[20:21], v[80:81], v[38:39] op_sel:[0,1,0] op_sel_hi:[1,1,1]
	s_add_u32 s14, s14, 0x1000
	s_addc_u32 s15, s15, 0
	v_add_f32_dpp v38, v38, v38 row_ror:8 row_mask:0xf bank_mask:0x3 bound_ctrl:1
	v_add_f32_dpp v38, v39, v39 row_ror:8 row_mask:0xf bank_mask:0xc bound_ctrl:1
	ds_read_b64 v[64:65], v3 offset:20736
	ds_read_b128 v[48:51], v2 offset:8448
	v_add_f32_dpp v38, v38, v38 row_half_mirror row_mask:0xf bank_mask:0xf bound_ctrl:1
	ds_read_b128 v[52:55], v2 offset:8704
	ds_read_b128 v[56:59], v2 offset:8960
	v_add_f32_dpp v38, v38, v38 quad_perm:[1,0,3,2] row_mask:0xf bank_mask:0xf bound_ctrl:1
	ds_read_b128 v[60:63], v2 offset:9216
	s_nop 0
	v_add_f32_dpp v38, v38, v38 quad_perm:[2,3,0,1] row_mask:0xf bank_mask:0xf bound_ctrl:1
	v_cvt_pk_bf16_f32 v47, v38, v38
	s_mov_b64 exec, s[2:3]
	global_store_short v28, v47, s[14:15] offset:-4096
	s_mov_b64 exec, -1
	s_waitcnt vmcnt(8)
	v_lshlrev_b32_e32 v108, 16, v84
	v_lshlrev_b32_e32 v109, 16, v85
	v_and_b32_e32 v110, s17, v84
	v_and_b32_e32 v111, s17, v85
	v_lshlrev_b32_e32 v112, 16, v86
	v_lshlrev_b32_e32 v113, 16, v87
	v_and_b32_e32 v114, s17, v86
	v_and_b32_e32 v115, s17, v87
	v_lshlrev_b32_e32 v116, 16, v88
	v_and_b32_e32 v117, s17, v88
	v_rcp_f32_e32 v25, v24
	v_mul_f32_e32 v113, v24, v113
	v_mul_f32_e32 v115, v24, v115
	v_mul_f32_e32 v109, 0x3db504f3, v109
	v_mul_f32_e32 v111, 0x3db504f3, v111
	v_cndmask_b32_e64 v27, 1.0, v25, s[20:21]
	v_mul_f32_e32 v24, v24, v26
	v_mul_f32_e32 v116, v27, v116
	v_mul_f32_e32 v117, v27, v117
	ds_write_b128 v29, v[108:111] offset:24832
	ds_write_b128 v29, v[112:115] offset:33024
	ds_write_b64 v30, v[90:91] offset:24832
	ds_write_b64 v31, v[116:117] offset:24832
	s_add_i32 s16, s16, 8
	s_waitcnt lgkmcnt(0)
	global_load_dword v84, v32, s[10:11]
	global_load_dword v85, v32, s[10:11] offset:-1024
	global_load_dword v86, v33, s[10:11]
	global_load_dword v87, v33, s[10:11] offset:-1024
	global_load_dword v88, v34, s[10:11]
	global_load_dword v90, v35, s[12:13]
	global_load_dword v91, v35, s[12:13] offset:4
	s_add_u32 s10, s10, 0x18000
	s_addc_u32 s11, s11, 0
	s_add_u32 s12, s12, 0x4000
	s_addc_u32 s13, s13, 0
	s_barrier
	s_cmpk_lt_u32 s16, 0x800
	s_cbranch_scc1 .Lret2_loop
.Lret2_done:
	s_waitcnt vmcnt(0)
	v_readlane_b32 s0, v255, 18
	v_readlane_b32 s1, v255, 19
	s_load_dwordx2 s[2:3], s[0:1], 0xe8
	s_lshr_b32 s0, s23, 5
	s_lshl_b32 s4, s0, 17
	s_add_u32 s4, s4, 78430464
	v_lshl_add_u32 v42, v46, 1, v4
	s_waitcnt lgkmcnt(0)
	s_add_u32 s2, s2, s4
	s_addc_u32 s3, s3, 0
	v_pk_mul_f32 v[6:7], v[6:7], v[40:41] op_sel:[0,1] op_sel_hi:[1,1]
	v_pk_mul_f32 v[8:9], v[8:9], v[40:41] op_sel:[0,1] op_sel_hi:[1,1]
	v_pk_mul_f32 v[10:11], v[10:11], v[40:41] op_sel:[0,1] op_sel_hi:[1,1]
	v_pk_mul_f32 v[12:13], v[12:13], v[40:41] op_sel:[0,1] op_sel_hi:[1,1]
	v_pk_mul_f32 v[14:15], v[14:15], v[40:41] op_sel:[0,1] op_sel_hi:[1,1]
	v_pk_mul_f32 v[16:17], v[16:17], v[40:41] op_sel:[0,1] op_sel_hi:[1,1]
	v_pk_mul_f32 v[18:19], v[18:19], v[40:41] op_sel:[0,1] op_sel_hi:[1,1]
	v_pk_mul_f32 v[20:21], v[20:21], v[40:41] op_sel:[0,1] op_sel_hi:[1,1]
	global_store_dwordx2 v42, v[6:7], s[2:3] offset:0
	global_store_dwordx2 v42, v[8:9], s[2:3] offset:1024
	global_store_dwordx2 v42, v[10:11], s[2:3] offset:2048
	global_store_dwordx2 v42, v[12:13], s[2:3] offset:3072
	s_add_u32 s2, s2, 0x1000
	s_addc_u32 s3, s3, 0
	global_store_dwordx2 v42, v[14:15], s[2:3] offset:0
	global_store_dwordx2 v42, v[16:17], s[2:3] offset:1024
	global_store_dwordx2 v42, v[18:19], s[2:3] offset:2048
	global_store_dwordx2 v42, v[20:21], s[2:3] offset:3072
	s_add_i32 s23, s23, s19
	s_waitcnt vmcnt(0)
	s_cmpk_lt_i32 s23, 0x400
	s_cbranch_scc1 .Lret2_item
	s_branch .LBB0_57

.Lgla2_gw2:
	s_mov_b32 s20, 0xffff0000
	s_mov_b32 s21, -1
	global_load_dword v110, v32, s[10:11]
	global_load_dword v111, v32, s[10:11] offset:-1024
	global_load_dword v112, v33, s[10:11]
	global_load_dword v113, v33, s[10:11] offset:-1024
	global_load_dword v114, v34, s[10:11]
	global_load_dword v116, v35, s[12:13]
	global_load_dword v117, v35, s[12:13] offset:4
	s_add_u32 s10, s10, 0x18000
	s_addc_u32 s11, s11, 0
	s_add_u32 s12, s12, 0x4000
	s_addc_u32 s13, s13, 0
	s_waitcnt vmcnt(0)
	v_lshlrev_b32_e32 v144, 16, v110
	v_lshlrev_b32_e32 v145, 16, v111
	v_and_b32_e32 v146, s17, v110
	v_and_b32_e32 v147, s17, v111
	v_lshlrev_b32_e32 v148, 16, v112
	v_lshlrev_b32_e32 v149, 16, v113
	v_and_b32_e32 v150, s17, v112
	v_and_b32_e32 v151, s17, v113
	v_lshlrev_b32_e32 v152, 16, v114
	v_and_b32_e32 v153, s17, v114
	v_rcp_f32_e32 v25, v24
	v_mul_f32_e32 v149, v24, v149
	v_mul_f32_e32 v151, v24, v151
	v_mul_f32_e32 v145, 0x3db504f3, v145
	v_mul_f32_e32 v147, 0x3db504f3, v147
	v_cndmask_b32_e64 v27, 1.0, v25, s[20:21]
	v_mul_f32_e32 v24, v24, v26
	v_mul_f32_e32 v152, v27, v152
	v_mul_f32_e32 v153, v27, v153
	ds_write_b128 v29, v[144:147] offset:256
	ds_write_b128 v29, v[148:151] offset:8448
	ds_write_b64 v30, v[116:117] offset:256
	ds_write_b64 v31, v[152:153] offset:256
	global_load_dword v110, v32, s[10:11]
	global_load_dword v111, v32, s[10:11] offset:-1024
	global_load_dword v112, v33, s[10:11]
	global_load_dword v113, v33, s[10:11] offset:-1024
	global_load_dword v114, v34, s[10:11]
	global_load_dword v116, v35, s[12:13]
	global_load_dword v117, v35, s[12:13] offset:4
	s_add_u32 s10, s10, 0x18000
	s_addc_u32 s11, s11, 0
	s_add_u32 s12, s12, 0x4000
	s_addc_u32 s13, s13, 0
	s_waitcnt vmcnt(0)
	v_lshlrev_b32_e32 v144, 16, v110
	v_lshlrev_b32_e32 v145, 16, v111
	v_and_b32_e32 v146, s17, v110
	v_and_b32_e32 v147, s17, v111
	v_lshlrev_b32_e32 v148, 16, v112
	v_lshlrev_b32_e32 v149, 16, v113
	v_and_b32_e32 v150, s17, v112
	v_and_b32_e32 v151, s17, v113
	v_lshlrev_b32_e32 v152, 16, v114
	v_and_b32_e32 v153, s17, v114
	v_rcp_f32_e32 v25, v24
	v_mul_f32_e32 v149, v24, v149
	v_mul_f32_e32 v151, v24, v151
	v_mul_f32_e32 v145, 0x3db504f3, v145
	v_mul_f32_e32 v147, 0x3db504f3, v147
	v_cndmask_b32_e64 v27, 1.0, v25, s[20:21]
	v_mul_f32_e32 v24, v24, v26
	v_mul_f32_e32 v152, v27, v152
	v_mul_f32_e32 v153, v27, v153
	ds_write_b128 v29, v[144:147] offset:24832
	ds_write_b128 v29, v[148:151] offset:33024
	ds_write_b64 v30, v[116:117] offset:24832
	ds_write_b64 v31, v[152:153] offset:24832
	global_load_dword v110, v32, s[10:11]
	global_load_dword v111, v32, s[10:11] offset:-1024
	global_load_dword v112, v33, s[10:11]
	global_load_dword v113, v33, s[10:11] offset:-1024
	global_load_dword v114, v34, s[10:11]
	global_load_dword v116, v35, s[12:13]
	global_load_dword v117, v35, s[12:13] offset:4
	s_add_u32 s10, s10, 0x18000
	s_addc_u32 s11, s11, 0
	s_add_u32 s12, s12, 0x4000
	s_addc_u32 s13, s13, 0
	v_add_u32_e32 v22, 0x8000, v2
	v_add_u32_e32 v23, 0x8000, v3
	v_mov_b32_e32 v6, 0
	v_mov_b32_e32 v7, 0
	v_mov_b32_e32 v8, 0
	v_mov_b32_e32 v9, 0
	v_mov_b32_e32 v10, 0
	v_mov_b32_e32 v11, 0
	v_mov_b32_e32 v12, 0
	v_mov_b32_e32 v13, 0
	v_mov_b32_e32 v14, 0
	v_mov_b32_e32 v15, 0
	v_mov_b32_e32 v16, 0
	v_mov_b32_e32 v17, 0
	v_mov_b32_e32 v18, 0
	v_mov_b32_e32 v19, 0
	v_mov_b32_e32 v20, 0
	v_mov_b32_e32 v21, 0
	s_mov_b32 s16, 0
	s_mov_b32 s2, 0x01010101
	s_mov_b32 s3, 0x01010101
	v_and_b32_e32 v28, 8, v198
	v_lshrrev_b32_e32 v28, 2, v28
	v_add_u32_e32 v28, v46, v28
	s_waitcnt vmcnt(0) lgkmcnt(0)
	s_barrier
	ds_read_b64 v[72:73], v3 offset:20736
	ds_read_b128 v[48:51], v2 offset:256
	ds_read_b128 v[64:67], v2 offset:16640
	ds_read_b128 v[52:55], v2 offset:512
	ds_read_b128 v[56:59], v2 offset:768
	ds_read_b128 v[68:71], v2 offset:16896
	ds_read_b128 v[60:63], v2 offset:1024
.Lgla2_loop:
	s_waitcnt lgkmcnt(4)
	v_pk_mul_f32 v[42:43], v[72:73], v[48:49] op_sel_hi:[1,0]
	v_pk_fma_f32 v[6:7], v[6:7], v[64:65], v[42:43] op_sel:[0,0,0] op_sel_hi:[1,0,1]
	v_pk_mul_f32 v[38:39], v[6:7], v[48:49] op_sel:[0,1] op_sel_hi:[1,1]
	v_pk_mul_f32 v[44:45], v[72:73], v[50:51] op_sel_hi:[1,0]
	v_pk_fma_f32 v[8:9], v[8:9], v[64:65], v[44:45] op_sel:[0,1,0] op_sel_hi:[1,1,1]
	v_pk_fma_f32 v[38:39], v[8:9], v[50:51], v[38:39] op_sel:[0,1,0] op_sel_hi:[1,1,1]
	s_waitcnt lgkmcnt(3)
	v_pk_mul_f32 v[42:43], v[72:73], v[52:53] op_sel_hi:[1,0]
	v_pk_fma_f32 v[10:11], v[10:11], v[66:67], v[42:43] op_sel:[0,0,0] op_sel_hi:[1,0,1]
	v_pk_fma_f32 v[38:39], v[10:11], v[52:53], v[38:39] op_sel:[0,1,0] op_sel_hi:[1,1,1]
	v_pk_mul_f32 v[44:45], v[72:73], v[54:55] op_sel_hi:[1,0]
	v_pk_fma_f32 v[12:13], v[12:13], v[66:67], v[44:45] op_sel:[0,1,0] op_sel_hi:[1,1,1]
	v_pk_fma_f32 v[38:39], v[12:13], v[54:55], v[38:39] op_sel:[0,1,0] op_sel_hi:[1,1,1]
	s_waitcnt lgkmcnt(1)
	v_pk_mul_f32 v[42:43], v[72:73], v[56:57] op_sel_hi:[1,0]
	v_pk_fma_f32 v[14:15], v[14:15], v[68:69], v[42:43] op_sel:[0,0,0] op_sel_hi:[1,0,1]
	v_pk_fma_f32 v[38:39], v[14:15], v[56:57], v[38:39] op_sel:[0,1,0] op_sel_hi:[1,1,1]
	v_pk_mul_f32 v[44:45], v[72:73], v[58:59] op_sel_hi:[1,0]
	v_pk_fma_f32 v[16:17], v[16:17], v[68:69], v[44:45] op_sel:[0,1,0] op_sel_hi:[1,1,1]
	v_pk_fma_f32 v[38:39], v[16:17], v[58:59], v[38:39] op_sel:[0,1,0] op_sel_hi:[1,1,1]
	s_waitcnt lgkmcnt(0)
	v_pk_mul_f32 v[42:43], v[72:73], v[60:61] op_sel_hi:[1,0]
	v_pk_fma_f32 v[18:19], v[18:19], v[70:71], v[42:43] op_sel:[0,0,0] op_sel_hi:[1,0,1]
	v_pk_fma_f32 v[38:39], v[18:19], v[60:61], v[38:39] op_sel:[0,1,0] op_sel_hi:[1,1,1]
	v_pk_mul_f32 v[44:45], v[72:73], v[62:63] op_sel_hi:[1,0]
	v_pk_fma_f32 v[20:21], v[20:21], v[70:71], v[44:45] op_sel:[0,1,0] op_sel_hi:[1,1,1]
	v_pk_fma_f32 v[38:39], v[20:21], v[62:63], v[38:39] op_sel:[0,1,0] op_sel_hi:[1,1,1]
	s_add_u32 s14, s14, 0x1000
	s_addc_u32 s15, s15, 0
	v_add_f32_dpp v38, v38, v38 row_ror:8 row_mask:0xf bank_mask:0x3 bound_ctrl:1
	v_add_f32_dpp v38, v39, v39 row_ror:8 row_mask:0xf bank_mask:0xc bound_ctrl:1
	ds_read_b64 v[104:105], v3 offset:20992
	ds_read_b128 v[80:83], v2 offset:1280
	v_add_f32_dpp v38, v38, v38 row_half_mirror row_mask:0xf bank_mask:0xf bound_ctrl:1
	ds_read_b128 v[96:99], v2 offset:17152
	ds_read_b128 v[84:87], v2 offset:1536
	v_add_f32_dpp v38, v38, v38 quad_perm:[1,0,3,2] row_mask:0xf bank_mask:0xf bound_ctrl:1
	ds_read_b128 v[88:91], v2 offset:1792
	ds_read_b128 v[100:103], v2 offset:17408
	v_add_f32_dpp v38, v38, v38 quad_perm:[2,3,0,1] row_mask:0xf bank_mask:0xf bound_ctrl:1
	ds_read_b128 v[92:95], v2 offset:2048
	v_cvt_pk_bf16_f32 v47, v38, v38
	s_mov_b64 exec, s[2:3]
	global_store_short v28, v47, s[14:15] offset:-4096
	s_mov_b64 exec, -1
	s_waitcnt lgkmcnt(4)
	v_pk_mul_f32 v[42:43], v[104:105], v[80:81] op_sel_hi:[1,0]
	v_pk_fma_f32 v[6:7], v[6:7], v[96:97], v[42:43] op_sel:[0,0,0] op_sel_hi:[1,0,1]
	v_pk_mul_f32 v[38:39], v[6:7], v[80:81] op_sel:[0,1] op_sel_hi:[1,1]
	v_pk_mul_f32 v[44:45], v[104:105], v[82:83] op_sel_hi:[1,0]
	v_pk_fma_f32 v[8:9], v[8:9], v[96:97], v[44:45] op_sel:[0,1,0] op_sel_hi:[1,1,1]
	v_pk_fma_f32 v[38:39], v[8:9], v[82:83], v[38:39] op_sel:[0,1,0] op_sel_hi:[1,1,1]
	s_waitcnt lgkmcnt(3)
	v_pk_mul_f32 v[42:43], v[104:105], v[84:85] op_sel_hi:[1,0]
	v_pk_fma_f32 v[10:11], v[10:11], v[98:99], v[42:43] op_sel:[0,0,0] op_sel_hi:[1,0,1]
	v_pk_fma_f32 v[38:39], v[10:11], v[84:85], v[38:39] op_sel:[0,1,0] op_sel_hi:[1,1,1]
	v_pk_mul_f32 v[44:45], v[104:105], v[86:87] op_sel_hi:[1,0]
	v_pk_fma_f32 v[12:13], v[12:13], v[98:99], v[44:45] op_sel:[0,1,0] op_sel_hi:[1,1,1]
	v_pk_fma_f32 v[38:39], v[12:13], v[86:87], v[38:39] op_sel:[0,1,0] op_sel_hi:[1,1,1]
	s_waitcnt lgkmcnt(1)
	v_pk_mul_f32 v[42:43], v[104:105], v[88:89] op_sel_hi:[1,0]
	v_pk_fma_f32 v[14:15], v[14:15], v[100:101], v[42:43] op_sel:[0,0,0] op_sel_hi:[1,0,1]
	v_pk_fma_f32 v[38:39], v[14:15], v[88:89], v[38:39] op_sel:[0,1,0] op_sel_hi:[1,1,1]
	v_pk_mul_f32 v[44:45], v[104:105], v[90:91] op_sel_hi:[1,0]
	v_pk_fma_f32 v[16:17], v[16:17], v[100:101], v[44:45] op_sel:[0,1,0] op_sel_hi:[1,1,1]
	v_pk_fma_f32 v[38:39], v[16:17], v[90:91], v[38:39] op_sel:[0,1,0] op_sel_hi:[1,1,1]
	s_waitcnt lgkmcnt(0)
	v_pk_mul_f32 v[42:43], v[104:105], v[92:93] op_sel_hi:[1,0]
	v_pk_fma_f32 v[18:19], v[18:19], v[102:103], v[42:43] op_sel:[0,0,0] op_sel_hi:[1,0,1]
	v_pk_fma_f32 v[38:39], v[18:19], v[92:93], v[38:39] op_sel:[0,1,0] op_sel_hi:[1,1,1]
	v_pk_mul_f32 v[44:45], v[104:105], v[94:95] op_sel_hi:[1,0]
	v_pk_fma_f32 v[20:21], v[20:21], v[102:103], v[44:45] op_sel:[0,1,0] op_sel_hi:[1,1,1]
	v_pk_fma_f32 v[38:39], v[20:21], v[94:95], v[38:39] op_sel:[0,1,0] op_sel_hi:[1,1,1]
	s_add_u32 s14, s14, 0x1000
	s_addc_u32 s15, s15, 0
	v_add_f32_dpp v38, v38, v38 row_ror:8 row_mask:0xf bank_mask:0x3 bound_ctrl:1
	v_add_f32_dpp v38, v39, v39 row_ror:8 row_mask:0xf bank_mask:0xc bound_ctrl:1
	ds_read_b64 v[72:73], v3 offset:21248
	ds_read_b128 v[48:51], v2 offset:2304
	v_add_f32_dpp v38, v38, v38 row_half_mirror row_mask:0xf bank_mask:0xf bound_ctrl:1
	ds_read_b128 v[64:67], v2 offset:17664
	ds_read_b128 v[52:55], v2 offset:2560
	v_add_f32_dpp v38, v38, v38 quad_perm:[1,0,3,2] row_mask:0xf bank_mask:0xf bound_ctrl:1
	ds_read_b128 v[56:59], v2 offset:2816
	ds_read_b128 v[68:71], v2 offset:17920
	v_add_f32_dpp v38, v38, v38 quad_perm:[2,3,0,1] row_mask:0xf bank_mask:0xf bound_ctrl:1
	ds_read_b128 v[60:63], v2 offset:3072
	v_cvt_pk_bf16_f32 v47, v38, v38
	s_mov_b64 exec, s[2:3]
	global_store_short v28, v47, s[14:15] offset:-4096
	s_mov_b64 exec, -1
	s_waitcnt lgkmcnt(4)
	v_pk_mul_f32 v[42:43], v[72:73], v[48:49] op_sel_hi:[1,0]
	v_pk_fma_f32 v[6:7], v[6:7], v[64:65], v[42:43] op_sel:[0,0,0] op_sel_hi:[1,0,1]
	v_pk_mul_f32 v[38:39], v[6:7], v[48:49] op_sel:[0,1] op_sel_hi:[1,1]
	v_pk_mul_f32 v[44:45], v[72:73], v[50:51] op_sel_hi:[1,0]
	v_pk_fma_f32 v[8:9], v[8:9], v[64:65], v[44:45] op_sel:[0,1,0] op_sel_hi:[1,1,1]
	v_pk_fma_f32 v[38:39], v[8:9], v[50:51], v[38:39] op_sel:[0,1,0] op_sel_hi:[1,1,1]
	s_waitcnt lgkmcnt(3)
	v_pk_mul_f32 v[42:43], v[72:73], v[52:53] op_sel_hi:[1,0]
	v_pk_fma_f32 v[10:11], v[10:11], v[66:67], v[42:43] op_sel:[0,0,0] op_sel_hi:[1,0,1]
	v_pk_fma_f32 v[38:39], v[10:11], v[52:53], v[38:39] op_sel:[0,1,0] op_sel_hi:[1,1,1]
	v_pk_mul_f32 v[44:45], v[72:73], v[54:55] op_sel_hi:[1,0]
	v_pk_fma_f32 v[12:13], v[12:13], v[66:67], v[44:45] op_sel:[0,1,0] op_sel_hi:[1,1,1]
	v_pk_fma_f32 v[38:39], v[12:13], v[54:55], v[38:39] op_sel:[0,1,0] op_sel_hi:[1,1,1]
	s_waitcnt lgkmcnt(1)
	v_pk_mul_f32 v[42:43], v[72:73], v[56:57] op_sel_hi:[1,0]
	v_pk_fma_f32 v[14:15], v[14:15], v[68:69], v[42:43] op_sel:[0,0,0] op_sel_hi:[1,0,1]
	v_pk_fma_f32 v[38:39], v[14:15], v[56:57], v[38:39] op_sel:[0,1,0] op_sel_hi:[1,1,1]
	v_pk_mul_f32 v[44:45], v[72:73], v[58:59] op_sel_hi:[1,0]
	v_pk_fma_f32 v[16:17], v[16:17], v[68:69], v[44:45] op_sel:[0,1,0] op_sel_hi:[1,1,1]
	v_pk_fma_f32 v[38:39], v[16:17], v[58:59], v[38:39] op_sel:[0,1,0] op_sel_hi:[1,1,1]
	s_waitcnt lgkmcnt(0)
	v_pk_mul_f32 v[42:43], v[72:73], v[60:61] op_sel_hi:[1,0]
	v_pk_fma_f32 v[18:19], v[18:19], v[70:71], v[42:43] op_sel:[0,0,0] op_sel_hi:[1,0,1]
	v_pk_fma_f32 v[38:39], v[18:19], v[60:61], v[38:39] op_sel:[0,1,0] op_sel_hi:[1,1,1]
	v_pk_mul_f32 v[44:45], v[72:73], v[62:63] op_sel_hi:[1,0]
	v_pk_fma_f32 v[20:21], v[20:21], v[70:71], v[44:45] op_sel:[0,1,0] op_sel_hi:[1,1,1]
	v_pk_fma_f32 v[38:39], v[20:21], v[62:63], v[38:39] op_sel:[0,1,0] op_sel_hi:[1,1,1]
	s_add_u32 s14, s14, 0x1000
	s_addc_u32 s15, s15, 0
	v_add_f32_dpp v38, v38, v38 row_ror:8 row_mask:0xf bank_mask:0x3 bound_ctrl:1
	v_add_f32_dpp v38, v39, v39 row_ror:8 row_mask:0xf bank_mask:0xc bound_ctrl:1
	ds_read_b64 v[104:105], v3 offset:21504
	ds_read_b128 v[80:83], v2 offset:3328
	v_add_f32_dpp v38, v38, v38 row_half_mirror row_mask:0xf bank_mask:0xf bound_ctrl:1
	ds_read_b128 v[96:99], v2 offset:18176
	ds_read_b128 v[84:87], v2 offset:3584
	v_add_f32_dpp v38, v38, v38 quad_perm:[1,0,3,2] row_mask:0xf bank_mask:0xf bound_ctrl:1
	ds_read_b128 v[88:91], v2 offset:3840
	ds_read_b128 v[100:103], v2 offset:18432
	v_add_f32_dpp v38, v38, v38 quad_perm:[2,3,0,1] row_mask:0xf bank_mask:0xf bound_ctrl:1
	ds_read_b128 v[92:95], v2 offset:4096
	v_cvt_pk_bf16_f32 v47, v38, v38
	s_mov_b64 exec, s[2:3]
	global_store_short v28, v47, s[14:15] offset:-4096
	s_mov_b64 exec, -1
	s_waitcnt lgkmcnt(4)
	v_pk_mul_f32 v[42:43], v[104:105], v[80:81] op_sel_hi:[1,0]
	v_pk_fma_f32 v[6:7], v[6:7], v[96:97], v[42:43] op_sel:[0,0,0] op_sel_hi:[1,0,1]
	v_pk_mul_f32 v[38:39], v[6:7], v[80:81] op_sel:[0,1] op_sel_hi:[1,1]
	v_pk_mul_f32 v[44:45], v[104:105], v[82:83] op_sel_hi:[1,0]
	v_pk_fma_f32 v[8:9], v[8:9], v[96:97], v[44:45] op_sel:[0,1,0] op_sel_hi:[1,1,1]
	v_pk_fma_f32 v[38:39], v[8:9], v[82:83], v[38:39] op_sel:[0,1,0] op_sel_hi:[1,1,1]
	s_waitcnt lgkmcnt(3)
	v_pk_mul_f32 v[42:43], v[104:105], v[84:85] op_sel_hi:[1,0]
	v_pk_fma_f32 v[10:11], v[10:11], v[98:99], v[42:43] op_sel:[0,0,0] op_sel_hi:[1,0,1]
	v_pk_fma_f32 v[38:39], v[10:11], v[84:85], v[38:39] op_sel:[0,1,0] op_sel_hi:[1,1,1]
	v_pk_mul_f32 v[44:45], v[104:105], v[86:87] op_sel_hi:[1,0]
	v_pk_fma_f32 v[12:13], v[12:13], v[98:99], v[44:45] op_sel:[0,1,0] op_sel_hi:[1,1,1]
	v_pk_fma_f32 v[38:39], v[12:13], v[86:87], v[38:39] op_sel:[0,1,0] op_sel_hi:[1,1,1]
	s_waitcnt lgkmcnt(1)
	v_pk_mul_f32 v[42:43], v[104:105], v[88:89] op_sel_hi:[1,0]
	v_pk_fma_f32 v[14:15], v[14:15], v[100:101], v[42:43] op_sel:[0,0,0] op_sel_hi:[1,0,1]
	v_pk_fma_f32 v[38:39], v[14:15], v[88:89], v[38:39] op_sel:[0,1,0] op_sel_hi:[1,1,1]
	v_pk_mul_f32 v[44:45], v[104:105], v[90:91] op_sel_hi:[1,0]
	v_pk_fma_f32 v[16:17], v[16:17], v[100:101], v[44:45] op_sel:[0,1,0] op_sel_hi:[1,1,1]
	v_pk_fma_f32 v[38:39], v[16:17], v[90:91], v[38:39] op_sel:[0,1,0] op_sel_hi:[1,1,1]
	s_waitcnt lgkmcnt(0)
	v_pk_mul_f32 v[42:43], v[104:105], v[92:93] op_sel_hi:[1,0]
	v_pk_fma_f32 v[18:19], v[18:19], v[102:103], v[42:43] op_sel:[0,0,0] op_sel_hi:[1,0,1]
	v_pk_fma_f32 v[38:39], v[18:19], v[92:93], v[38:39] op_sel:[0,1,0] op_sel_hi:[1,1,1]
	v_pk_mul_f32 v[44:45], v[104:105], v[94:95] op_sel_hi:[1,0]
	v_pk_fma_f32 v[20:21], v[20:21], v[102:103], v[44:45] op_sel:[0,1,0] op_sel_hi:[1,1,1]
	v_pk_fma_f32 v[38:39], v[20:21], v[94:95], v[38:39] op_sel:[0,1,0] op_sel_hi:[1,1,1]
	s_add_u32 s14, s14, 0x1000
	s_addc_u32 s15, s15, 0
	v_add_f32_dpp v38, v38, v38 row_ror:8 row_mask:0xf bank_mask:0x3 bound_ctrl:1
	v_add_f32_dpp v38, v39, v39 row_ror:8 row_mask:0xf bank_mask:0xc bound_ctrl:1
	ds_read_b64 v[72:73], v3 offset:21760
	ds_read_b128 v[48:51], v2 offset:4352
	v_add_f32_dpp v38, v38, v38 row_half_mirror row_mask:0xf bank_mask:0xf bound_ctrl:1
	ds_read_b128 v[64:67], v2 offset:18688
	ds_read_b128 v[52:55], v2 offset:4608
	v_add_f32_dpp v38, v38, v38 quad_perm:[1,0,3,2] row_mask:0xf bank_mask:0xf bound_ctrl:1
	ds_read_b128 v[56:59], v2 offset:4864
	ds_read_b128 v[68:71], v2 offset:18944
	v_add_f32_dpp v38, v38, v38 quad_perm:[2,3,0,1] row_mask:0xf bank_mask:0xf bound_ctrl:1
	ds_read_b128 v[60:63], v2 offset:5120
	v_cvt_pk_bf16_f32 v47, v38, v38
	s_mov_b64 exec, s[2:3]
	global_store_short v28, v47, s[14:15] offset:-4096
	s_mov_b64 exec, -1
	s_waitcnt lgkmcnt(4)
	v_pk_mul_f32 v[42:43], v[72:73], v[48:49] op_sel_hi:[1,0]
	v_pk_fma_f32 v[6:7], v[6:7], v[64:65], v[42:43] op_sel:[0,0,0] op_sel_hi:[1,0,1]
	v_pk_mul_f32 v[38:39], v[6:7], v[48:49] op_sel:[0,1] op_sel_hi:[1,1]
	v_pk_mul_f32 v[44:45], v[72:73], v[50:51] op_sel_hi:[1,0]
	v_pk_fma_f32 v[8:9], v[8:9], v[64:65], v[44:45] op_sel:[0,1,0] op_sel_hi:[1,1,1]
	v_pk_fma_f32 v[38:39], v[8:9], v[50:51], v[38:39] op_sel:[0,1,0] op_sel_hi:[1,1,1]
	s_waitcnt lgkmcnt(3)
	v_pk_mul_f32 v[42:43], v[72:73], v[52:53] op_sel_hi:[1,0]
	v_pk_fma_f32 v[10:11], v[10:11], v[66:67], v[42:43] op_sel:[0,0,0] op_sel_hi:[1,0,1]
	v_pk_fma_f32 v[38:39], v[10:11], v[52:53], v[38:39] op_sel:[0,1,0] op_sel_hi:[1,1,1]
	v_pk_mul_f32 v[44:45], v[72:73], v[54:55] op_sel_hi:[1,0]
	v_pk_fma_f32 v[12:13], v[12:13], v[66:67], v[44:45] op_sel:[0,1,0] op_sel_hi:[1,1,1]
	v_pk_fma_f32 v[38:39], v[12:13], v[54:55], v[38:39] op_sel:[0,1,0] op_sel_hi:[1,1,1]
	s_waitcnt lgkmcnt(1)
	v_pk_mul_f32 v[42:43], v[72:73], v[56:57] op_sel_hi:[1,0]
	v_pk_fma_f32 v[14:15], v[14:15], v[68:69], v[42:43] op_sel:[0,0,0] op_sel_hi:[1,0,1]
	v_pk_fma_f32 v[38:39], v[14:15], v[56:57], v[38:39] op_sel:[0,1,0] op_sel_hi:[1,1,1]
	v_pk_mul_f32 v[44:45], v[72:73], v[58:59] op_sel_hi:[1,0]
	v_pk_fma_f32 v[16:17], v[16:17], v[68:69], v[44:45] op_sel:[0,1,0] op_sel_hi:[1,1,1]
	v_pk_fma_f32 v[38:39], v[16:17], v[58:59], v[38:39] op_sel:[0,1,0] op_sel_hi:[1,1,1]
	s_waitcnt lgkmcnt(0)
	v_pk_mul_f32 v[42:43], v[72:73], v[60:61] op_sel_hi:[1,0]
	v_pk_fma_f32 v[18:19], v[18:19], v[70:71], v[42:43] op_sel:[0,0,0] op_sel_hi:[1,0,1]
	v_pk_fma_f32 v[38:39], v[18:19], v[60:61], v[38:39] op_sel:[0,1,0] op_sel_hi:[1,1,1]
	v_pk_mul_f32 v[44:45], v[72:73], v[62:63] op_sel_hi:[1,0]
	v_pk_fma_f32 v[20:21], v[20:21], v[70:71], v[44:45] op_sel:[0,1,0] op_sel_hi:[1,1,1]
	v_pk_fma_f32 v[38:39], v[20:21], v[62:63], v[38:39] op_sel:[0,1,0] op_sel_hi:[1,1,1]
	s_add_u32 s14, s14, 0x1000
	s_addc_u32 s15, s15, 0
	v_add_f32_dpp v38, v38, v38 row_ror:8 row_mask:0xf bank_mask:0x3 bound_ctrl:1
	v_add_f32_dpp v38, v39, v39 row_ror:8 row_mask:0xf bank_mask:0xc bound_ctrl:1
	ds_read_b64 v[104:105], v3 offset:22016
	ds_read_b128 v[80:83], v2 offset:5376
	v_add_f32_dpp v38, v38, v38 row_half_mirror row_mask:0xf bank_mask:0xf bound_ctrl:1
	ds_read_b128 v[96:99], v2 offset:19200
	ds_read_b128 v[84:87], v2 offset:5632
	v_add_f32_dpp v38, v38, v38 quad_perm:[1,0,3,2] row_mask:0xf bank_mask:0xf bound_ctrl:1
	ds_read_b128 v[88:91], v2 offset:5888
	ds_read_b128 v[100:103], v2 offset:19456
	v_add_f32_dpp v38, v38, v38 quad_perm:[2,3,0,1] row_mask:0xf bank_mask:0xf bound_ctrl:1
	ds_read_b128 v[92:95], v2 offset:6144
	v_cvt_pk_bf16_f32 v47, v38, v38
	s_mov_b64 exec, s[2:3]
	global_store_short v28, v47, s[14:15] offset:-4096
	s_mov_b64 exec, -1
	s_waitcnt lgkmcnt(4)
	v_pk_mul_f32 v[42:43], v[104:105], v[80:81] op_sel_hi:[1,0]
	v_pk_fma_f32 v[6:7], v[6:7], v[96:97], v[42:43] op_sel:[0,0,0] op_sel_hi:[1,0,1]
	v_pk_mul_f32 v[38:39], v[6:7], v[80:81] op_sel:[0,1] op_sel_hi:[1,1]
	v_pk_mul_f32 v[44:45], v[104:105], v[82:83] op_sel_hi:[1,0]
	v_pk_fma_f32 v[8:9], v[8:9], v[96:97], v[44:45] op_sel:[0,1,0] op_sel_hi:[1,1,1]
	v_pk_fma_f32 v[38:39], v[8:9], v[82:83], v[38:39] op_sel:[0,1,0] op_sel_hi:[1,1,1]
	s_waitcnt lgkmcnt(3)
	v_pk_mul_f32 v[42:43], v[104:105], v[84:85] op_sel_hi:[1,0]
	v_pk_fma_f32 v[10:11], v[10:11], v[98:99], v[42:43] op_sel:[0,0,0] op_sel_hi:[1,0,1]
	v_pk_fma_f32 v[38:39], v[10:11], v[84:85], v[38:39] op_sel:[0,1,0] op_sel_hi:[1,1,1]
	v_pk_mul_f32 v[44:45], v[104:105], v[86:87] op_sel_hi:[1,0]
	v_pk_fma_f32 v[12:13], v[12:13], v[98:99], v[44:45] op_sel:[0,1,0] op_sel_hi:[1,1,1]
	v_pk_fma_f32 v[38:39], v[12:13], v[86:87], v[38:39] op_sel:[0,1,0] op_sel_hi:[1,1,1]
	s_waitcnt lgkmcnt(1)
	v_pk_mul_f32 v[42:43], v[104:105], v[88:89] op_sel_hi:[1,0]
	v_pk_fma_f32 v[14:15], v[14:15], v[100:101], v[42:43] op_sel:[0,0,0] op_sel_hi:[1,0,1]
	v_pk_fma_f32 v[38:39], v[14:15], v[88:89], v[38:39] op_sel:[0,1,0] op_sel_hi:[1,1,1]
	v_pk_mul_f32 v[44:45], v[104:105], v[90:91] op_sel_hi:[1,0]
	v_pk_fma_f32 v[16:17], v[16:17], v[100:101], v[44:45] op_sel:[0,1,0] op_sel_hi:[1,1,1]
	v_pk_fma_f32 v[38:39], v[16:17], v[90:91], v[38:39] op_sel:[0,1,0] op_sel_hi:[1,1,1]
	s_waitcnt lgkmcnt(0)
	v_pk_mul_f32 v[42:43], v[104:105], v[92:93] op_sel_hi:[1,0]
	v_pk_fma_f32 v[18:19], v[18:19], v[102:103], v[42:43] op_sel:[0,0,0] op_sel_hi:[1,0,1]
	v_pk_fma_f32 v[38:39], v[18:19], v[92:93], v[38:39] op_sel:[0,1,0] op_sel_hi:[1,1,1]
	v_pk_mul_f32 v[44:45], v[104:105], v[94:95] op_sel_hi:[1,0]
	v_pk_fma_f32 v[20:21], v[20:21], v[102:103], v[44:45] op_sel:[0,1,0] op_sel_hi:[1,1,1]
	v_pk_fma_f32 v[38:39], v[20:21], v[94:95], v[38:39] op_sel:[0,1,0] op_sel_hi:[1,1,1]
	s_add_u32 s14, s14, 0x1000
	s_addc_u32 s15, s15, 0
	v_add_f32_dpp v38, v38, v38 row_ror:8 row_mask:0xf bank_mask:0x3 bound_ctrl:1
	v_add_f32_dpp v38, v39, v39 row_ror:8 row_mask:0xf bank_mask:0xc bound_ctrl:1
	ds_read_b64 v[72:73], v3 offset:22272
	ds_read_b128 v[48:51], v2 offset:6400
	v_add_f32_dpp v38, v38, v38 row_half_mirror row_mask:0xf bank_mask:0xf bound_ctrl:1
	ds_read_b128 v[64:67], v2 offset:19712
	ds_read_b128 v[52:55], v2 offset:6656
	v_add_f32_dpp v38, v38, v38 quad_perm:[1,0,3,2] row_mask:0xf bank_mask:0xf bound_ctrl:1
	ds_read_b128 v[56:59], v2 offset:6912
	ds_read_b128 v[68:71], v2 offset:19968
	v_add_f32_dpp v38, v38, v38 quad_perm:[2,3,0,1] row_mask:0xf bank_mask:0xf bound_ctrl:1
	ds_read_b128 v[60:63], v2 offset:7168
	v_cvt_pk_bf16_f32 v47, v38, v38
	s_mov_b64 exec, s[2:3]
	global_store_short v28, v47, s[14:15] offset:-4096
	s_mov_b64 exec, -1
	s_waitcnt lgkmcnt(4)
	v_pk_mul_f32 v[42:43], v[72:73], v[48:49] op_sel_hi:[1,0]
	v_pk_fma_f32 v[6:7], v[6:7], v[64:65], v[42:43] op_sel:[0,0,0] op_sel_hi:[1,0,1]
	v_pk_mul_f32 v[38:39], v[6:7], v[48:49] op_sel:[0,1] op_sel_hi:[1,1]
	v_pk_mul_f32 v[44:45], v[72:73], v[50:51] op_sel_hi:[1,0]
	v_pk_fma_f32 v[8:9], v[8:9], v[64:65], v[44:45] op_sel:[0,1,0] op_sel_hi:[1,1,1]
	v_pk_fma_f32 v[38:39], v[8:9], v[50:51], v[38:39] op_sel:[0,1,0] op_sel_hi:[1,1,1]
	s_waitcnt lgkmcnt(3)
	v_pk_mul_f32 v[42:43], v[72:73], v[52:53] op_sel_hi:[1,0]
	v_pk_fma_f32 v[10:11], v[10:11], v[66:67], v[42:43] op_sel:[0,0,0] op_sel_hi:[1,0,1]
	v_pk_fma_f32 v[38:39], v[10:11], v[52:53], v[38:39] op_sel:[0,1,0] op_sel_hi:[1,1,1]
	v_pk_mul_f32 v[44:45], v[72:73], v[54:55] op_sel_hi:[1,0]
	v_pk_fma_f32 v[12:13], v[12:13], v[66:67], v[44:45] op_sel:[0,1,0] op_sel_hi:[1,1,1]
	v_pk_fma_f32 v[38:39], v[12:13], v[54:55], v[38:39] op_sel:[0,1,0] op_sel_hi:[1,1,1]
	s_waitcnt lgkmcnt(1)
	v_pk_mul_f32 v[42:43], v[72:73], v[56:57] op_sel_hi:[1,0]
	v_pk_fma_f32 v[14:15], v[14:15], v[68:69], v[42:43] op_sel:[0,0,0] op_sel_hi:[1,0,1]
	v_pk_fma_f32 v[38:39], v[14:15], v[56:57], v[38:39] op_sel:[0,1,0] op_sel_hi:[1,1,1]
	v_pk_mul_f32 v[44:45], v[72:73], v[58:59] op_sel_hi:[1,0]
	v_pk_fma_f32 v[16:17], v[16:17], v[68:69], v[44:45] op_sel:[0,1,0] op_sel_hi:[1,1,1]
	v_pk_fma_f32 v[38:39], v[16:17], v[58:59], v[38:39] op_sel:[0,1,0] op_sel_hi:[1,1,1]
	s_waitcnt lgkmcnt(0)
	v_pk_mul_f32 v[42:43], v[72:73], v[60:61] op_sel_hi:[1,0]
	v_pk_fma_f32 v[18:19], v[18:19], v[70:71], v[42:43] op_sel:[0,0,0] op_sel_hi:[1,0,1]
	v_pk_fma_f32 v[38:39], v[18:19], v[60:61], v[38:39] op_sel:[0,1,0] op_sel_hi:[1,1,1]
	v_pk_mul_f32 v[44:45], v[72:73], v[62:63] op_sel_hi:[1,0]
	v_pk_fma_f32 v[20:21], v[20:21], v[70:71], v[44:45] op_sel:[0,1,0] op_sel_hi:[1,1,1]
	v_pk_fma_f32 v[38:39], v[20:21], v[62:63], v[38:39] op_sel:[0,1,0] op_sel_hi:[1,1,1]
	s_add_u32 s14, s14, 0x1000
	s_addc_u32 s15, s15, 0
	v_add_f32_dpp v38, v38, v38 row_ror:8 row_mask:0xf bank_mask:0x3 bound_ctrl:1
	v_add_f32_dpp v38, v39, v39 row_ror:8 row_mask:0xf bank_mask:0xc bound_ctrl:1
	ds_read_b64 v[104:105], v3 offset:22528
	ds_read_b128 v[80:83], v2 offset:7424
	v_add_f32_dpp v38, v38, v38 row_half_mirror row_mask:0xf bank_mask:0xf bound_ctrl:1
	ds_read_b128 v[96:99], v2 offset:20224
	ds_read_b128 v[84:87], v2 offset:7680
	v_add_f32_dpp v38, v38, v38 quad_perm:[1,0,3,2] row_mask:0xf bank_mask:0xf bound_ctrl:1
	ds_read_b128 v[88:91], v2 offset:7936
	ds_read_b128 v[100:103], v2 offset:20480
	v_add_f32_dpp v38, v38, v38 quad_perm:[2,3,0,1] row_mask:0xf bank_mask:0xf bound_ctrl:1
	ds_read_b128 v[92:95], v2 offset:8192
	v_cvt_pk_bf16_f32 v47, v38, v38
	s_mov_b64 exec, s[2:3]
	global_store_short v28, v47, s[14:15] offset:-4096
	s_mov_b64 exec, -1
	s_waitcnt lgkmcnt(4)
	v_pk_mul_f32 v[42:43], v[104:105], v[80:81] op_sel_hi:[1,0]
	v_pk_fma_f32 v[6:7], v[6:7], v[96:97], v[42:43] op_sel:[0,0,0] op_sel_hi:[1,0,1]
	v_pk_mul_f32 v[38:39], v[6:7], v[80:81] op_sel:[0,1] op_sel_hi:[1,1]
	v_pk_mul_f32 v[44:45], v[104:105], v[82:83] op_sel_hi:[1,0]
	v_pk_fma_f32 v[8:9], v[8:9], v[96:97], v[44:45] op_sel:[0,1,0] op_sel_hi:[1,1,1]
	v_pk_fma_f32 v[38:39], v[8:9], v[82:83], v[38:39] op_sel:[0,1,0] op_sel_hi:[1,1,1]
	s_waitcnt lgkmcnt(3)
	v_pk_mul_f32 v[42:43], v[104:105], v[84:85] op_sel_hi:[1,0]
	v_pk_fma_f32 v[10:11], v[10:11], v[98:99], v[42:43] op_sel:[0,0,0] op_sel_hi:[1,0,1]
	v_pk_fma_f32 v[38:39], v[10:11], v[84:85], v[38:39] op_sel:[0,1,0] op_sel_hi:[1,1,1]
	v_pk_mul_f32 v[44:45], v[104:105], v[86:87] op_sel_hi:[1,0]
	v_pk_fma_f32 v[12:13], v[12:13], v[98:99], v[44:45] op_sel:[0,1,0] op_sel_hi:[1,1,1]
	v_pk_fma_f32 v[38:39], v[12:13], v[86:87], v[38:39] op_sel:[0,1,0] op_sel_hi:[1,1,1]
	s_waitcnt lgkmcnt(1)
	v_pk_mul_f32 v[42:43], v[104:105], v[88:89] op_sel_hi:[1,0]
	v_pk_fma_f32 v[14:15], v[14:15], v[100:101], v[42:43] op_sel:[0,0,0] op_sel_hi:[1,0,1]
	v_pk_fma_f32 v[38:39], v[14:15], v[88:89], v[38:39] op_sel:[0,1,0] op_sel_hi:[1,1,1]
	v_pk_mul_f32 v[44:45], v[104:105], v[90:91] op_sel_hi:[1,0]
	v_pk_fma_f32 v[16:17], v[16:17], v[100:101], v[44:45] op_sel:[0,1,0] op_sel_hi:[1,1,1]
	v_pk_fma_f32 v[38:39], v[16:17], v[90:91], v[38:39] op_sel:[0,1,0] op_sel_hi:[1,1,1]
	s_waitcnt lgkmcnt(0)
	v_pk_mul_f32 v[42:43], v[104:105], v[92:93] op_sel_hi:[1,0]
	v_pk_fma_f32 v[18:19], v[18:19], v[102:103], v[42:43] op_sel:[0,0,0] op_sel_hi:[1,0,1]
	v_pk_fma_f32 v[38:39], v[18:19], v[92:93], v[38:39] op_sel:[0,1,0] op_sel_hi:[1,1,1]
	v_pk_mul_f32 v[44:45], v[104:105], v[94:95] op_sel_hi:[1,0]
	v_pk_fma_f32 v[20:21], v[20:21], v[102:103], v[44:45] op_sel:[0,1,0] op_sel_hi:[1,1,1]
	v_pk_fma_f32 v[38:39], v[20:21], v[94:95], v[38:39] op_sel:[0,1,0] op_sel_hi:[1,1,1]
	s_add_u32 s14, s14, 0x1000
	s_addc_u32 s15, s15, 0
	v_add_f32_dpp v38, v38, v38 row_ror:8 row_mask:0xf bank_mask:0x3 bound_ctrl:1
	v_add_f32_dpp v38, v39, v39 row_ror:8 row_mask:0xf bank_mask:0xc bound_ctrl:1
	ds_read_b64 v[72:73], v3 offset:45312
	ds_read_b128 v[48:51], v2 offset:24832
	v_add_f32_dpp v38, v38, v38 row_half_mirror row_mask:0xf bank_mask:0xf bound_ctrl:1
	ds_read_b128 v[64:67], v2 offset:41216
	ds_read_b128 v[52:55], v2 offset:25088
	v_add_f32_dpp v38, v38, v38 quad_perm:[1,0,3,2] row_mask:0xf bank_mask:0xf bound_ctrl:1
	ds_read_b128 v[56:59], v2 offset:25344
	ds_read_b128 v[68:71], v2 offset:41472
	v_add_f32_dpp v38, v38, v38 quad_perm:[2,3,0,1] row_mask:0xf bank_mask:0xf bound_ctrl:1
	ds_read_b128 v[60:63], v2 offset:25600
	v_cvt_pk_bf16_f32 v47, v38, v38
	s_mov_b64 exec, s[2:3]
	global_store_short v28, v47, s[14:15] offset:-4096
	s_mov_b64 exec, -1
	s_waitcnt vmcnt(8)
	v_lshlrev_b32_e32 v144, 16, v110
	v_lshlrev_b32_e32 v145, 16, v111
	v_and_b32_e32 v146, s17, v110
	v_and_b32_e32 v147, s17, v111
	v_lshlrev_b32_e32 v148, 16, v112
	v_lshlrev_b32_e32 v149, 16, v113
	v_and_b32_e32 v150, s17, v112
	v_and_b32_e32 v151, s17, v113
	v_lshlrev_b32_e32 v152, 16, v114
	v_and_b32_e32 v153, s17, v114
	v_rcp_f32_e32 v25, v24
	v_mul_f32_e32 v149, v24, v149
	v_mul_f32_e32 v151, v24, v151
	v_mul_f32_e32 v145, 0x3db504f3, v145
	v_mul_f32_e32 v147, 0x3db504f3, v147
	v_cndmask_b32_e64 v27, 1.0, v25, s[20:21]
	v_mul_f32_e32 v24, v24, v26
	v_mul_f32_e32 v152, v27, v152
	v_mul_f32_e32 v153, v27, v153
	ds_write_b128 v29, v[144:147] offset:49408
	ds_write_b128 v29, v[148:151] offset:57600
	ds_write_b64 v30, v[116:117] offset:49408
	ds_write_b64 v31, v[152:153] offset:49408
	s_add_i32 s16, s16, 8
	s_waitcnt lgkmcnt(0)
	global_load_dword v110, v32, s[10:11]
	global_load_dword v111, v32, s[10:11] offset:-1024
	global_load_dword v112, v33, s[10:11]
	global_load_dword v113, v33, s[10:11] offset:-1024
	global_load_dword v114, v34, s[10:11]
	global_load_dword v116, v35, s[12:13]
	global_load_dword v117, v35, s[12:13] offset:4
	s_add_u32 s10, s10, 0x18000
	s_addc_u32 s11, s11, 0
	s_add_u32 s12, s12, 0x4000
	s_addc_u32 s13, s13, 0
	s_barrier
	s_cmpk_lt_u32 s16, 0x800
	s_cbranch_scc0 .Lgla2_done
	s_waitcnt lgkmcnt(4)
	v_pk_mul_f32 v[42:43], v[72:73], v[48:49] op_sel_hi:[1,0]
	v_pk_fma_f32 v[6:7], v[6:7], v[64:65], v[42:43] op_sel:[0,0,0] op_sel_hi:[1,0,1]
	v_pk_mul_f32 v[38:39], v[6:7], v[48:49] op_sel:[0,1] op_sel_hi:[1,1]
	v_pk_mul_f32 v[44:45], v[72:73], v[50:51] op_sel_hi:[1,0]
	v_pk_fma_f32 v[8:9], v[8:9], v[64:65], v[44:45] op_sel:[0,1,0] op_sel_hi:[1,1,1]
	v_pk_fma_f32 v[38:39], v[8:9], v[50:51], v[38:39] op_sel:[0,1,0] op_sel_hi:[1,1,1]
	s_waitcnt lgkmcnt(3)
	v_pk_mul_f32 v[42:43], v[72:73], v[52:53] op_sel_hi:[1,0]
	v_pk_fma_f32 v[10:11], v[10:11], v[66:67], v[42:43] op_sel:[0,0,0] op_sel_hi:[1,0,1]
	v_pk_fma_f32 v[38:39], v[10:11], v[52:53], v[38:39] op_sel:[0,1,0] op_sel_hi:[1,1,1]
	v_pk_mul_f32 v[44:45], v[72:73], v[54:55] op_sel_hi:[1,0]
	v_pk_fma_f32 v[12:13], v[12:13], v[66:67], v[44:45] op_sel:[0,1,0] op_sel_hi:[1,1,1]
	v_pk_fma_f32 v[38:39], v[12:13], v[54:55], v[38:39] op_sel:[0,1,0] op_sel_hi:[1,1,1]
	s_waitcnt lgkmcnt(1)
	v_pk_mul_f32 v[42:43], v[72:73], v[56:57] op_sel_hi:[1,0]
	v_pk_fma_f32 v[14:15], v[14:15], v[68:69], v[42:43] op_sel:[0,0,0] op_sel_hi:[1,0,1]
	v_pk_fma_f32 v[38:39], v[14:15], v[56:57], v[38:39] op_sel:[0,1,0] op_sel_hi:[1,1,1]
	v_pk_mul_f32 v[44:45], v[72:73], v[58:59] op_sel_hi:[1,0]
	v_pk_fma_f32 v[16:17], v[16:17], v[68:69], v[44:45] op_sel:[0,1,0] op_sel_hi:[1,1,1]
	v_pk_fma_f32 v[38:39], v[16:17], v[58:59], v[38:39] op_sel:[0,1,0] op_sel_hi:[1,1,1]
	s_waitcnt lgkmcnt(0)
	v_pk_mul_f32 v[42:43], v[72:73], v[60:61] op_sel_hi:[1,0]
	v_pk_fma_f32 v[18:19], v[18:19], v[70:71], v[42:43] op_sel:[0,0,0] op_sel_hi:[1,0,1]
	v_pk_fma_f32 v[38:39], v[18:19], v[60:61], v[38:39] op_sel:[0,1,0] op_sel_hi:[1,1,1]
	v_pk_mul_f32 v[44:45], v[72:73], v[62:63] op_sel_hi:[1,0]
	v_pk_fma_f32 v[20:21], v[20:21], v[70:71], v[44:45] op_sel:[0,1,0] op_sel_hi:[1,1,1]
	v_pk_fma_f32 v[38:39], v[20:21], v[62:63], v[38:39] op_sel:[0,1,0] op_sel_hi:[1,1,1]
	s_add_u32 s14, s14, 0x1000
	s_addc_u32 s15, s15, 0
	v_add_f32_dpp v38, v38, v38 row_ror:8 row_mask:0xf bank_mask:0x3 bound_ctrl:1
	v_add_f32_dpp v38, v39, v39 row_ror:8 row_mask:0xf bank_mask:0xc bound_ctrl:1
	ds_read_b64 v[104:105], v3 offset:45568
	ds_read_b128 v[80:83], v2 offset:25856
	v_add_f32_dpp v38, v38, v38 row_half_mirror row_mask:0xf bank_mask:0xf bound_ctrl:1
	ds_read_b128 v[96:99], v2 offset:41728
	ds_read_b128 v[84:87], v2 offset:26112
	v_add_f32_dpp v38, v38, v38 quad_perm:[1,0,3,2] row_mask:0xf bank_mask:0xf bound_ctrl:1
	ds_read_b128 v[88:91], v2 offset:26368
	ds_read_b128 v[100:103], v2 offset:41984
	v_add_f32_dpp v38, v38, v38 quad_perm:[2,3,0,1] row_mask:0xf bank_mask:0xf bound_ctrl:1
	ds_read_b128 v[92:95], v2 offset:26624
	v_cvt_pk_bf16_f32 v47, v38, v38
	s_mov_b64 exec, s[2:3]
	global_store_short v28, v47, s[14:15] offset:-4096
	s_mov_b64 exec, -1
	s_waitcnt lgkmcnt(4)
	v_pk_mul_f32 v[42:43], v[104:105], v[80:81] op_sel_hi:[1,0]
	v_pk_fma_f32 v[6:7], v[6:7], v[96:97], v[42:43] op_sel:[0,0,0] op_sel_hi:[1,0,1]
	v_pk_mul_f32 v[38:39], v[6:7], v[80:81] op_sel:[0,1] op_sel_hi:[1,1]
	v_pk_mul_f32 v[44:45], v[104:105], v[82:83] op_sel_hi:[1,0]
	v_pk_fma_f32 v[8:9], v[8:9], v[96:97], v[44:45] op_sel:[0,1,0] op_sel_hi:[1,1,1]
	v_pk_fma_f32 v[38:39], v[8:9], v[82:83], v[38:39] op_sel:[0,1,0] op_sel_hi:[1,1,1]
	s_waitcnt lgkmcnt(3)
	v_pk_mul_f32 v[42:43], v[104:105], v[84:85] op_sel_hi:[1,0]
	v_pk_fma_f32 v[10:11], v[10:11], v[98:99], v[42:43] op_sel:[0,0,0] op_sel_hi:[1,0,1]
	v_pk_fma_f32 v[38:39], v[10:11], v[84:85], v[38:39] op_sel:[0,1,0] op_sel_hi:[1,1,1]
	v_pk_mul_f32 v[44:45], v[104:105], v[86:87] op_sel_hi:[1,0]
	v_pk_fma_f32 v[12:13], v[12:13], v[98:99], v[44:45] op_sel:[0,1,0] op_sel_hi:[1,1,1]
	v_pk_fma_f32 v[38:39], v[12:13], v[86:87], v[38:39] op_sel:[0,1,0] op_sel_hi:[1,1,1]
	s_waitcnt lgkmcnt(1)
	v_pk_mul_f32 v[42:43], v[104:105], v[88:89] op_sel_hi:[1,0]
	v_pk_fma_f32 v[14:15], v[14:15], v[100:101], v[42:43] op_sel:[0,0,0] op_sel_hi:[1,0,1]
	v_pk_fma_f32 v[38:39], v[14:15], v[88:89], v[38:39] op_sel:[0,1,0] op_sel_hi:[1,1,1]
	v_pk_mul_f32 v[44:45], v[104:105], v[90:91] op_sel_hi:[1,0]
	v_pk_fma_f32 v[16:17], v[16:17], v[100:101], v[44:45] op_sel:[0,1,0] op_sel_hi:[1,1,1]
	v_pk_fma_f32 v[38:39], v[16:17], v[90:91], v[38:39] op_sel:[0,1,0] op_sel_hi:[1,1,1]
	s_waitcnt lgkmcnt(0)
	v_pk_mul_f32 v[42:43], v[104:105], v[92:93] op_sel_hi:[1,0]
	v_pk_fma_f32 v[18:19], v[18:19], v[102:103], v[42:43] op_sel:[0,0,0] op_sel_hi:[1,0,1]
	v_pk_fma_f32 v[38:39], v[18:19], v[92:93], v[38:39] op_sel:[0,1,0] op_sel_hi:[1,1,1]
	v_pk_mul_f32 v[44:45], v[104:105], v[94:95] op_sel_hi:[1,0]
	v_pk_fma_f32 v[20:21], v[20:21], v[102:103], v[44:45] op_sel:[0,1,0] op_sel_hi:[1,1,1]
	v_pk_fma_f32 v[38:39], v[20:21], v[94:95], v[38:39] op_sel:[0,1,0] op_sel_hi:[1,1,1]
	s_add_u32 s14, s14, 0x1000
	s_addc_u32 s15, s15, 0
	v_add_f32_dpp v38, v38, v38 row_ror:8 row_mask:0xf bank_mask:0x3 bound_ctrl:1
	v_add_f32_dpp v38, v39, v39 row_ror:8 row_mask:0xf bank_mask:0xc bound_ctrl:1
	ds_read_b64 v[72:73], v3 offset:45824
	ds_read_b128 v[48:51], v2 offset:26880
	v_add_f32_dpp v38, v38, v38 row_half_mirror row_mask:0xf bank_mask:0xf bound_ctrl:1
	ds_read_b128 v[64:67], v2 offset:42240
	ds_read_b128 v[52:55], v2 offset:27136
	v_add_f32_dpp v38, v38, v38 quad_perm:[1,0,3,2] row_mask:0xf bank_mask:0xf bound_ctrl:1
	ds_read_b128 v[56:59], v2 offset:27392
	ds_read_b128 v[68:71], v2 offset:42496
	v_add_f32_dpp v38, v38, v38 quad_perm:[2,3,0,1] row_mask:0xf bank_mask:0xf bound_ctrl:1
	ds_read_b128 v[60:63], v2 offset:27648
	v_cvt_pk_bf16_f32 v47, v38, v38
	s_mov_b64 exec, s[2:3]
	global_store_short v28, v47, s[14:15] offset:-4096
	s_mov_b64 exec, -1
	s_waitcnt lgkmcnt(4)
	v_pk_mul_f32 v[42:43], v[72:73], v[48:49] op_sel_hi:[1,0]
	v_pk_fma_f32 v[6:7], v[6:7], v[64:65], v[42:43] op_sel:[0,0,0] op_sel_hi:[1,0,1]
	v_pk_mul_f32 v[38:39], v[6:7], v[48:49] op_sel:[0,1] op_sel_hi:[1,1]
	v_pk_mul_f32 v[44:45], v[72:73], v[50:51] op_sel_hi:[1,0]
	v_pk_fma_f32 v[8:9], v[8:9], v[64:65], v[44:45] op_sel:[0,1,0] op_sel_hi:[1,1,1]
	v_pk_fma_f32 v[38:39], v[8:9], v[50:51], v[38:39] op_sel:[0,1,0] op_sel_hi:[1,1,1]
	s_waitcnt lgkmcnt(3)
	v_pk_mul_f32 v[42:43], v[72:73], v[52:53] op_sel_hi:[1,0]
	v_pk_fma_f32 v[10:11], v[10:11], v[66:67], v[42:43] op_sel:[0,0,0] op_sel_hi:[1,0,1]
	v_pk_fma_f32 v[38:39], v[10:11], v[52:53], v[38:39] op_sel:[0,1,0] op_sel_hi:[1,1,1]
	v_pk_mul_f32 v[44:45], v[72:73], v[54:55] op_sel_hi:[1,0]
	v_pk_fma_f32 v[12:13], v[12:13], v[66:67], v[44:45] op_sel:[0,1,0] op_sel_hi:[1,1,1]
	v_pk_fma_f32 v[38:39], v[12:13], v[54:55], v[38:39] op_sel:[0,1,0] op_sel_hi:[1,1,1]
	s_waitcnt lgkmcnt(1)
	v_pk_mul_f32 v[42:43], v[72:73], v[56:57] op_sel_hi:[1,0]
	v_pk_fma_f32 v[14:15], v[14:15], v[68:69], v[42:43] op_sel:[0,0,0] op_sel_hi:[1,0,1]
	v_pk_fma_f32 v[38:39], v[14:15], v[56:57], v[38:39] op_sel:[0,1,0] op_sel_hi:[1,1,1]
	v_pk_mul_f32 v[44:45], v[72:73], v[58:59] op_sel_hi:[1,0]
	v_pk_fma_f32 v[16:17], v[16:17], v[68:69], v[44:45] op_sel:[0,1,0] op_sel_hi:[1,1,1]
	v_pk_fma_f32 v[38:39], v[16:17], v[58:59], v[38:39] op_sel:[0,1,0] op_sel_hi:[1,1,1]
	s_waitcnt lgkmcnt(0)
	v_pk_mul_f32 v[42:43], v[72:73], v[60:61] op_sel_hi:[1,0]
	v_pk_fma_f32 v[18:19], v[18:19], v[70:71], v[42:43] op_sel:[0,0,0] op_sel_hi:[1,0,1]
	v_pk_fma_f32 v[38:39], v[18:19], v[60:61], v[38:39] op_sel:[0,1,0] op_sel_hi:[1,1,1]
	v_pk_mul_f32 v[44:45], v[72:73], v[62:63] op_sel_hi:[1,0]
	v_pk_fma_f32 v[20:21], v[20:21], v[70:71], v[44:45] op_sel:[0,1,0] op_sel_hi:[1,1,1]
	v_pk_fma_f32 v[38:39], v[20:21], v[62:63], v[38:39] op_sel:[0,1,0] op_sel_hi:[1,1,1]
	s_add_u32 s14, s14, 0x1000
	s_addc_u32 s15, s15, 0
	v_add_f32_dpp v38, v38, v38 row_ror:8 row_mask:0xf bank_mask:0x3 bound_ctrl:1
	v_add_f32_dpp v38, v39, v39 row_ror:8 row_mask:0xf bank_mask:0xc bound_ctrl:1
	ds_read_b64 v[104:105], v3 offset:46080
	ds_read_b128 v[80:83], v2 offset:27904
	v_add_f32_dpp v38, v38, v38 row_half_mirror row_mask:0xf bank_mask:0xf bound_ctrl:1
	ds_read_b128 v[96:99], v2 offset:42752
	ds_read_b128 v[84:87], v2 offset:28160
	v_add_f32_dpp v38, v38, v38 quad_perm:[1,0,3,2] row_mask:0xf bank_mask:0xf bound_ctrl:1
	ds_read_b128 v[88:91], v2 offset:28416
	ds_read_b128 v[100:103], v2 offset:43008
	v_add_f32_dpp v38, v38, v38 quad_perm:[2,3,0,1] row_mask:0xf bank_mask:0xf bound_ctrl:1
	ds_read_b128 v[92:95], v2 offset:28672
	v_cvt_pk_bf16_f32 v47, v38, v38
	s_mov_b64 exec, s[2:3]
	global_store_short v28, v47, s[14:15] offset:-4096
	s_mov_b64 exec, -1
	s_waitcnt lgkmcnt(4)
	v_pk_mul_f32 v[42:43], v[104:105], v[80:81] op_sel_hi:[1,0]
	v_pk_fma_f32 v[6:7], v[6:7], v[96:97], v[42:43] op_sel:[0,0,0] op_sel_hi:[1,0,1]
	v_pk_mul_f32 v[38:39], v[6:7], v[80:81] op_sel:[0,1] op_sel_hi:[1,1]
	v_pk_mul_f32 v[44:45], v[104:105], v[82:83] op_sel_hi:[1,0]
	v_pk_fma_f32 v[8:9], v[8:9], v[96:97], v[44:45] op_sel:[0,1,0] op_sel_hi:[1,1,1]
	v_pk_fma_f32 v[38:39], v[8:9], v[82:83], v[38:39] op_sel:[0,1,0] op_sel_hi:[1,1,1]
	s_waitcnt lgkmcnt(3)
	v_pk_mul_f32 v[42:43], v[104:105], v[84:85] op_sel_hi:[1,0]
	v_pk_fma_f32 v[10:11], v[10:11], v[98:99], v[42:43] op_sel:[0,0,0] op_sel_hi:[1,0,1]
	v_pk_fma_f32 v[38:39], v[10:11], v[84:85], v[38:39] op_sel:[0,1,0] op_sel_hi:[1,1,1]
	v_pk_mul_f32 v[44:45], v[104:105], v[86:87] op_sel_hi:[1,0]
	v_pk_fma_f32 v[12:13], v[12:13], v[98:99], v[44:45] op_sel:[0,1,0] op_sel_hi:[1,1,1]
	v_pk_fma_f32 v[38:39], v[12:13], v[86:87], v[38:39] op_sel:[0,1,0] op_sel_hi:[1,1,1]
	s_waitcnt lgkmcnt(1)
	v_pk_mul_f32 v[42:43], v[104:105], v[88:89] op_sel_hi:[1,0]
	v_pk_fma_f32 v[14:15], v[14:15], v[100:101], v[42:43] op_sel:[0,0,0] op_sel_hi:[1,0,1]
	v_pk_fma_f32 v[38:39], v[14:15], v[88:89], v[38:39] op_sel:[0,1,0] op_sel_hi:[1,1,1]
	v_pk_mul_f32 v[44:45], v[104:105], v[90:91] op_sel_hi:[1,0]
	v_pk_fma_f32 v[16:17], v[16:17], v[100:101], v[44:45] op_sel:[0,1,0] op_sel_hi:[1,1,1]
	v_pk_fma_f32 v[38:39], v[16:17], v[90:91], v[38:39] op_sel:[0,1,0] op_sel_hi:[1,1,1]
	s_waitcnt lgkmcnt(0)
	v_pk_mul_f32 v[42:43], v[104:105], v[92:93] op_sel_hi:[1,0]
	v_pk_fma_f32 v[18:19], v[18:19], v[102:103], v[42:43] op_sel:[0,0,0] op_sel_hi:[1,0,1]
	v_pk_fma_f32 v[38:39], v[18:19], v[92:93], v[38:39] op_sel:[0,1,0] op_sel_hi:[1,1,1]
	v_pk_mul_f32 v[44:45], v[104:105], v[94:95] op_sel_hi:[1,0]
	v_pk_fma_f32 v[20:21], v[20:21], v[102:103], v[44:45] op_sel:[0,1,0] op_sel_hi:[1,1,1]
	v_pk_fma_f32 v[38:39], v[20:21], v[94:95], v[38:39] op_sel:[0,1,0] op_sel_hi:[1,1,1]
	s_add_u32 s14, s14, 0x1000
	s_addc_u32 s15, s15, 0
	v_add_f32_dpp v38, v38, v38 row_ror:8 row_mask:0xf bank_mask:0x3 bound_ctrl:1
	v_add_f32_dpp v38, v39, v39 row_ror:8 row_mask:0xf bank_mask:0xc bound_ctrl:1
	ds_read_b64 v[72:73], v3 offset:46336
	ds_read_b128 v[48:51], v2 offset:28928
	v_add_f32_dpp v38, v38, v38 row_half_mirror row_mask:0xf bank_mask:0xf bound_ctrl:1
	ds_read_b128 v[64:67], v2 offset:43264
	ds_read_b128 v[52:55], v2 offset:29184
	v_add_f32_dpp v38, v38, v38 quad_perm:[1,0,3,2] row_mask:0xf bank_mask:0xf bound_ctrl:1
	ds_read_b128 v[56:59], v2 offset:29440
	ds_read_b128 v[68:71], v2 offset:43520
	v_add_f32_dpp v38, v38, v38 quad_perm:[2,3,0,1] row_mask:0xf bank_mask:0xf bound_ctrl:1
	ds_read_b128 v[60:63], v2 offset:29696
	v_cvt_pk_bf16_f32 v47, v38, v38
	s_mov_b64 exec, s[2:3]
	global_store_short v28, v47, s[14:15] offset:-4096
	s_mov_b64 exec, -1
	s_waitcnt lgkmcnt(4)
	v_pk_mul_f32 v[42:43], v[72:73], v[48:49] op_sel_hi:[1,0]
	v_pk_fma_f32 v[6:7], v[6:7], v[64:65], v[42:43] op_sel:[0,0,0] op_sel_hi:[1,0,1]
	v_pk_mul_f32 v[38:39], v[6:7], v[48:49] op_sel:[0,1] op_sel_hi:[1,1]
	v_pk_mul_f32 v[44:45], v[72:73], v[50:51] op_sel_hi:[1,0]
	v_pk_fma_f32 v[8:9], v[8:9], v[64:65], v[44:45] op_sel:[0,1,0] op_sel_hi:[1,1,1]
	v_pk_fma_f32 v[38:39], v[8:9], v[50:51], v[38:39] op_sel:[0,1,0] op_sel_hi:[1,1,1]
	s_waitcnt lgkmcnt(3)
	v_pk_mul_f32 v[42:43], v[72:73], v[52:53] op_sel_hi:[1,0]
	v_pk_fma_f32 v[10:11], v[10:11], v[66:67], v[42:43] op_sel:[0,0,0] op_sel_hi:[1,0,1]
	v_pk_fma_f32 v[38:39], v[10:11], v[52:53], v[38:39] op_sel:[0,1,0] op_sel_hi:[1,1,1]
	v_pk_mul_f32 v[44:45], v[72:73], v[54:55] op_sel_hi:[1,0]
	v_pk_fma_f32 v[12:13], v[12:13], v[66:67], v[44:45] op_sel:[0,1,0] op_sel_hi:[1,1,1]
	v_pk_fma_f32 v[38:39], v[12:13], v[54:55], v[38:39] op_sel:[0,1,0] op_sel_hi:[1,1,1]
	s_waitcnt lgkmcnt(1)
	v_pk_mul_f32 v[42:43], v[72:73], v[56:57] op_sel_hi:[1,0]
	v_pk_fma_f32 v[14:15], v[14:15], v[68:69], v[42:43] op_sel:[0,0,0] op_sel_hi:[1,0,1]
	v_pk_fma_f32 v[38:39], v[14:15], v[56:57], v[38:39] op_sel:[0,1,0] op_sel_hi:[1,1,1]
	v_pk_mul_f32 v[44:45], v[72:73], v[58:59] op_sel_hi:[1,0]
	v_pk_fma_f32 v[16:17], v[16:17], v[68:69], v[44:45] op_sel:[0,1,0] op_sel_hi:[1,1,1]
	v_pk_fma_f32 v[38:39], v[16:17], v[58:59], v[38:39] op_sel:[0,1,0] op_sel_hi:[1,1,1]
	s_waitcnt lgkmcnt(0)
	v_pk_mul_f32 v[42:43], v[72:73], v[60:61] op_sel_hi:[1,0]
	v_pk_fma_f32 v[18:19], v[18:19], v[70:71], v[42:43] op_sel:[0,0,0] op_sel_hi:[1,0,1]
	v_pk_fma_f32 v[38:39], v[18:19], v[60:61], v[38:39] op_sel:[0,1,0] op_sel_hi:[1,1,1]
	v_pk_mul_f32 v[44:45], v[72:73], v[62:63] op_sel_hi:[1,0]
	v_pk_fma_f32 v[20:21], v[20:21], v[70:71], v[44:45] op_sel:[0,1,0] op_sel_hi:[1,1,1]
	v_pk_fma_f32 v[38:39], v[20:21], v[62:63], v[38:39] op_sel:[0,1,0] op_sel_hi:[1,1,1]
	s_add_u32 s14, s14, 0x1000
	s_addc_u32 s15, s15, 0
	v_add_f32_dpp v38, v38, v38 row_ror:8 row_mask:0xf bank_mask:0x3 bound_ctrl:1
	v_add_f32_dpp v38, v39, v39 row_ror:8 row_mask:0xf bank_mask:0xc bound_ctrl:1
	ds_read_b64 v[104:105], v3 offset:46592
	ds_read_b128 v[80:83], v2 offset:29952
	v_add_f32_dpp v38, v38, v38 row_half_mirror row_mask:0xf bank_mask:0xf bound_ctrl:1
	ds_read_b128 v[96:99], v2 offset:43776
	ds_read_b128 v[84:87], v2 offset:30208
	v_add_f32_dpp v38, v38, v38 quad_perm:[1,0,3,2] row_mask:0xf bank_mask:0xf bound_ctrl:1
	ds_read_b128 v[88:91], v2 offset:30464
	ds_read_b128 v[100:103], v2 offset:44032
	v_add_f32_dpp v38, v38, v38 quad_perm:[2,3,0,1] row_mask:0xf bank_mask:0xf bound_ctrl:1
	ds_read_b128 v[92:95], v2 offset:30720
	v_cvt_pk_bf16_f32 v47, v38, v38
	s_mov_b64 exec, s[2:3]
	global_store_short v28, v47, s[14:15] offset:-4096
	s_mov_b64 exec, -1
	s_waitcnt lgkmcnt(4)
	v_pk_mul_f32 v[42:43], v[104:105], v[80:81] op_sel_hi:[1,0]
	v_pk_fma_f32 v[6:7], v[6:7], v[96:97], v[42:43] op_sel:[0,0,0] op_sel_hi:[1,0,1]
	v_pk_mul_f32 v[38:39], v[6:7], v[80:81] op_sel:[0,1] op_sel_hi:[1,1]
	v_pk_mul_f32 v[44:45], v[104:105], v[82:83] op_sel_hi:[1,0]
	v_pk_fma_f32 v[8:9], v[8:9], v[96:97], v[44:45] op_sel:[0,1,0] op_sel_hi:[1,1,1]
	v_pk_fma_f32 v[38:39], v[8:9], v[82:83], v[38:39] op_sel:[0,1,0] op_sel_hi:[1,1,1]
	s_waitcnt lgkmcnt(3)
	v_pk_mul_f32 v[42:43], v[104:105], v[84:85] op_sel_hi:[1,0]
	v_pk_fma_f32 v[10:11], v[10:11], v[98:99], v[42:43] op_sel:[0,0,0] op_sel_hi:[1,0,1]
	v_pk_fma_f32 v[38:39], v[10:11], v[84:85], v[38:39] op_sel:[0,1,0] op_sel_hi:[1,1,1]
	v_pk_mul_f32 v[44:45], v[104:105], v[86:87] op_sel_hi:[1,0]
	v_pk_fma_f32 v[12:13], v[12:13], v[98:99], v[44:45] op_sel:[0,1,0] op_sel_hi:[1,1,1]
	v_pk_fma_f32 v[38:39], v[12:13], v[86:87], v[38:39] op_sel:[0,1,0] op_sel_hi:[1,1,1]
	s_waitcnt lgkmcnt(1)
	v_pk_mul_f32 v[42:43], v[104:105], v[88:89] op_sel_hi:[1,0]
	v_pk_fma_f32 v[14:15], v[14:15], v[100:101], v[42:43] op_sel:[0,0,0] op_sel_hi:[1,0,1]
	v_pk_fma_f32 v[38:39], v[14:15], v[88:89], v[38:39] op_sel:[0,1,0] op_sel_hi:[1,1,1]
	v_pk_mul_f32 v[44:45], v[104:105], v[90:91] op_sel_hi:[1,0]
	v_pk_fma_f32 v[16:17], v[16:17], v[100:101], v[44:45] op_sel:[0,1,0] op_sel_hi:[1,1,1]
	v_pk_fma_f32 v[38:39], v[16:17], v[90:91], v[38:39] op_sel:[0,1,0] op_sel_hi:[1,1,1]
	s_waitcnt lgkmcnt(0)
	v_pk_mul_f32 v[42:43], v[104:105], v[92:93] op_sel_hi:[1,0]
	v_pk_fma_f32 v[18:19], v[18:19], v[102:103], v[42:43] op_sel:[0,0,0] op_sel_hi:[1,0,1]
	v_pk_fma_f32 v[38:39], v[18:19], v[92:93], v[38:39] op_sel:[0,1,0] op_sel_hi:[1,1,1]
	v_pk_mul_f32 v[44:45], v[104:105], v[94:95] op_sel_hi:[1,0]
	v_pk_fma_f32 v[20:21], v[20:21], v[102:103], v[44:45] op_sel:[0,1,0] op_sel_hi:[1,1,1]
	v_pk_fma_f32 v[38:39], v[20:21], v[94:95], v[38:39] op_sel:[0,1,0] op_sel_hi:[1,1,1]
	s_add_u32 s14, s14, 0x1000
	s_addc_u32 s15, s15, 0
	v_add_f32_dpp v38, v38, v38 row_ror:8 row_mask:0xf bank_mask:0x3 bound_ctrl:1
	v_add_f32_dpp v38, v39, v39 row_ror:8 row_mask:0xf bank_mask:0xc bound_ctrl:1
	ds_read_b64 v[72:73], v3 offset:46848
	ds_read_b128 v[48:51], v2 offset:30976
	v_add_f32_dpp v38, v38, v38 row_half_mirror row_mask:0xf bank_mask:0xf bound_ctrl:1
	ds_read_b128 v[64:67], v2 offset:44288
	ds_read_b128 v[52:55], v2 offset:31232
	v_add_f32_dpp v38, v38, v38 quad_perm:[1,0,3,2] row_mask:0xf bank_mask:0xf bound_ctrl:1
	ds_read_b128 v[56:59], v2 offset:31488
	ds_read_b128 v[68:71], v2 offset:44544
	v_add_f32_dpp v38, v38, v38 quad_perm:[2,3,0,1] row_mask:0xf bank_mask:0xf bound_ctrl:1
	ds_read_b128 v[60:63], v2 offset:31744
	v_cvt_pk_bf16_f32 v47, v38, v38
	s_mov_b64 exec, s[2:3]
	global_store_short v28, v47, s[14:15] offset:-4096
	s_mov_b64 exec, -1
	s_waitcnt lgkmcnt(4)
	v_pk_mul_f32 v[42:43], v[72:73], v[48:49] op_sel_hi:[1,0]
	v_pk_fma_f32 v[6:7], v[6:7], v[64:65], v[42:43] op_sel:[0,0,0] op_sel_hi:[1,0,1]
	v_pk_mul_f32 v[38:39], v[6:7], v[48:49] op_sel:[0,1] op_sel_hi:[1,1]
	v_pk_mul_f32 v[44:45], v[72:73], v[50:51] op_sel_hi:[1,0]
	v_pk_fma_f32 v[8:9], v[8:9], v[64:65], v[44:45] op_sel:[0,1,0] op_sel_hi:[1,1,1]
	v_pk_fma_f32 v[38:39], v[8:9], v[50:51], v[38:39] op_sel:[0,1,0] op_sel_hi:[1,1,1]
	s_waitcnt lgkmcnt(3)
	v_pk_mul_f32 v[42:43], v[72:73], v[52:53] op_sel_hi:[1,0]
	v_pk_fma_f32 v[10:11], v[10:11], v[66:67], v[42:43] op_sel:[0,0,0] op_sel_hi:[1,0,1]
	v_pk_fma_f32 v[38:39], v[10:11], v[52:53], v[38:39] op_sel:[0,1,0] op_sel_hi:[1,1,1]
	v_pk_mul_f32 v[44:45], v[72:73], v[54:55] op_sel_hi:[1,0]
	v_pk_fma_f32 v[12:13], v[12:13], v[66:67], v[44:45] op_sel:[0,1,0] op_sel_hi:[1,1,1]
	v_pk_fma_f32 v[38:39], v[12:13], v[54:55], v[38:39] op_sel:[0,1,0] op_sel_hi:[1,1,1]
	s_waitcnt lgkmcnt(1)
	v_pk_mul_f32 v[42:43], v[72:73], v[56:57] op_sel_hi:[1,0]
	v_pk_fma_f32 v[14:15], v[14:15], v[68:69], v[42:43] op_sel:[0,0,0] op_sel_hi:[1,0,1]
	v_pk_fma_f32 v[38:39], v[14:15], v[56:57], v[38:39] op_sel:[0,1,0] op_sel_hi:[1,1,1]
	v_pk_mul_f32 v[44:45], v[72:73], v[58:59] op_sel_hi:[1,0]
	v_pk_fma_f32 v[16:17], v[16:17], v[68:69], v[44:45] op_sel:[0,1,0] op_sel_hi:[1,1,1]
	v_pk_fma_f32 v[38:39], v[16:17], v[58:59], v[38:39] op_sel:[0,1,0] op_sel_hi:[1,1,1]
	s_waitcnt lgkmcnt(0)
	v_pk_mul_f32 v[42:43], v[72:73], v[60:61] op_sel_hi:[1,0]
	v_pk_fma_f32 v[18:19], v[18:19], v[70:71], v[42:43] op_sel:[0,0,0] op_sel_hi:[1,0,1]
	v_pk_fma_f32 v[38:39], v[18:19], v[60:61], v[38:39] op_sel:[0,1,0] op_sel_hi:[1,1,1]
	v_pk_mul_f32 v[44:45], v[72:73], v[62:63] op_sel_hi:[1,0]
	v_pk_fma_f32 v[20:21], v[20:21], v[70:71], v[44:45] op_sel:[0,1,0] op_sel_hi:[1,1,1]
	v_pk_fma_f32 v[38:39], v[20:21], v[62:63], v[38:39] op_sel:[0,1,0] op_sel_hi:[1,1,1]
	s_add_u32 s14, s14, 0x1000
	s_addc_u32 s15, s15, 0
	v_add_f32_dpp v38, v38, v38 row_ror:8 row_mask:0xf bank_mask:0x3 bound_ctrl:1
	v_add_f32_dpp v38, v39, v39 row_ror:8 row_mask:0xf bank_mask:0xc bound_ctrl:1
	ds_read_b64 v[104:105], v3 offset:47104
	ds_read_b128 v[80:83], v2 offset:32000
	v_add_f32_dpp v38, v38, v38 row_half_mirror row_mask:0xf bank_mask:0xf bound_ctrl:1
	ds_read_b128 v[96:99], v2 offset:44800
	ds_read_b128 v[84:87], v2 offset:32256
	v_add_f32_dpp v38, v38, v38 quad_perm:[1,0,3,2] row_mask:0xf bank_mask:0xf bound_ctrl:1
	ds_read_b128 v[88:91], v2 offset:32512
	ds_read_b128 v[100:103], v2 offset:45056
	v_add_f32_dpp v38, v38, v38 quad_perm:[2,3,0,1] row_mask:0xf bank_mask:0xf bound_ctrl:1
	ds_read_b128 v[92:95], v2 offset:32768
	v_cvt_pk_bf16_f32 v47, v38, v38
	s_mov_b64 exec, s[2:3]
	global_store_short v28, v47, s[14:15] offset:-4096
	s_mov_b64 exec, -1
	s_waitcnt lgkmcnt(4)
	v_pk_mul_f32 v[42:43], v[104:105], v[80:81] op_sel_hi:[1,0]
	v_pk_fma_f32 v[6:7], v[6:7], v[96:97], v[42:43] op_sel:[0,0,0] op_sel_hi:[1,0,1]
	v_pk_mul_f32 v[38:39], v[6:7], v[80:81] op_sel:[0,1] op_sel_hi:[1,1]
	v_pk_mul_f32 v[44:45], v[104:105], v[82:83] op_sel_hi:[1,0]
	v_pk_fma_f32 v[8:9], v[8:9], v[96:97], v[44:45] op_sel:[0,1,0] op_sel_hi:[1,1,1]
	v_pk_fma_f32 v[38:39], v[8:9], v[82:83], v[38:39] op_sel:[0,1,0] op_sel_hi:[1,1,1]
	s_waitcnt lgkmcnt(3)
	v_pk_mul_f32 v[42:43], v[104:105], v[84:85] op_sel_hi:[1,0]
	v_pk_fma_f32 v[10:11], v[10:11], v[98:99], v[42:43] op_sel:[0,0,0] op_sel_hi:[1,0,1]
	v_pk_fma_f32 v[38:39], v[10:11], v[84:85], v[38:39] op_sel:[0,1,0] op_sel_hi:[1,1,1]
	v_pk_mul_f32 v[44:45], v[104:105], v[86:87] op_sel_hi:[1,0]
	v_pk_fma_f32 v[12:13], v[12:13], v[98:99], v[44:45] op_sel:[0,1,0] op_sel_hi:[1,1,1]
	v_pk_fma_f32 v[38:39], v[12:13], v[86:87], v[38:39] op_sel:[0,1,0] op_sel_hi:[1,1,1]
	s_waitcnt lgkmcnt(1)
	v_pk_mul_f32 v[42:43], v[104:105], v[88:89] op_sel_hi:[1,0]
	v_pk_fma_f32 v[14:15], v[14:15], v[100:101], v[42:43] op_sel:[0,0,0] op_sel_hi:[1,0,1]
	v_pk_fma_f32 v[38:39], v[14:15], v[88:89], v[38:39] op_sel:[0,1,0] op_sel_hi:[1,1,1]
	v_pk_mul_f32 v[44:45], v[104:105], v[90:91] op_sel_hi:[1,0]
	v_pk_fma_f32 v[16:17], v[16:17], v[100:101], v[44:45] op_sel:[0,1,0] op_sel_hi:[1,1,1]
	v_pk_fma_f32 v[38:39], v[16:17], v[90:91], v[38:39] op_sel:[0,1,0] op_sel_hi:[1,1,1]
	s_waitcnt lgkmcnt(0)
	v_pk_mul_f32 v[42:43], v[104:105], v[92:93] op_sel_hi:[1,0]
	v_pk_fma_f32 v[18:19], v[18:19], v[102:103], v[42:43] op_sel:[0,0,0] op_sel_hi:[1,0,1]
	v_pk_fma_f32 v[38:39], v[18:19], v[92:93], v[38:39] op_sel:[0,1,0] op_sel_hi:[1,1,1]
	v_pk_mul_f32 v[44:45], v[104:105], v[94:95] op_sel_hi:[1,0]
	v_pk_fma_f32 v[20:21], v[20:21], v[102:103], v[44:45] op_sel:[0,1,0] op_sel_hi:[1,1,1]
	v_pk_fma_f32 v[38:39], v[20:21], v[94:95], v[38:39] op_sel:[0,1,0] op_sel_hi:[1,1,1]
	s_add_u32 s14, s14, 0x1000
	s_addc_u32 s15, s15, 0
	v_add_f32_dpp v38, v38, v38 row_ror:8 row_mask:0xf bank_mask:0x3 bound_ctrl:1
	v_add_f32_dpp v38, v39, v39 row_ror:8 row_mask:0xf bank_mask:0xc bound_ctrl:1
	ds_read_b64 v[72:73], v23 offset:37120
	ds_read_b128 v[48:51], v2 offset:49408
	v_add_f32_dpp v38, v38, v38 row_half_mirror row_mask:0xf bank_mask:0xf bound_ctrl:1
	ds_read_b128 v[64:67], v22 offset:33024
	ds_read_b128 v[52:55], v2 offset:49664
	v_add_f32_dpp v38, v38, v38 quad_perm:[1,0,3,2] row_mask:0xf bank_mask:0xf bound_ctrl:1
	ds_read_b128 v[56:59], v2 offset:49920
	ds_read_b128 v[68:71], v22 offset:33280
	v_add_f32_dpp v38, v38, v38 quad_perm:[2,3,0,1] row_mask:0xf bank_mask:0xf bound_ctrl:1
	ds_read_b128 v[60:63], v2 offset:50176
	v_cvt_pk_bf16_f32 v47, v38, v38
	s_mov_b64 exec, s[2:3]
	global_store_short v28, v47, s[14:15] offset:-4096
	s_mov_b64 exec, -1
	s_waitcnt vmcnt(8)
	v_lshlrev_b32_e32 v144, 16, v110
	v_lshlrev_b32_e32 v145, 16, v111
	v_and_b32_e32 v146, s17, v110
	v_and_b32_e32 v147, s17, v111
	v_lshlrev_b32_e32 v148, 16, v112
	v_lshlrev_b32_e32 v149, 16, v113
	v_and_b32_e32 v150, s17, v112
	v_and_b32_e32 v151, s17, v113
	v_lshlrev_b32_e32 v152, 16, v114
	v_and_b32_e32 v153, s17, v114
	v_rcp_f32_e32 v25, v24
	v_mul_f32_e32 v149, v24, v149
	v_mul_f32_e32 v151, v24, v151
	v_mul_f32_e32 v145, 0x3db504f3, v145
	v_mul_f32_e32 v147, 0x3db504f3, v147
	v_cndmask_b32_e64 v27, 1.0, v25, s[20:21]
	v_mul_f32_e32 v24, v24, v26
	v_mul_f32_e32 v152, v27, v152
	v_mul_f32_e32 v153, v27, v153
	ds_write_b128 v29, v[144:147] offset:256
	ds_write_b128 v29, v[148:151] offset:8448
	ds_write_b64 v30, v[116:117] offset:256
	ds_write_b64 v31, v[152:153] offset:256
	s_add_i32 s16, s16, 8
	s_waitcnt lgkmcnt(0)
	global_load_dword v110, v32, s[10:11]
	global_load_dword v111, v32, s[10:11] offset:-1024
	global_load_dword v112, v33, s[10:11]
	global_load_dword v113, v33, s[10:11] offset:-1024
	global_load_dword v114, v34, s[10:11]
	global_load_dword v116, v35, s[12:13]
	global_load_dword v117, v35, s[12:13] offset:4
	s_add_u32 s10, s10, 0x18000
	s_addc_u32 s11, s11, 0
	s_add_u32 s12, s12, 0x4000
	s_addc_u32 s13, s13, 0
	s_barrier
	s_cmpk_lt_u32 s16, 0x800
	s_cbranch_scc0 .Lgla2_done
	s_waitcnt lgkmcnt(4)
	v_pk_mul_f32 v[42:43], v[72:73], v[48:49] op_sel_hi:[1,0]
	v_pk_fma_f32 v[6:7], v[6:7], v[64:65], v[42:43] op_sel:[0,0,0] op_sel_hi:[1,0,1]
	v_pk_mul_f32 v[38:39], v[6:7], v[48:49] op_sel:[0,1] op_sel_hi:[1,1]
	v_pk_mul_f32 v[44:45], v[72:73], v[50:51] op_sel_hi:[1,0]
	v_pk_fma_f32 v[8:9], v[8:9], v[64:65], v[44:45] op_sel:[0,1,0] op_sel_hi:[1,1,1]
	v_pk_fma_f32 v[38:39], v[8:9], v[50:51], v[38:39] op_sel:[0,1,0] op_sel_hi:[1,1,1]
	s_waitcnt lgkmcnt(3)
	v_pk_mul_f32 v[42:43], v[72:73], v[52:53] op_sel_hi:[1,0]
	v_pk_fma_f32 v[10:11], v[10:11], v[66:67], v[42:43] op_sel:[0,0,0] op_sel_hi:[1,0,1]
	v_pk_fma_f32 v[38:39], v[10:11], v[52:53], v[38:39] op_sel:[0,1,0] op_sel_hi:[1,1,1]
	v_pk_mul_f32 v[44:45], v[72:73], v[54:55] op_sel_hi:[1,0]
	v_pk_fma_f32 v[12:13], v[12:13], v[66:67], v[44:45] op_sel:[0,1,0] op_sel_hi:[1,1,1]
	v_pk_fma_f32 v[38:39], v[12:13], v[54:55], v[38:39] op_sel:[0,1,0] op_sel_hi:[1,1,1]
	s_waitcnt lgkmcnt(1)
	v_pk_mul_f32 v[42:43], v[72:73], v[56:57] op_sel_hi:[1,0]
	v_pk_fma_f32 v[14:15], v[14:15], v[68:69], v[42:43] op_sel:[0,0,0] op_sel_hi:[1,0,1]
	v_pk_fma_f32 v[38:39], v[14:15], v[56:57], v[38:39] op_sel:[0,1,0] op_sel_hi:[1,1,1]
	v_pk_mul_f32 v[44:45], v[72:73], v[58:59] op_sel_hi:[1,0]
	v_pk_fma_f32 v[16:17], v[16:17], v[68:69], v[44:45] op_sel:[0,1,0] op_sel_hi:[1,1,1]
	v_pk_fma_f32 v[38:39], v[16:17], v[58:59], v[38:39] op_sel:[0,1,0] op_sel_hi:[1,1,1]
	s_waitcnt lgkmcnt(0)
	v_pk_mul_f32 v[42:43], v[72:73], v[60:61] op_sel_hi:[1,0]
	v_pk_fma_f32 v[18:19], v[18:19], v[70:71], v[42:43] op_sel:[0,0,0] op_sel_hi:[1,0,1]
	v_pk_fma_f32 v[38:39], v[18:19], v[60:61], v[38:39] op_sel:[0,1,0] op_sel_hi:[1,1,1]
	v_pk_mul_f32 v[44:45], v[72:73], v[62:63] op_sel_hi:[1,0]
	v_pk_fma_f32 v[20:21], v[20:21], v[70:71], v[44:45] op_sel:[0,1,0] op_sel_hi:[1,1,1]
	v_pk_fma_f32 v[38:39], v[20:21], v[62:63], v[38:39] op_sel:[0,1,0] op_sel_hi:[1,1,1]
	s_add_u32 s14, s14, 0x1000
	s_addc_u32 s15, s15, 0
	v_add_f32_dpp v38, v38, v38 row_ror:8 row_mask:0xf bank_mask:0x3 bound_ctrl:1
	v_add_f32_dpp v38, v39, v39 row_ror:8 row_mask:0xf bank_mask:0xc bound_ctrl:1
	ds_read_b64 v[104:105], v23 offset:37376
	ds_read_b128 v[80:83], v2 offset:50432
	v_add_f32_dpp v38, v38, v38 row_half_mirror row_mask:0xf bank_mask:0xf bound_ctrl:1
	ds_read_b128 v[96:99], v22 offset:33536
	ds_read_b128 v[84:87], v2 offset:50688
	v_add_f32_dpp v38, v38, v38 quad_perm:[1,0,3,2] row_mask:0xf bank_mask:0xf bound_ctrl:1
	ds_read_b128 v[88:91], v2 offset:50944
	ds_read_b128 v[100:103], v22 offset:33792
	v_add_f32_dpp v38, v38, v38 quad_perm:[2,3,0,1] row_mask:0xf bank_mask:0xf bound_ctrl:1
	ds_read_b128 v[92:95], v2 offset:51200
	v_cvt_pk_bf16_f32 v47, v38, v38
	s_mov_b64 exec, s[2:3]
	global_store_short v28, v47, s[14:15] offset:-4096
	s_mov_b64 exec, -1
	s_waitcnt lgkmcnt(4)
	v_pk_mul_f32 v[42:43], v[104:105], v[80:81] op_sel_hi:[1,0]
	v_pk_fma_f32 v[6:7], v[6:7], v[96:97], v[42:43] op_sel:[0,0,0] op_sel_hi:[1,0,1]
	v_pk_mul_f32 v[38:39], v[6:7], v[80:81] op_sel:[0,1] op_sel_hi:[1,1]
	v_pk_mul_f32 v[44:45], v[104:105], v[82:83] op_sel_hi:[1,0]
	v_pk_fma_f32 v[8:9], v[8:9], v[96:97], v[44:45] op_sel:[0,1,0] op_sel_hi:[1,1,1]
	v_pk_fma_f32 v[38:39], v[8:9], v[82:83], v[38:39] op_sel:[0,1,0] op_sel_hi:[1,1,1]
	s_waitcnt lgkmcnt(3)
	v_pk_mul_f32 v[42:43], v[104:105], v[84:85] op_sel_hi:[1,0]
	v_pk_fma_f32 v[10:11], v[10:11], v[98:99], v[42:43] op_sel:[0,0,0] op_sel_hi:[1,0,1]
	v_pk_fma_f32 v[38:39], v[10:11], v[84:85], v[38:39] op_sel:[0,1,0] op_sel_hi:[1,1,1]
	v_pk_mul_f32 v[44:45], v[104:105], v[86:87] op_sel_hi:[1,0]
	v_pk_fma_f32 v[12:13], v[12:13], v[98:99], v[44:45] op_sel:[0,1,0] op_sel_hi:[1,1,1]
	v_pk_fma_f32 v[38:39], v[12:13], v[86:87], v[38:39] op_sel:[0,1,0] op_sel_hi:[1,1,1]
	s_waitcnt lgkmcnt(1)
	v_pk_mul_f32 v[42:43], v[104:105], v[88:89] op_sel_hi:[1,0]
	v_pk_fma_f32 v[14:15], v[14:15], v[100:101], v[42:43] op_sel:[0,0,0] op_sel_hi:[1,0,1]
	v_pk_fma_f32 v[38:39], v[14:15], v[88:89], v[38:39] op_sel:[0,1,0] op_sel_hi:[1,1,1]
	v_pk_mul_f32 v[44:45], v[104:105], v[90:91] op_sel_hi:[1,0]
	v_pk_fma_f32 v[16:17], v[16:17], v[100:101], v[44:45] op_sel:[0,1,0] op_sel_hi:[1,1,1]
	v_pk_fma_f32 v[38:39], v[16:17], v[90:91], v[38:39] op_sel:[0,1,0] op_sel_hi:[1,1,1]
	s_waitcnt lgkmcnt(0)
	v_pk_mul_f32 v[42:43], v[104:105], v[92:93] op_sel_hi:[1,0]
	v_pk_fma_f32 v[18:19], v[18:19], v[102:103], v[42:43] op_sel:[0,0,0] op_sel_hi:[1,0,1]
	v_pk_fma_f32 v[38:39], v[18:19], v[92:93], v[38:39] op_sel:[0,1,0] op_sel_hi:[1,1,1]
	v_pk_mul_f32 v[44:45], v[104:105], v[94:95] op_sel_hi:[1,0]
	v_pk_fma_f32 v[20:21], v[20:21], v[102:103], v[44:45] op_sel:[0,1,0] op_sel_hi:[1,1,1]
	v_pk_fma_f32 v[38:39], v[20:21], v[94:95], v[38:39] op_sel:[0,1,0] op_sel_hi:[1,1,1]
	s_add_u32 s14, s14, 0x1000
	s_addc_u32 s15, s15, 0
	v_add_f32_dpp v38, v38, v38 row_ror:8 row_mask:0xf bank_mask:0x3 bound_ctrl:1
	v_add_f32_dpp v38, v39, v39 row_ror:8 row_mask:0xf bank_mask:0xc bound_ctrl:1
	ds_read_b64 v[72:73], v23 offset:37632
	ds_read_b128 v[48:51], v2 offset:51456
	v_add_f32_dpp v38, v38, v38 row_half_mirror row_mask:0xf bank_mask:0xf bound_ctrl:1
	ds_read_b128 v[64:67], v22 offset:34048
	ds_read_b128 v[52:55], v2 offset:51712
	v_add_f32_dpp v38, v38, v38 quad_perm:[1,0,3,2] row_mask:0xf bank_mask:0xf bound_ctrl:1
	ds_read_b128 v[56:59], v2 offset:51968
	ds_read_b128 v[68:71], v22 offset:34304
	v_add_f32_dpp v38, v38, v38 quad_perm:[2,3,0,1] row_mask:0xf bank_mask:0xf bound_ctrl:1
	ds_read_b128 v[60:63], v2 offset:52224
	v_cvt_pk_bf16_f32 v47, v38, v38
	s_mov_b64 exec, s[2:3]
	global_store_short v28, v47, s[14:15] offset:-4096
	s_mov_b64 exec, -1
	s_waitcnt lgkmcnt(4)
	v_pk_mul_f32 v[42:43], v[72:73], v[48:49] op_sel_hi:[1,0]
	v_pk_fma_f32 v[6:7], v[6:7], v[64:65], v[42:43] op_sel:[0,0,0] op_sel_hi:[1,0,1]
	v_pk_mul_f32 v[38:39], v[6:7], v[48:49] op_sel:[0,1] op_sel_hi:[1,1]
	v_pk_mul_f32 v[44:45], v[72:73], v[50:51] op_sel_hi:[1,0]
	v_pk_fma_f32 v[8:9], v[8:9], v[64:65], v[44:45] op_sel:[0,1,0] op_sel_hi:[1,1,1]
	v_pk_fma_f32 v[38:39], v[8:9], v[50:51], v[38:39] op_sel:[0,1,0] op_sel_hi:[1,1,1]
	s_waitcnt lgkmcnt(3)
	v_pk_mul_f32 v[42:43], v[72:73], v[52:53] op_sel_hi:[1,0]
	v_pk_fma_f32 v[10:11], v[10:11], v[66:67], v[42:43] op_sel:[0,0,0] op_sel_hi:[1,0,1]
	v_pk_fma_f32 v[38:39], v[10:11], v[52:53], v[38:39] op_sel:[0,1,0] op_sel_hi:[1,1,1]
	v_pk_mul_f32 v[44:45], v[72:73], v[54:55] op_sel_hi:[1,0]
	v_pk_fma_f32 v[12:13], v[12:13], v[66:67], v[44:45] op_sel:[0,1,0] op_sel_hi:[1,1,1]
	v_pk_fma_f32 v[38:39], v[12:13], v[54:55], v[38:39] op_sel:[0,1,0] op_sel_hi:[1,1,1]
	s_waitcnt lgkmcnt(1)
	v_pk_mul_f32 v[42:43], v[72:73], v[56:57] op_sel_hi:[1,0]
	v_pk_fma_f32 v[14:15], v[14:15], v[68:69], v[42:43] op_sel:[0,0,0] op_sel_hi:[1,0,1]
	v_pk_fma_f32 v[38:39], v[14:15], v[56:57], v[38:39] op_sel:[0,1,0] op_sel_hi:[1,1,1]
	v_pk_mul_f32 v[44:45], v[72:73], v[58:59] op_sel_hi:[1,0]
	v_pk_fma_f32 v[16:17], v[16:17], v[68:69], v[44:45] op_sel:[0,1,0] op_sel_hi:[1,1,1]
	v_pk_fma_f32 v[38:39], v[16:17], v[58:59], v[38:39] op_sel:[0,1,0] op_sel_hi:[1,1,1]
	s_waitcnt lgkmcnt(0)
	v_pk_mul_f32 v[42:43], v[72:73], v[60:61] op_sel_hi:[1,0]
	v_pk_fma_f32 v[18:19], v[18:19], v[70:71], v[42:43] op_sel:[0,0,0] op_sel_hi:[1,0,1]
	v_pk_fma_f32 v[38:39], v[18:19], v[60:61], v[38:39] op_sel:[0,1,0] op_sel_hi:[1,1,1]
	v_pk_mul_f32 v[44:45], v[72:73], v[62:63] op_sel_hi:[1,0]
	v_pk_fma_f32 v[20:21], v[20:21], v[70:71], v[44:45] op_sel:[0,1,0] op_sel_hi:[1,1,1]
	v_pk_fma_f32 v[38:39], v[20:21], v[62:63], v[38:39] op_sel:[0,1,0] op_sel_hi:[1,1,1]
	s_add_u32 s14, s14, 0x1000
	s_addc_u32 s15, s15, 0
	v_add_f32_dpp v38, v38, v38 row_ror:8 row_mask:0xf bank_mask:0x3 bound_ctrl:1
	v_add_f32_dpp v38, v39, v39 row_ror:8 row_mask:0xf bank_mask:0xc bound_ctrl:1
	ds_read_b64 v[104:105], v23 offset:37888
	ds_read_b128 v[80:83], v2 offset:52480
	v_add_f32_dpp v38, v38, v38 row_half_mirror row_mask:0xf bank_mask:0xf bound_ctrl:1
	ds_read_b128 v[96:99], v22 offset:34560
	ds_read_b128 v[84:87], v2 offset:52736
	v_add_f32_dpp v38, v38, v38 quad_perm:[1,0,3,2] row_mask:0xf bank_mask:0xf bound_ctrl:1
	ds_read_b128 v[88:91], v2 offset:52992
	ds_read_b128 v[100:103], v22 offset:34816
	v_add_f32_dpp v38, v38, v38 quad_perm:[2,3,0,1] row_mask:0xf bank_mask:0xf bound_ctrl:1
	ds_read_b128 v[92:95], v2 offset:53248
	v_cvt_pk_bf16_f32 v47, v38, v38
	s_mov_b64 exec, s[2:3]
	global_store_short v28, v47, s[14:15] offset:-4096
	s_mov_b64 exec, -1
	s_waitcnt lgkmcnt(4)
	v_pk_mul_f32 v[42:43], v[104:105], v[80:81] op_sel_hi:[1,0]
	v_pk_fma_f32 v[6:7], v[6:7], v[96:97], v[42:43] op_sel:[0,0,0] op_sel_hi:[1,0,1]
	v_pk_mul_f32 v[38:39], v[6:7], v[80:81] op_sel:[0,1] op_sel_hi:[1,1]
	v_pk_mul_f32 v[44:45], v[104:105], v[82:83] op_sel_hi:[1,0]
	v_pk_fma_f32 v[8:9], v[8:9], v[96:97], v[44:45] op_sel:[0,1,0] op_sel_hi:[1,1,1]
	v_pk_fma_f32 v[38:39], v[8:9], v[82:83], v[38:39] op_sel:[0,1,0] op_sel_hi:[1,1,1]
	s_waitcnt lgkmcnt(3)
	v_pk_mul_f32 v[42:43], v[104:105], v[84:85] op_sel_hi:[1,0]
	v_pk_fma_f32 v[10:11], v[10:11], v[98:99], v[42:43] op_sel:[0,0,0] op_sel_hi:[1,0,1]
	v_pk_fma_f32 v[38:39], v[10:11], v[84:85], v[38:39] op_sel:[0,1,0] op_sel_hi:[1,1,1]
	v_pk_mul_f32 v[44:45], v[104:105], v[86:87] op_sel_hi:[1,0]
	v_pk_fma_f32 v[12:13], v[12:13], v[98:99], v[44:45] op_sel:[0,1,0] op_sel_hi:[1,1,1]
	v_pk_fma_f32 v[38:39], v[12:13], v[86:87], v[38:39] op_sel:[0,1,0] op_sel_hi:[1,1,1]
	s_waitcnt lgkmcnt(1)
	v_pk_mul_f32 v[42:43], v[104:105], v[88:89] op_sel_hi:[1,0]
	v_pk_fma_f32 v[14:15], v[14:15], v[100:101], v[42:43] op_sel:[0,0,0] op_sel_hi:[1,0,1]
	v_pk_fma_f32 v[38:39], v[14:15], v[88:89], v[38:39] op_sel:[0,1,0] op_sel_hi:[1,1,1]
	v_pk_mul_f32 v[44:45], v[104:105], v[90:91] op_sel_hi:[1,0]
	v_pk_fma_f32 v[16:17], v[16:17], v[100:101], v[44:45] op_sel:[0,1,0] op_sel_hi:[1,1,1]
	v_pk_fma_f32 v[38:39], v[16:17], v[90:91], v[38:39] op_sel:[0,1,0] op_sel_hi:[1,1,1]
	s_waitcnt lgkmcnt(0)
	v_pk_mul_f32 v[42:43], v[104:105], v[92:93] op_sel_hi:[1,0]
	v_pk_fma_f32 v[18:19], v[18:19], v[102:103], v[42:43] op_sel:[0,0,0] op_sel_hi:[1,0,1]
	v_pk_fma_f32 v[38:39], v[18:19], v[92:93], v[38:39] op_sel:[0,1,0] op_sel_hi:[1,1,1]
	v_pk_mul_f32 v[44:45], v[104:105], v[94:95] op_sel_hi:[1,0]
	v_pk_fma_f32 v[20:21], v[20:21], v[102:103], v[44:45] op_sel:[0,1,0] op_sel_hi:[1,1,1]
	v_pk_fma_f32 v[38:39], v[20:21], v[94:95], v[38:39] op_sel:[0,1,0] op_sel_hi:[1,1,1]
	s_add_u32 s14, s14, 0x1000
	s_addc_u32 s15, s15, 0
	v_add_f32_dpp v38, v38, v38 row_ror:8 row_mask:0xf bank_mask:0x3 bound_ctrl:1
	v_add_f32_dpp v38, v39, v39 row_ror:8 row_mask:0xf bank_mask:0xc bound_ctrl:1
	ds_read_b64 v[72:73], v23 offset:38144
	ds_read_b128 v[48:51], v2 offset:53504
	v_add_f32_dpp v38, v38, v38 row_half_mirror row_mask:0xf bank_mask:0xf bound_ctrl:1
	ds_read_b128 v[64:67], v22 offset:35072
	ds_read_b128 v[52:55], v2 offset:53760
	v_add_f32_dpp v38, v38, v38 quad_perm:[1,0,3,2] row_mask:0xf bank_mask:0xf bound_ctrl:1
	ds_read_b128 v[56:59], v2 offset:54016
	ds_read_b128 v[68:71], v22 offset:35328
	v_add_f32_dpp v38, v38, v38 quad_perm:[2,3,0,1] row_mask:0xf bank_mask:0xf bound_ctrl:1
	ds_read_b128 v[60:63], v2 offset:54272
	v_cvt_pk_bf16_f32 v47, v38, v38
	s_mov_b64 exec, s[2:3]
	global_store_short v28, v47, s[14:15] offset:-4096
	s_mov_b64 exec, -1
	s_waitcnt lgkmcnt(4)
	v_pk_mul_f32 v[42:43], v[72:73], v[48:49] op_sel_hi:[1,0]
	v_pk_fma_f32 v[6:7], v[6:7], v[64:65], v[42:43] op_sel:[0,0,0] op_sel_hi:[1,0,1]
	v_pk_mul_f32 v[38:39], v[6:7], v[48:49] op_sel:[0,1] op_sel_hi:[1,1]
	v_pk_mul_f32 v[44:45], v[72:73], v[50:51] op_sel_hi:[1,0]
	v_pk_fma_f32 v[8:9], v[8:9], v[64:65], v[44:45] op_sel:[0,1,0] op_sel_hi:[1,1,1]
	v_pk_fma_f32 v[38:39], v[8:9], v[50:51], v[38:39] op_sel:[0,1,0] op_sel_hi:[1,1,1]
	s_waitcnt lgkmcnt(3)
	v_pk_mul_f32 v[42:43], v[72:73], v[52:53] op_sel_hi:[1,0]
	v_pk_fma_f32 v[10:11], v[10:11], v[66:67], v[42:43] op_sel:[0,0,0] op_sel_hi:[1,0,1]
	v_pk_fma_f32 v[38:39], v[10:11], v[52:53], v[38:39] op_sel:[0,1,0] op_sel_hi:[1,1,1]
	v_pk_mul_f32 v[44:45], v[72:73], v[54:55] op_sel_hi:[1,0]
	v_pk_fma_f32 v[12:13], v[12:13], v[66:67], v[44:45] op_sel:[0,1,0] op_sel_hi:[1,1,1]
	v_pk_fma_f32 v[38:39], v[12:13], v[54:55], v[38:39] op_sel:[0,1,0] op_sel_hi:[1,1,1]
	s_waitcnt lgkmcnt(1)
	v_pk_mul_f32 v[42:43], v[72:73], v[56:57] op_sel_hi:[1,0]
	v_pk_fma_f32 v[14:15], v[14:15], v[68:69], v[42:43] op_sel:[0,0,0] op_sel_hi:[1,0,1]
	v_pk_fma_f32 v[38:39], v[14:15], v[56:57], v[38:39] op_sel:[0,1,0] op_sel_hi:[1,1,1]
	v_pk_mul_f32 v[44:45], v[72:73], v[58:59] op_sel_hi:[1,0]
	v_pk_fma_f32 v[16:17], v[16:17], v[68:69], v[44:45] op_sel:[0,1,0] op_sel_hi:[1,1,1]
	v_pk_fma_f32 v[38:39], v[16:17], v[58:59], v[38:39] op_sel:[0,1,0] op_sel_hi:[1,1,1]
	s_waitcnt lgkmcnt(0)
	v_pk_mul_f32 v[42:43], v[72:73], v[60:61] op_sel_hi:[1,0]
	v_pk_fma_f32 v[18:19], v[18:19], v[70:71], v[42:43] op_sel:[0,0,0] op_sel_hi:[1,0,1]
	v_pk_fma_f32 v[38:39], v[18:19], v[60:61], v[38:39] op_sel:[0,1,0] op_sel_hi:[1,1,1]
	v_pk_mul_f32 v[44:45], v[72:73], v[62:63] op_sel_hi:[1,0]
	v_pk_fma_f32 v[20:21], v[20:21], v[70:71], v[44:45] op_sel:[0,1,0] op_sel_hi:[1,1,1]
	v_pk_fma_f32 v[38:39], v[20:21], v[62:63], v[38:39] op_sel:[0,1,0] op_sel_hi:[1,1,1]
	s_add_u32 s14, s14, 0x1000
	s_addc_u32 s15, s15, 0
	v_add_f32_dpp v38, v38, v38 row_ror:8 row_mask:0xf bank_mask:0x3 bound_ctrl:1
	v_add_f32_dpp v38, v39, v39 row_ror:8 row_mask:0xf bank_mask:0xc bound_ctrl:1
	ds_read_b64 v[104:105], v23 offset:38400
	ds_read_b128 v[80:83], v2 offset:54528
	v_add_f32_dpp v38, v38, v38 row_half_mirror row_mask:0xf bank_mask:0xf bound_ctrl:1
	ds_read_b128 v[96:99], v22 offset:35584
	ds_read_b128 v[84:87], v2 offset:54784
	v_add_f32_dpp v38, v38, v38 quad_perm:[1,0,3,2] row_mask:0xf bank_mask:0xf bound_ctrl:1
	ds_read_b128 v[88:91], v2 offset:55040
	ds_read_b128 v[100:103], v22 offset:35840
	v_add_f32_dpp v38, v38, v38 quad_perm:[2,3,0,1] row_mask:0xf bank_mask:0xf bound_ctrl:1
	ds_read_b128 v[92:95], v2 offset:55296
	v_cvt_pk_bf16_f32 v47, v38, v38
	s_mov_b64 exec, s[2:3]
	global_store_short v28, v47, s[14:15] offset:-4096
	s_mov_b64 exec, -1
	s_waitcnt lgkmcnt(4)
	v_pk_mul_f32 v[42:43], v[104:105], v[80:81] op_sel_hi:[1,0]
	v_pk_fma_f32 v[6:7], v[6:7], v[96:97], v[42:43] op_sel:[0,0,0] op_sel_hi:[1,0,1]
	v_pk_mul_f32 v[38:39], v[6:7], v[80:81] op_sel:[0,1] op_sel_hi:[1,1]
	v_pk_mul_f32 v[44:45], v[104:105], v[82:83] op_sel_hi:[1,0]
	v_pk_fma_f32 v[8:9], v[8:9], v[96:97], v[44:45] op_sel:[0,1,0] op_sel_hi:[1,1,1]
	v_pk_fma_f32 v[38:39], v[8:9], v[82:83], v[38:39] op_sel:[0,1,0] op_sel_hi:[1,1,1]
	s_waitcnt lgkmcnt(3)
	v_pk_mul_f32 v[42:43], v[104:105], v[84:85] op_sel_hi:[1,0]
	v_pk_fma_f32 v[10:11], v[10:11], v[98:99], v[42:43] op_sel:[0,0,0] op_sel_hi:[1,0,1]
	v_pk_fma_f32 v[38:39], v[10:11], v[84:85], v[38:39] op_sel:[0,1,0] op_sel_hi:[1,1,1]
	v_pk_mul_f32 v[44:45], v[104:105], v[86:87] op_sel_hi:[1,0]
	v_pk_fma_f32 v[12:13], v[12:13], v[98:99], v[44:45] op_sel:[0,1,0] op_sel_hi:[1,1,1]
	v_pk_fma_f32 v[38:39], v[12:13], v[86:87], v[38:39] op_sel:[0,1,0] op_sel_hi:[1,1,1]
	s_waitcnt lgkmcnt(1)
	v_pk_mul_f32 v[42:43], v[104:105], v[88:89] op_sel_hi:[1,0]
	v_pk_fma_f32 v[14:15], v[14:15], v[100:101], v[42:43] op_sel:[0,0,0] op_sel_hi:[1,0,1]
	v_pk_fma_f32 v[38:39], v[14:15], v[88:89], v[38:39] op_sel:[0,1,0] op_sel_hi:[1,1,1]
	v_pk_mul_f32 v[44:45], v[104:105], v[90:91] op_sel_hi:[1,0]
	v_pk_fma_f32 v[16:17], v[16:17], v[100:101], v[44:45] op_sel:[0,1,0] op_sel_hi:[1,1,1]
	v_pk_fma_f32 v[38:39], v[16:17], v[90:91], v[38:39] op_sel:[0,1,0] op_sel_hi:[1,1,1]
	s_waitcnt lgkmcnt(0)
	v_pk_mul_f32 v[42:43], v[104:105], v[92:93] op_sel_hi:[1,0]
	v_pk_fma_f32 v[18:19], v[18:19], v[102:103], v[42:43] op_sel:[0,0,0] op_sel_hi:[1,0,1]
	v_pk_fma_f32 v[38:39], v[18:19], v[92:93], v[38:39] op_sel:[0,1,0] op_sel_hi:[1,1,1]
	v_pk_mul_f32 v[44:45], v[104:105], v[94:95] op_sel_hi:[1,0]
	v_pk_fma_f32 v[20:21], v[20:21], v[102:103], v[44:45] op_sel:[0,1,0] op_sel_hi:[1,1,1]
	v_pk_fma_f32 v[38:39], v[20:21], v[94:95], v[38:39] op_sel:[0,1,0] op_sel_hi:[1,1,1]
	s_add_u32 s14, s14, 0x1000
	s_addc_u32 s15, s15, 0
	v_add_f32_dpp v38, v38, v38 row_ror:8 row_mask:0xf bank_mask:0x3 bound_ctrl:1
	v_add_f32_dpp v38, v39, v39 row_ror:8 row_mask:0xf bank_mask:0xc bound_ctrl:1
	ds_read_b64 v[72:73], v23 offset:38656
	ds_read_b128 v[48:51], v2 offset:55552
	v_add_f32_dpp v38, v38, v38 row_half_mirror row_mask:0xf bank_mask:0xf bound_ctrl:1
	ds_read_b128 v[64:67], v22 offset:36096
	ds_read_b128 v[52:55], v2 offset:55808
	v_add_f32_dpp v38, v38, v38 quad_perm:[1,0,3,2] row_mask:0xf bank_mask:0xf bound_ctrl:1
	ds_read_b128 v[56:59], v2 offset:56064
	ds_read_b128 v[68:71], v22 offset:36352
	v_add_f32_dpp v38, v38, v38 quad_perm:[2,3,0,1] row_mask:0xf bank_mask:0xf bound_ctrl:1
	ds_read_b128 v[60:63], v2 offset:56320
	v_cvt_pk_bf16_f32 v47, v38, v38
	s_mov_b64 exec, s[2:3]
	global_store_short v28, v47, s[14:15] offset:-4096
	s_mov_b64 exec, -1
	s_waitcnt lgkmcnt(4)
	v_pk_mul_f32 v[42:43], v[72:73], v[48:49] op_sel_hi:[1,0]
	v_pk_fma_f32 v[6:7], v[6:7], v[64:65], v[42:43] op_sel:[0,0,0] op_sel_hi:[1,0,1]
	v_pk_mul_f32 v[38:39], v[6:7], v[48:49] op_sel:[0,1] op_sel_hi:[1,1]
	v_pk_mul_f32 v[44:45], v[72:73], v[50:51] op_sel_hi:[1,0]
	v_pk_fma_f32 v[8:9], v[8:9], v[64:65], v[44:45] op_sel:[0,1,0] op_sel_hi:[1,1,1]
	v_pk_fma_f32 v[38:39], v[8:9], v[50:51], v[38:39] op_sel:[0,1,0] op_sel_hi:[1,1,1]
	s_waitcnt lgkmcnt(3)
	v_pk_mul_f32 v[42:43], v[72:73], v[52:53] op_sel_hi:[1,0]
	v_pk_fma_f32 v[10:11], v[10:11], v[66:67], v[42:43] op_sel:[0,0,0] op_sel_hi:[1,0,1]
	v_pk_fma_f32 v[38:39], v[10:11], v[52:53], v[38:39] op_sel:[0,1,0] op_sel_hi:[1,1,1]
	v_pk_mul_f32 v[44:45], v[72:73], v[54:55] op_sel_hi:[1,0]
	v_pk_fma_f32 v[12:13], v[12:13], v[66:67], v[44:45] op_sel:[0,1,0] op_sel_hi:[1,1,1]
	v_pk_fma_f32 v[38:39], v[12:13], v[54:55], v[38:39] op_sel:[0,1,0] op_sel_hi:[1,1,1]
	s_waitcnt lgkmcnt(1)
	v_pk_mul_f32 v[42:43], v[72:73], v[56:57] op_sel_hi:[1,0]
	v_pk_fma_f32 v[14:15], v[14:15], v[68:69], v[42:43] op_sel:[0,0,0] op_sel_hi:[1,0,1]
	v_pk_fma_f32 v[38:39], v[14:15], v[56:57], v[38:39] op_sel:[0,1,0] op_sel_hi:[1,1,1]
	v_pk_mul_f32 v[44:45], v[72:73], v[58:59] op_sel_hi:[1,0]
	v_pk_fma_f32 v[16:17], v[16:17], v[68:69], v[44:45] op_sel:[0,1,0] op_sel_hi:[1,1,1]
	v_pk_fma_f32 v[38:39], v[16:17], v[58:59], v[38:39] op_sel:[0,1,0] op_sel_hi:[1,1,1]
	s_waitcnt lgkmcnt(0)
	v_pk_mul_f32 v[42:43], v[72:73], v[60:61] op_sel_hi:[1,0]
	v_pk_fma_f32 v[18:19], v[18:19], v[70:71], v[42:43] op_sel:[0,0,0] op_sel_hi:[1,0,1]
	v_pk_fma_f32 v[38:39], v[18:19], v[60:61], v[38:39] op_sel:[0,1,0] op_sel_hi:[1,1,1]
	v_pk_mul_f32 v[44:45], v[72:73], v[62:63] op_sel_hi:[1,0]
	v_pk_fma_f32 v[20:21], v[20:21], v[70:71], v[44:45] op_sel:[0,1,0] op_sel_hi:[1,1,1]
	v_pk_fma_f32 v[38:39], v[20:21], v[62:63], v[38:39] op_sel:[0,1,0] op_sel_hi:[1,1,1]
	s_add_u32 s14, s14, 0x1000
	s_addc_u32 s15, s15, 0
	v_add_f32_dpp v38, v38, v38 row_ror:8 row_mask:0xf bank_mask:0x3 bound_ctrl:1
	v_add_f32_dpp v38, v39, v39 row_ror:8 row_mask:0xf bank_mask:0xc bound_ctrl:1
	ds_read_b64 v[104:105], v23 offset:38912
	ds_read_b128 v[80:83], v2 offset:56576
	v_add_f32_dpp v38, v38, v38 row_half_mirror row_mask:0xf bank_mask:0xf bound_ctrl:1
	ds_read_b128 v[96:99], v22 offset:36608
	ds_read_b128 v[84:87], v2 offset:56832
	v_add_f32_dpp v38, v38, v38 quad_perm:[1,0,3,2] row_mask:0xf bank_mask:0xf bound_ctrl:1
	ds_read_b128 v[88:91], v2 offset:57088
	ds_read_b128 v[100:103], v22 offset:36864
	v_add_f32_dpp v38, v38, v38 quad_perm:[2,3,0,1] row_mask:0xf bank_mask:0xf bound_ctrl:1
	ds_read_b128 v[92:95], v2 offset:57344
	v_cvt_pk_bf16_f32 v47, v38, v38
	s_mov_b64 exec, s[2:3]
	global_store_short v28, v47, s[14:15] offset:-4096
	s_mov_b64 exec, -1
	s_waitcnt lgkmcnt(4)
	v_pk_mul_f32 v[42:43], v[104:105], v[80:81] op_sel_hi:[1,0]
	v_pk_fma_f32 v[6:7], v[6:7], v[96:97], v[42:43] op_sel:[0,0,0] op_sel_hi:[1,0,1]
	v_pk_mul_f32 v[38:39], v[6:7], v[80:81] op_sel:[0,1] op_sel_hi:[1,1]
	v_pk_mul_f32 v[44:45], v[104:105], v[82:83] op_sel_hi:[1,0]
	v_pk_fma_f32 v[8:9], v[8:9], v[96:97], v[44:45] op_sel:[0,1,0] op_sel_hi:[1,1,1]
	v_pk_fma_f32 v[38:39], v[8:9], v[82:83], v[38:39] op_sel:[0,1,0] op_sel_hi:[1,1,1]
	s_waitcnt lgkmcnt(3)
	v_pk_mul_f32 v[42:43], v[104:105], v[84:85] op_sel_hi:[1,0]
	v_pk_fma_f32 v[10:11], v[10:11], v[98:99], v[42:43] op_sel:[0,0,0] op_sel_hi:[1,0,1]
	v_pk_fma_f32 v[38:39], v[10:11], v[84:85], v[38:39] op_sel:[0,1,0] op_sel_hi:[1,1,1]
	v_pk_mul_f32 v[44:45], v[104:105], v[86:87] op_sel_hi:[1,0]
	v_pk_fma_f32 v[12:13], v[12:13], v[98:99], v[44:45] op_sel:[0,1,0] op_sel_hi:[1,1,1]
	v_pk_fma_f32 v[38:39], v[12:13], v[86:87], v[38:39] op_sel:[0,1,0] op_sel_hi:[1,1,1]
	s_waitcnt lgkmcnt(1)
	v_pk_mul_f32 v[42:43], v[104:105], v[88:89] op_sel_hi:[1,0]
	v_pk_fma_f32 v[14:15], v[14:15], v[100:101], v[42:43] op_sel:[0,0,0] op_sel_hi:[1,0,1]
	v_pk_fma_f32 v[38:39], v[14:15], v[88:89], v[38:39] op_sel:[0,1,0] op_sel_hi:[1,1,1]
	v_pk_mul_f32 v[44:45], v[104:105], v[90:91] op_sel_hi:[1,0]
	v_pk_fma_f32 v[16:17], v[16:17], v[100:101], v[44:45] op_sel:[0,1,0] op_sel_hi:[1,1,1]
	v_pk_fma_f32 v[38:39], v[16:17], v[90:91], v[38:39] op_sel:[0,1,0] op_sel_hi:[1,1,1]
	s_waitcnt lgkmcnt(0)
	v_pk_mul_f32 v[42:43], v[104:105], v[92:93] op_sel_hi:[1,0]
	v_pk_fma_f32 v[18:19], v[18:19], v[102:103], v[42:43] op_sel:[0,0,0] op_sel_hi:[1,0,1]
	v_pk_fma_f32 v[38:39], v[18:19], v[92:93], v[38:39] op_sel:[0,1,0] op_sel_hi:[1,1,1]
	v_pk_mul_f32 v[44:45], v[104:105], v[94:95] op_sel_hi:[1,0]
	v_pk_fma_f32 v[20:21], v[20:21], v[102:103], v[44:45] op_sel:[0,1,0] op_sel_hi:[1,1,1]
	v_pk_fma_f32 v[38:39], v[20:21], v[94:95], v[38:39] op_sel:[0,1,0] op_sel_hi:[1,1,1]
	s_add_u32 s14, s14, 0x1000
	s_addc_u32 s15, s15, 0
	v_add_f32_dpp v38, v38, v38 row_ror:8 row_mask:0xf bank_mask:0x3 bound_ctrl:1
	v_add_f32_dpp v38, v39, v39 row_ror:8 row_mask:0xf bank_mask:0xc bound_ctrl:1
	ds_read_b64 v[72:73], v3 offset:20736
	ds_read_b128 v[48:51], v2 offset:256
	v_add_f32_dpp v38, v38, v38 row_half_mirror row_mask:0xf bank_mask:0xf bound_ctrl:1
	ds_read_b128 v[64:67], v2 offset:16640
	ds_read_b128 v[52:55], v2 offset:512
	v_add_f32_dpp v38, v38, v38 quad_perm:[1,0,3,2] row_mask:0xf bank_mask:0xf bound_ctrl:1
	ds_read_b128 v[56:59], v2 offset:768
	ds_read_b128 v[68:71], v2 offset:16896
	v_add_f32_dpp v38, v38, v38 quad_perm:[2,3,0,1] row_mask:0xf bank_mask:0xf bound_ctrl:1
	ds_read_b128 v[60:63], v2 offset:1024
	v_cvt_pk_bf16_f32 v47, v38, v38
	s_mov_b64 exec, s[2:3]
	global_store_short v28, v47, s[14:15] offset:-4096
	s_mov_b64 exec, -1
	s_waitcnt vmcnt(8)
	v_lshlrev_b32_e32 v144, 16, v110
	v_lshlrev_b32_e32 v145, 16, v111
	v_and_b32_e32 v146, s17, v110
	v_and_b32_e32 v147, s17, v111
	v_lshlrev_b32_e32 v148, 16, v112
	v_lshlrev_b32_e32 v149, 16, v113
	v_and_b32_e32 v150, s17, v112
	v_and_b32_e32 v151, s17, v113
	v_lshlrev_b32_e32 v152, 16, v114
	v_and_b32_e32 v153, s17, v114
	v_rcp_f32_e32 v25, v24
	v_mul_f32_e32 v149, v24, v149
	v_mul_f32_e32 v151, v24, v151
	v_mul_f32_e32 v145, 0x3db504f3, v145
	v_mul_f32_e32 v147, 0x3db504f3, v147
	v_cndmask_b32_e64 v27, 1.0, v25, s[20:21]
	v_mul_f32_e32 v24, v24, v26
	v_mul_f32_e32 v152, v27, v152
	v_mul_f32_e32 v153, v27, v153
	ds_write_b128 v29, v[144:147] offset:24832
	ds_write_b128 v29, v[148:151] offset:33024
	ds_write_b64 v30, v[116:117] offset:24832
	ds_write_b64 v31, v[152:153] offset:24832
	s_add_i32 s16, s16, 8
	s_waitcnt lgkmcnt(0)
	global_load_dword v110, v32, s[10:11]
	global_load_dword v111, v32, s[10:11] offset:-1024
	global_load_dword v112, v33, s[10:11]
	global_load_dword v113, v33, s[10:11] offset:-1024
	global_load_dword v114, v34, s[10:11]
	global_load_dword v116, v35, s[12:13]
	global_load_dword v117, v35, s[12:13] offset:4
	s_add_u32 s10, s10, 0x18000
	s_addc_u32 s11, s11, 0
	s_add_u32 s12, s12, 0x4000
	s_addc_u32 s13, s13, 0
	s_barrier
	s_cmpk_lt_u32 s16, 0x800
	s_cbranch_scc1 .Lgla2_loop
.Lgla2_done:
	s_waitcnt vmcnt(0)
	v_readlane_b32 s0, v255, 18
	v_readlane_b32 s1, v255, 19
	s_load_dwordx2 s[2:3], s[0:1], 0xe8
	s_lshr_b32 s0, s18, 5
	s_lshl_b32 s4, s0, 17
	s_add_u32 s4, s4, 74236160
	v_lshl_add_u32 v42, v46, 1, v4
	s_waitcnt lgkmcnt(0)
	s_add_u32 s2, s2, s4
	s_addc_u32 s3, s3, 0
	global_store_dwordx2 v42, v[6:7], s[2:3] offset:0
	global_store_dwordx2 v42, v[8:9], s[2:3] offset:1024
	global_store_dwordx2 v42, v[10:11], s[2:3] offset:2048
	global_store_dwordx2 v42, v[12:13], s[2:3] offset:3072
	s_add_u32 s2, s2, 0x1000
	s_addc_u32 s3, s3, 0
	global_store_dwordx2 v42, v[14:15], s[2:3] offset:0
	global_store_dwordx2 v42, v[16:17], s[2:3] offset:1024
	global_store_dwordx2 v42, v[18:19], s[2:3] offset:2048
	global_store_dwordx2 v42, v[20:21], s[2:3] offset:3072
	s_add_i32 s18, s18, s19
	s_waitcnt vmcnt(0)
	s_cmpk_lt_i32 s18, 0x400
	s_cbranch_scc1 .Lgla2_item
	s_branch .LBB0_80

.Lml2_nsc1:
	v_add_u32_e32 v64, s20, v69
	v_add_u32_e32 v65, s20, v70
	v_add_u32_e32 v66, s20, v71
	v_add_u32_e32 v67, s20, v72
	v_add_u32_e32 v68, s20, v73
	v_add_u32_e32 v58, s18, v2
	v_add_u32_e32 v59, s18, v3
	v_mov_b32_e32 v60, s18
	v_add_u32_e32 v61, s19, v2
	v_add_u32_e32 v62, s19, v3
	v_mov_b32_e32 v63, s19
	v_mov_b32_e32 v6, 0
	v_mov_b32_e32 v7, 0
	v_mov_b32_e32 v8, 0
	v_mov_b32_e32 v9, 0
	v_mov_b32_e32 v10, 0
	v_mov_b32_e32 v11, 0
	v_mov_b32_e32 v12, 0
	v_mov_b32_e32 v13, 0
	v_mov_b32_e32 v14, 0
	v_mov_b32_e32 v15, 0
	v_mov_b32_e32 v16, 0
	v_mov_b32_e32 v17, 0
	s_mov_b32 s16, 0
	s_waitcnt vmcnt(0) lgkmcnt(0)
	s_barrier
	global_load_dword v80, v74, s[8:9]
	global_load_dword v81, v74, s[8:9] offset:-2048
	global_load_dword v83, v76, s[8:9] offset:2048
	global_load_dword v82, v75, s[10:11]
	global_load_dword v84, v77, s[10:11]
	global_load_dword v85, v78, s[12:13]
	s_cmp_lg_u32 s36, 4
	s_cbranch_scc1 .Lml2_nsl2
	global_load_dwordx2 v[86:87], v79, s[22:23]
.Lml2_nsl2:
	s_add_u32 s22, s22, 0x400
	s_addc_u32 s23, s23, 0
	s_add_u32 s8, s8, 0xc000
	s_addc_u32 s9, s9, 0
	s_add_u32 s10, s10, 0x20000
	s_addc_u32 s11, s11, 0
	s_add_u32 s12, s12, 0x400
	s_addc_u32 s13, s13, 0
	ds_read_b128 v[30:33], v2 offset:8448
	ds_read_b128 v[34:37], v2 offset:8704
	ds_read_b64 v[38:39], v3 offset:12544
	ds_read_b128 v[40:43], v1 offset:14848
.Lml2_loop:
	ds_read_b128 v[44:47], v2 offset:8960
	ds_read_b128 v[48:51], v2 offset:9216
	ds_read_b64 v[52:53], v3 offset:12800
	ds_read_b128 v[54:57], v1 offset:14864
	s_waitcnt lgkmcnt(4)
	v_pk_mul_f32 v[18:19], v[30:31], v[40:41] op_sel:[0,1] op_sel_hi:[1,1]
	v_pk_mul_f32 v[20:21], v[32:33], v[40:41] op_sel:[0,1] op_sel_hi:[1,1]
	v_pk_mul_f32 v[22:23], v[38:39], v[18:19] op_sel:[0,0] op_sel_hi:[1,0]
	v_pk_fma_f32 v[6:7], v[6:7], v[40:41], v[22:23] op_sel_hi:[1,0,1]
	v_pk_mul_f32 v[26:27], v[6:7], v[34:35] op_sel_hi:[1,0]
	v_pk_mul_f32 v[24:25], v[38:39], v[18:19] op_sel:[0,1] op_sel_hi:[1,1]
	v_pk_fma_f32 v[8:9], v[8:9], v[40:41], v[24:25] op_sel_hi:[1,0,1]
	v_pk_fma_f32 v[26:27], v[8:9], v[34:35], v[26:27] op_sel:[0,1,0] op_sel_hi:[1,1,1]
	v_pk_mul_f32 v[22:23], v[38:39], v[20:21] op_sel:[0,0] op_sel_hi:[1,0]
	v_pk_fma_f32 v[10:11], v[10:11], v[40:41], v[22:23] op_sel_hi:[1,0,1]
	v_pk_fma_f32 v[26:27], v[10:11], v[36:37], v[26:27] op_sel:[0,0,0] op_sel_hi:[1,0,1]
	v_pk_mul_f32 v[24:25], v[38:39], v[20:21] op_sel:[0,1] op_sel_hi:[1,1]
	v_pk_fma_f32 v[12:13], v[12:13], v[40:41], v[24:25] op_sel_hi:[1,0,1]
	v_pk_fma_f32 v[26:27], v[12:13], v[36:37], v[26:27] op_sel:[0,1,0] op_sel_hi:[1,1,1]
	v_pk_fma_f32 v[14:15], v[14:15], v[40:41], v[18:19] op_sel_hi:[1,0,1]
	v_pk_fma_f32 v[16:17], v[16:17], v[40:41], v[20:21] op_sel_hi:[1,0,1]
	v_add_f32_dpp v26, v26, v26 quad_perm:[1,0,3,2] row_mask:0xf bank_mask:0xf bound_ctrl:1
	v_add_f32_dpp v27, v27, v27 quad_perm:[1,0,3,2] row_mask:0xf bank_mask:0xf bound_ctrl:1
	s_add_u32 s14, s14, 0x1000
	v_add_f32_dpp v26, v26, v26 quad_perm:[2,3,0,1] row_mask:0xf bank_mask:0xf bound_ctrl:1
	v_add_f32_dpp v27, v27, v27 quad_perm:[2,3,0,1] row_mask:0xf bank_mask:0xf bound_ctrl:1
	s_addc_u32 s15, s15, 0
	v_add_f32_dpp v26, v26, v26 row_half_mirror row_mask:0xf bank_mask:0xf bound_ctrl:1
	v_add_f32_dpp v27, v27, v27 row_half_mirror row_mask:0xf bank_mask:0xf bound_ctrl:1
	s_cmp_eq_u32 s21, 0
	v_add_f32_dpp v26, v26, v26 row_mirror row_mask:0xf bank_mask:0xf bound_ctrl:1
	v_add_f32_dpp v27, v27, v27 row_mirror row_mask:0xf bank_mask:0xf bound_ctrl:1
	s_cbranch_scc1 .Lml2_den0_0

.Lml2_nsc2:
	s_add_u32 s24, s24, 0x400
	s_addc_u32 s25, s25, 0
	s_sub_i32 s21, s21, 8
	s_add_i32 s16, s16, 8
	s_waitcnt lgkmcnt(0)
	global_load_dword v80, v74, s[8:9]
	global_load_dword v81, v74, s[8:9] offset:-2048
	global_load_dword v83, v76, s[8:9] offset:2048
	global_load_dword v82, v75, s[10:11]
	global_load_dword v84, v77, s[10:11]
	global_load_dword v85, v78, s[12:13]
	s_cmp_lg_u32 s36, 4
	s_cbranch_scc1 .Lml2_nsl3
	global_load_dwordx2 v[86:87], v79, s[22:23]
.Lml2_nsl3:
	s_add_u32 s22, s22, 0x400
	s_addc_u32 s23, s23, 0
	s_add_u32 s8, s8, 0xc000
	s_addc_u32 s9, s9, 0
	s_add_u32 s10, s10, 0x20000
	s_addc_u32 s11, s11, 0
	s_add_u32 s12, s12, 0x400
	s_addc_u32 s13, s13, 0
	s_barrier
	s_cmpk_lt_u32 s16, 0x800
	s_cbranch_scc0 .Lml2_done
	ds_read_b128 v[44:47], v2 offset:25344
	ds_read_b128 v[48:51], v2 offset:25600
	ds_read_b64 v[52:53], v3 offset:29184
	ds_read_b128 v[54:57], v1 offset:31248
	s_waitcnt lgkmcnt(4)
	v_pk_mul_f32 v[18:19], v[30:31], v[40:41] op_sel:[0,1] op_sel_hi:[1,1]
	v_pk_mul_f32 v[20:21], v[32:33], v[40:41] op_sel:[0,1] op_sel_hi:[1,1]
	v_pk_mul_f32 v[22:23], v[38:39], v[18:19] op_sel:[0,0] op_sel_hi:[1,0]
	v_pk_fma_f32 v[6:7], v[6:7], v[40:41], v[22:23] op_sel_hi:[1,0,1]
	v_pk_mul_f32 v[26:27], v[6:7], v[34:35] op_sel_hi:[1,0]
	v_pk_mul_f32 v[24:25], v[38:39], v[18:19] op_sel:[0,1] op_sel_hi:[1,1]
	v_pk_fma_f32 v[8:9], v[8:9], v[40:41], v[24:25] op_sel_hi:[1,0,1]
	v_pk_fma_f32 v[26:27], v[8:9], v[34:35], v[26:27] op_sel:[0,1,0] op_sel_hi:[1,1,1]
	v_pk_mul_f32 v[22:23], v[38:39], v[20:21] op_sel:[0,0] op_sel_hi:[1,0]
	v_pk_fma_f32 v[10:11], v[10:11], v[40:41], v[22:23] op_sel_hi:[1,0,1]
	v_pk_fma_f32 v[26:27], v[10:11], v[36:37], v[26:27] op_sel:[0,0,0] op_sel_hi:[1,0,1]
	v_pk_mul_f32 v[24:25], v[38:39], v[20:21] op_sel:[0,1] op_sel_hi:[1,1]
	v_pk_fma_f32 v[12:13], v[12:13], v[40:41], v[24:25] op_sel_hi:[1,0,1]
	v_pk_fma_f32 v[26:27], v[12:13], v[36:37], v[26:27] op_sel:[0,1,0] op_sel_hi:[1,1,1]
	v_pk_fma_f32 v[14:15], v[14:15], v[40:41], v[18:19] op_sel_hi:[1,0,1]
	v_pk_fma_f32 v[16:17], v[16:17], v[40:41], v[20:21] op_sel_hi:[1,0,1]
	v_add_f32_dpp v26, v26, v26 quad_perm:[1,0,3,2] row_mask:0xf bank_mask:0xf bound_ctrl:1
	v_add_f32_dpp v27, v27, v27 quad_perm:[1,0,3,2] row_mask:0xf bank_mask:0xf bound_ctrl:1
	s_add_u32 s14, s14, 0x1000
	v_add_f32_dpp v26, v26, v26 quad_perm:[2,3,0,1] row_mask:0xf bank_mask:0xf bound_ctrl:1
	v_add_f32_dpp v27, v27, v27 quad_perm:[2,3,0,1] row_mask:0xf bank_mask:0xf bound_ctrl:1
	s_addc_u32 s15, s15, 0
	v_add_f32_dpp v26, v26, v26 row_half_mirror row_mask:0xf bank_mask:0xf bound_ctrl:1
	v_add_f32_dpp v27, v27, v27 row_half_mirror row_mask:0xf bank_mask:0xf bound_ctrl:1
	s_cmp_eq_u32 s21, 0
	v_add_f32_dpp v26, v26, v26 row_mirror row_mask:0xf bank_mask:0xf bound_ctrl:1
	v_add_f32_dpp v27, v27, v27 row_mirror row_mask:0xf bank_mask:0xf bound_ctrl:1
	s_cbranch_scc1 .Lml2_den1_0

.Lml2_nsl4:
	s_add_u32 s22, s22, 0x400
	s_addc_u32 s23, s23, 0
	s_add_u32 s8, s8, 0xc000
	s_addc_u32 s9, s9, 0
	s_add_u32 s10, s10, 0x20000
	s_addc_u32 s11, s11, 0
	s_add_u32 s12, s12, 0x400
	s_addc_u32 s13, s13, 0
	s_barrier
	s_cmpk_lt_u32 s16, 0x800
	s_cbranch_scc0 .Lml2_done
	ds_read_b128 v[44:47], v2 offset:41728
	ds_read_b128 v[48:51], v2 offset:41984
	ds_read_b64 v[52:53], v3 offset:45568
	ds_read_b128 v[54:57], v1 offset:47632
	s_waitcnt lgkmcnt(4)
	v_pk_mul_f32 v[18:19], v[30:31], v[40:41] op_sel:[0,1] op_sel_hi:[1,1]
	v_pk_mul_f32 v[20:21], v[32:33], v[40:41] op_sel:[0,1] op_sel_hi:[1,1]
	v_pk_mul_f32 v[22:23], v[38:39], v[18:19] op_sel:[0,0] op_sel_hi:[1,0]
	v_pk_fma_f32 v[6:7], v[6:7], v[40:41], v[22:23] op_sel_hi:[1,0,1]
	v_pk_mul_f32 v[26:27], v[6:7], v[34:35] op_sel_hi:[1,0]
	v_pk_mul_f32 v[24:25], v[38:39], v[18:19] op_sel:[0,1] op_sel_hi:[1,1]
	v_pk_fma_f32 v[8:9], v[8:9], v[40:41], v[24:25] op_sel_hi:[1,0,1]
	v_pk_fma_f32 v[26:27], v[8:9], v[34:35], v[26:27] op_sel:[0,1,0] op_sel_hi:[1,1,1]
	v_pk_mul_f32 v[22:23], v[38:39], v[20:21] op_sel:[0,0] op_sel_hi:[1,0]
	v_pk_fma_f32 v[10:11], v[10:11], v[40:41], v[22:23] op_sel_hi:[1,0,1]
	v_pk_fma_f32 v[26:27], v[10:11], v[36:37], v[26:27] op_sel:[0,0,0] op_sel_hi:[1,0,1]
	v_pk_mul_f32 v[24:25], v[38:39], v[20:21] op_sel:[0,1] op_sel_hi:[1,1]
	v_pk_fma_f32 v[12:13], v[12:13], v[40:41], v[24:25] op_sel_hi:[1,0,1]
	v_pk_fma_f32 v[26:27], v[12:13], v[36:37], v[26:27] op_sel:[0,1,0] op_sel_hi:[1,1,1]
	v_pk_fma_f32 v[14:15], v[14:15], v[40:41], v[18:19] op_sel_hi:[1,0,1]
	v_pk_fma_f32 v[16:17], v[16:17], v[40:41], v[20:21] op_sel_hi:[1,0,1]
	v_add_f32_dpp v26, v26, v26 quad_perm:[1,0,3,2] row_mask:0xf bank_mask:0xf bound_ctrl:1
	v_add_f32_dpp v27, v27, v27 quad_perm:[1,0,3,2] row_mask:0xf bank_mask:0xf bound_ctrl:1
	s_add_u32 s14, s14, 0x1000
	v_add_f32_dpp v26, v26, v26 quad_perm:[2,3,0,1] row_mask:0xf bank_mask:0xf bound_ctrl:1
	v_add_f32_dpp v27, v27, v27 quad_perm:[2,3,0,1] row_mask:0xf bank_mask:0xf bound_ctrl:1
	s_addc_u32 s15, s15, 0
	v_add_f32_dpp v26, v26, v26 row_half_mirror row_mask:0xf bank_mask:0xf bound_ctrl:1
	v_add_f32_dpp v27, v27, v27 row_half_mirror row_mask:0xf bank_mask:0xf bound_ctrl:1
	s_cmp_eq_u32 s21, 0
	v_add_f32_dpp v26, v26, v26 row_mirror row_mask:0xf bank_mask:0xf bound_ctrl:1
	v_add_f32_dpp v27, v27, v27 row_mirror row_mask:0xf bank_mask:0xf bound_ctrl:1
	s_cbranch_scc1 .Lml2_den2_0

.Lml2_nsl5:
	s_add_u32 s22, s22, 0x400
	s_addc_u32 s23, s23, 0
	s_add_u32 s8, s8, 0xc000
	s_addc_u32 s9, s9, 0
	s_add_u32 s10, s10, 0x20000
	s_addc_u32 s11, s11, 0
	s_add_u32 s12, s12, 0x400
	s_addc_u32 s13, s13, 0
	s_barrier
	s_cmpk_lt_u32 s16, 0x800
	s_cbranch_scc1 .Lml2_loop
.Lml2_done:
	s_waitcnt vmcnt(0)
	s_lshr_b32 s2, s30, 4
	s_lshl_b32 s4, s2, 15
	s_add_u32 s4, s4, 0x44c8000
	s_add_u32 s0, s34, s4
	s_addc_u32 s1, s35, 0
	v_and_b32_e32 v104, 15, v198
	v_lshlrev_b32_e32 v105, 11, v104
	v_lshl_add_u32 v105, v4, 1, v105
	global_store_dwordx2 v105, v[6:7], s[0:1] offset:0
	global_store_dwordx2 v105, v[8:9], s[0:1] offset:512
	global_store_dwordx2 v105, v[10:11], s[0:1] offset:1024
	global_store_dwordx2 v105, v[12:13], s[0:1] offset:1536
	s_cmp_lg_u32 s31, 0
	s_cbranch_scc1 .Lml2_nonm
	s_lshl_b32 s4, s2, 8
	s_add_u32 s4, s4, 0x46c8000
	s_add_u32 s0, s34, s4
	s_addc_u32 s1, s35, 0
	v_lshlrev_b32_e32 v104, 4, v104
	global_store_dwordx2 v104, v[14:15], s[0:1]
	global_store_dwordx2 v104, v[16:17], s[0:1] offset:8
	s_lshl_b32 s4, s2, 2
	s_add_u32 s4, s4, 0x46cc000
	s_add_u32 s0, s34, s4
	s_addc_u32 s1, s35, 0
	global_store_dword v1, v57, s[0:1]

.Lgd2_item:
	s_lshr_b32 s2, s27, 4
	s_and_b32 s3, s27, 15
	s_lshl_b32 s4, s3, 4
	v_lshl_add_u32 v154, v5, 2, s4
	v_lshl_add_u32 v153, v154, 1, v4
	s_and_b32 s4, s3, 3
	s_lshl_b32 s4, s4, 5
	v_lshl_add_u32 v3, v5, 3, s4
	s_and_b32 s4, s3, 12
	s_lshl_b32 s4, s4, 4
	v_min_u32_e32 v155, 15, v198
	v_lshl_add_u32 v104, v155, 2, s4
	s_and_b32 s5, s2, 7
	s_lshl_b32 s3, s5, 7
	s_add_u32 s4, s4, s3
	s_add_u32 s4, s4, 2048
	v_lshl_add_u32 v105, v155, 2, s4
	s_lshr_b32 s4, s2, 3
	v_readlane_b32 s3, v255, 15
	s_mul_i32 s6, s4, 0xc00000
	s_mul_i32 s7, s3, 0x1800
	s_add_u32 s6, s6, s7
	s_lshl_b32 s7, s5, 8
	s_add_u32 s6, s6, s7
	s_add_u32 s6, s6, 0xb38d900
	s_add_u32 s8, s24, s6
	s_addc_u32 s9, s25, 0
	s_lshl_b32 s6, s4, 25
	s_lshl_b32 s7, s3, 14
	s_add_u32 s6, s6, s7
	s_lshl_b32 s7, s5, 7
	s_add_u32 s6, s6, s7
	s_add_u32 s6, s6, 62659584
	s_add_u32 s10, s22, s6
	s_addc_u32 s11, s23, 0
	s_lshl_b32 s6, s4, 18
	s_lshl_b32 s7, s3, 7
	s_add_u32 s6, s6, s7
	s_lshl_b32 s7, s5, 4
	s_add_u32 s6, s6, s7
	s_add_u32 s6, s6, 0x37b8400
	s_add_u32 s12, s22, s6
	s_addc_u32 s13, s23, 0
	s_lshl_b32 s6, s4, 23
	s_lshl_b32 s7, s5, 8
	s_add_u32 s6, s6, s7
	s_add_u32 s6, s6, 333186048
	s_add_u32 s14, s22, s6
	s_addc_u32 s15, s23, 0
	s_movk_i32 s18, 256
	s_movk_i32 s19, 16640
	s_mov_b32 s20, 33024
	v_add_u32_e32 v28, s18, v32
	v_add_u32_e32 v29, s18, v33
	v_add_u32_e32 v30, s18, v34
	v_add_u32_e32 v31, s18, v35
	global_load_dword v108, v36, s[8:9]
	global_load_dword v109, v36, s[8:9] offset:-2048
	global_load_dword v111, v104, s[8:9] offset:2048
	global_load_dword v110, v37, s[10:11]
	global_load_dword v112, v105, s[10:11]
	global_load_dword v113, v106, s[12:13]
	s_add_u32 s8, s8, 0xc000
	s_addc_u32 s9, s9, 0
	s_add_u32 s10, s10, 0x20000
	s_addc_u32 s11, s11, 0
	s_add_u32 s12, s12, 0x400
	s_addc_u32 s13, s13, 0
	s_waitcnt vmcnt(0)
	v_lshlrev_b32_e32 v116, 16, v108
	v_lshlrev_b32_e32 v117, 16, v109
	v_and_b32_e32 v118, s17, v108
	v_and_b32_e32 v119, s17, v109
	v_lshlrev_b32_e32 v120, 16, v110
	v_and_b32_e32 v121, s17, v110
	v_lshlrev_b32_e32 v122, 16, v111
	v_and_b32_e32 v123, s17, v111
	v_lshlrev_b32_e32 v124, 16, v112
	v_and_b32_e32 v125, s17, v112
	ds_write_b128 v32, v[116:119] offset:256
	ds_write_b64 v33, v[120:121] offset:256
	ds_write_b64 v34, v[122:123] offset:256
	ds_write_b64 v34, v[124:125] offset:384
	ds_write_b32 v35, v113 offset:256
	v_add_u32_e32 v28, s19, v32
	v_add_u32_e32 v29, s19, v33
	v_add_u32_e32 v30, s19, v34
	v_add_u32_e32 v31, s19, v35
	global_load_dword v108, v36, s[8:9]
	global_load_dword v109, v36, s[8:9] offset:-2048
	global_load_dword v111, v104, s[8:9] offset:2048
	global_load_dword v110, v37, s[10:11]
	global_load_dword v112, v105, s[10:11]
	global_load_dword v113, v106, s[12:13]
	s_add_u32 s8, s8, 0xc000
	s_addc_u32 s9, s9, 0
	s_add_u32 s10, s10, 0x20000
	s_addc_u32 s11, s11, 0
	s_add_u32 s12, s12, 0x400
	s_addc_u32 s13, s13, 0
	s_waitcnt vmcnt(0)
	v_lshlrev_b32_e32 v116, 16, v108
	v_lshlrev_b32_e32 v117, 16, v109
	v_and_b32_e32 v118, s17, v108
	v_and_b32_e32 v119, s17, v109
	v_lshlrev_b32_e32 v120, 16, v110
	v_and_b32_e32 v121, s17, v110
	v_lshlrev_b32_e32 v122, 16, v111
	v_and_b32_e32 v123, s17, v111
	v_lshlrev_b32_e32 v124, 16, v112
	v_and_b32_e32 v125, s17, v112
	ds_write_b128 v32, v[116:119] offset:16640
	ds_write_b64 v33, v[120:121] offset:16640
	ds_write_b64 v34, v[122:123] offset:16640
	ds_write_b64 v34, v[124:125] offset:16768
	ds_write_b32 v35, v113 offset:16640
	v_add_u32_e32 v28, s20, v32
	v_add_u32_e32 v29, s20, v33
	v_add_u32_e32 v30, s20, v34
	v_add_u32_e32 v31, s20, v35
	v_add_u32_e32 v22, s18, v2
	v_add_u32_e32 v23, s18, v3
	v_mov_b32_e32 v24, s18
	v_add_u32_e32 v25, s19, v2
	v_add_u32_e32 v26, s19, v3
	v_mov_b32_e32 v27, s19
	v_mov_b32_e32 v6, 0
	v_mov_b32_e32 v7, 0
	v_mov_b32_e32 v8, 0
	v_mov_b32_e32 v9, 0
	v_mov_b32_e32 v10, 0
	v_mov_b32_e32 v11, 0
	v_mov_b32_e32 v12, 0
	v_mov_b32_e32 v13, 0
	v_mov_b32_e32 v14, 0
	v_mov_b32_e32 v15, 0
	v_mov_b32_e32 v16, 0
	v_mov_b32_e32 v17, 0
	v_mov_b32_e32 v18, 0
	v_mov_b32_e32 v19, 0
	v_mov_b32_e32 v20, 0
	v_mov_b32_e32 v21, 0
	v_mov_b32_e32 v51, 1.0
	s_mov_b32 s16, 0
	s_waitcnt vmcnt(0) lgkmcnt(0)
	s_barrier
	s_setprio 1
	global_load_dword v108, v36, s[8:9]
	global_load_dword v109, v36, s[8:9] offset:-2048
	global_load_dword v111, v104, s[8:9] offset:2048
	global_load_dword v110, v37, s[10:11]
	global_load_dword v112, v105, s[10:11]
	global_load_dword v113, v106, s[12:13]
	s_add_u32 s8, s8, 0xc000
	s_addc_u32 s9, s9, 0
	s_add_u32 s10, s10, 0x20000
	s_addc_u32 s11, s11, 0
	s_add_u32 s12, s12, 0x400
	s_addc_u32 s13, s13, 0
	ds_read_b128 v[56:59], v2 offset:256
	ds_read_b128 v[60:63], v2 offset:512
	ds_read_b128 v[64:67], v2 offset:768
	ds_read_b128 v[68:71], v2 offset:1024
	ds_read_b64 v[72:73], v3 offset:12544
	ds_read_b128 v[76:79], v1 offset:14592
.Lgd2_loop:
	s_waitcnt lgkmcnt(5)
	v_pk_mul_f32 v[38:39], v[6:7], v[56:57] op_sel_hi:[1,0]
	v_pk_mul_f32 v[40:41], v[6:7], v[56:57] op_sel:[0,1] op_sel_hi:[1,1]
	v_pk_fma_f32 v[38:39], v[8:9], v[58:59], v[38:39] op_sel_hi:[1,0,1]
	v_pk_fma_f32 v[40:41], v[8:9], v[58:59], v[40:41] op_sel:[0,1,0] op_sel_hi:[1,1,1]
	s_waitcnt lgkmcnt(4)
	v_pk_fma_f32 v[38:39], v[10:11], v[60:61], v[38:39] op_sel_hi:[1,0,1]
	v_pk_fma_f32 v[40:41], v[10:11], v[60:61], v[40:41] op_sel:[0,1,0] op_sel_hi:[1,1,1]
	v_pk_fma_f32 v[38:39], v[12:13], v[62:63], v[38:39] op_sel_hi:[1,0,1]
	v_pk_fma_f32 v[40:41], v[12:13], v[62:63], v[40:41] op_sel:[0,1,0] op_sel_hi:[1,1,1]
	s_waitcnt lgkmcnt(3)
	v_pk_fma_f32 v[38:39], v[14:15], v[64:65], v[38:39] op_sel_hi:[1,0,1]
	v_pk_fma_f32 v[40:41], v[14:15], v[64:65], v[40:41] op_sel:[0,1,0] op_sel_hi:[1,1,1]
	v_pk_fma_f32 v[38:39], v[16:17], v[66:67], v[38:39] op_sel_hi:[1,0,1]
	v_pk_fma_f32 v[40:41], v[16:17], v[66:67], v[40:41] op_sel:[0,1,0] op_sel_hi:[1,1,1]
	s_waitcnt lgkmcnt(2)
	v_pk_fma_f32 v[38:39], v[18:19], v[68:69], v[38:39] op_sel_hi:[1,0,1]
	v_pk_fma_f32 v[40:41], v[18:19], v[68:69], v[40:41] op_sel:[0,1,0] op_sel_hi:[1,1,1]
	v_pk_fma_f32 v[38:39], v[20:21], v[70:71], v[38:39] op_sel_hi:[1,0,1]
	v_pk_fma_f32 v[40:41], v[20:21], v[70:71], v[40:41] op_sel:[0,1,0] op_sel_hi:[1,1,1]
	s_waitcnt lgkmcnt(0)
	v_mul_f32_e32 v50, v76, v51
	v_add_f32_dpp v38, v38, v38 row_ror:8 row_mask:0xf bank_mask:0x3 bound_ctrl:1
	v_add_f32_dpp v39, v39, v39 row_ror:8 row_mask:0xf bank_mask:0x3 bound_ctrl:1
	v_add_f32_dpp v38, v40, v40 row_ror:8 row_mask:0xf bank_mask:0xc bound_ctrl:1
	v_add_f32_dpp v39, v41, v41 row_ror:8 row_mask:0xf bank_mask:0xc bound_ctrl:1
	ds_read_b128 v[80:83], v2 offset:1280
	v_add_f32_dpp v38, v38, v38 row_half_mirror row_mask:0xf bank_mask:0x5 bound_ctrl:1
	v_add_f32_dpp v38, v39, v39 row_half_mirror row_mask:0xf bank_mask:0xa bound_ctrl:1
	ds_read_b128 v[84:87], v2 offset:1536
	ds_read_b128 v[88:91], v2 offset:1792
	v_add_f32_dpp v38, v38, v38 quad_perm:[1,0,3,2] row_mask:0xf bank_mask:0xf bound_ctrl:1
	ds_read_b128 v[92:95], v2 offset:2048
	ds_read_b64 v[96:97], v3 offset:12800
	v_add_f32_dpp v38, v38, v38 quad_perm:[2,3,0,1] row_mask:0xf bank_mask:0xf bound_ctrl:1
	ds_read_b128 v[100:103], v1 offset:14608
	v_cmp_gt_f32_e32 vcc, 0x2b8cbccc, v50
	v_fmac_f32_dpp v72, -v38, v50 row_newbcast:0 row_mask:0xf bank_mask:0xf bound_ctrl:1
	v_fmac_f32_dpp v73, -v38, v50 row_newbcast:4 row_mask:0xf bank_mask:0xf bound_ctrl:1
	v_pk_mul_f32 v[44:45], v[72:73], v[76:77] op_sel:[0,1] op_sel_hi:[1,1]
	v_pk_mul_f32 v[48:49], v[44:45], v[78:79] op_sel_hi:[1,0]
	v_rcp_f32_e32 v52, v50
	s_add_u32 s14, s14, 0x1000
	s_addc_u32 s15, s15, 0
	v_fmac_f32_dpp v48, v38, v50 row_newbcast:8 row_mask:0xf bank_mask:0xf bound_ctrl:1
	v_fmac_f32_dpp v49, v38, v50 row_newbcast:12 row_mask:0xf bank_mask:0xf bound_ctrl:1
	s_cbranch_vccnz .Lgd2_rare0_0

.Lgd2_back0_7:
	v_cvt_pk_bf16_f32 v54, v48, v49
	v_pk_mul_f32 v[46:47], v[44:45], v[52:53] op_sel_hi:[1,0]
	v_pk_fma_f32 v[6:7], v[80:81], v[46:47], v[6:7] op_sel_hi:[0,1,1]
	v_pk_fma_f32 v[8:9], v[82:83], v[46:47], v[8:9] op_sel_hi:[0,1,1]
	v_pk_fma_f32 v[10:11], v[84:85], v[46:47], v[10:11] op_sel_hi:[0,1,1]
	v_pk_fma_f32 v[12:13], v[86:87], v[46:47], v[12:13] op_sel_hi:[0,1,1]
	v_pk_fma_f32 v[14:15], v[88:89], v[46:47], v[14:15] op_sel_hi:[0,1,1]
	v_pk_fma_f32 v[16:17], v[90:91], v[46:47], v[16:17] op_sel_hi:[0,1,1]
	v_pk_fma_f32 v[18:19], v[92:93], v[46:47], v[18:19] op_sel_hi:[0,1,1]
	v_pk_fma_f32 v[20:21], v[94:95], v[46:47], v[20:21] op_sel_hi:[0,1,1]
	global_store_dword v154, v54, s[14:15] offset:-4096
	s_waitcnt vmcnt(8)
	v_lshlrev_b32_e32 v116, 16, v108
	v_lshlrev_b32_e32 v117, 16, v109
	v_and_b32_e32 v118, s17, v108
	v_and_b32_e32 v119, s17, v109
	v_lshlrev_b32_e32 v120, 16, v110
	v_and_b32_e32 v121, s17, v110
	v_lshlrev_b32_e32 v122, 16, v111
	v_and_b32_e32 v123, s17, v111
	v_lshlrev_b32_e32 v124, 16, v112
	v_and_b32_e32 v125, s17, v112
	ds_write_b128 v32, v[116:119] offset:33024
	ds_write_b64 v33, v[120:121] offset:33024
	ds_write_b64 v34, v[122:123] offset:33024
	ds_write_b64 v34, v[124:125] offset:33152
	ds_write_b32 v35, v113 offset:33024
	s_add_i32 s16, s16, 8
	s_waitcnt lgkmcnt(0)
	global_load_dword v108, v36, s[8:9]
	global_load_dword v109, v36, s[8:9] offset:-2048
	global_load_dword v111, v104, s[8:9] offset:2048
	global_load_dword v110, v37, s[10:11]
	global_load_dword v112, v105, s[10:11]
	global_load_dword v113, v106, s[12:13]
	s_add_u32 s8, s8, 0xc000
	s_addc_u32 s9, s9, 0
	s_add_u32 s10, s10, 0x20000
	s_addc_u32 s11, s11, 0
	s_add_u32 s12, s12, 0x400
	s_addc_u32 s13, s13, 0
	s_barrier
	s_cmpk_lt_u32 s16, 0x800
	s_cbranch_scc0 .Lgd2_done
	s_waitcnt lgkmcnt(5)
	v_pk_mul_f32 v[38:39], v[6:7], v[56:57] op_sel_hi:[1,0]
	v_pk_mul_f32 v[40:41], v[6:7], v[56:57] op_sel:[0,1] op_sel_hi:[1,1]
	v_pk_fma_f32 v[38:39], v[8:9], v[58:59], v[38:39] op_sel_hi:[1,0,1]
	v_pk_fma_f32 v[40:41], v[8:9], v[58:59], v[40:41] op_sel:[0,1,0] op_sel_hi:[1,1,1]
	s_waitcnt lgkmcnt(4)
	v_pk_fma_f32 v[38:39], v[10:11], v[60:61], v[38:39] op_sel_hi:[1,0,1]
	v_pk_fma_f32 v[40:41], v[10:11], v[60:61], v[40:41] op_sel:[0,1,0] op_sel_hi:[1,1,1]
	v_pk_fma_f32 v[38:39], v[12:13], v[62:63], v[38:39] op_sel_hi:[1,0,1]
	v_pk_fma_f32 v[40:41], v[12:13], v[62:63], v[40:41] op_sel:[0,1,0] op_sel_hi:[1,1,1]
	s_waitcnt lgkmcnt(3)
	v_pk_fma_f32 v[38:39], v[14:15], v[64:65], v[38:39] op_sel_hi:[1,0,1]
	v_pk_fma_f32 v[40:41], v[14:15], v[64:65], v[40:41] op_sel:[0,1,0] op_sel_hi:[1,1,1]
	v_pk_fma_f32 v[38:39], v[16:17], v[66:67], v[38:39] op_sel_hi:[1,0,1]
	v_pk_fma_f32 v[40:41], v[16:17], v[66:67], v[40:41] op_sel:[0,1,0] op_sel_hi:[1,1,1]
	s_waitcnt lgkmcnt(2)
	v_pk_fma_f32 v[38:39], v[18:19], v[68:69], v[38:39] op_sel_hi:[1,0,1]
	v_pk_fma_f32 v[40:41], v[18:19], v[68:69], v[40:41] op_sel:[0,1,0] op_sel_hi:[1,1,1]
	v_pk_fma_f32 v[38:39], v[20:21], v[70:71], v[38:39] op_sel_hi:[1,0,1]
	v_pk_fma_f32 v[40:41], v[20:21], v[70:71], v[40:41] op_sel:[0,1,0] op_sel_hi:[1,1,1]
	s_waitcnt lgkmcnt(0)
	v_mul_f32_e32 v50, v76, v51
	v_add_f32_dpp v38, v38, v38 row_ror:8 row_mask:0xf bank_mask:0x3 bound_ctrl:1
	v_add_f32_dpp v39, v39, v39 row_ror:8 row_mask:0xf bank_mask:0x3 bound_ctrl:1
	v_add_f32_dpp v38, v40, v40 row_ror:8 row_mask:0xf bank_mask:0xc bound_ctrl:1
	v_add_f32_dpp v39, v41, v41 row_ror:8 row_mask:0xf bank_mask:0xc bound_ctrl:1
	ds_read_b128 v[80:83], v2 offset:17664
	v_add_f32_dpp v38, v38, v38 row_half_mirror row_mask:0xf bank_mask:0x5 bound_ctrl:1
	v_add_f32_dpp v38, v39, v39 row_half_mirror row_mask:0xf bank_mask:0xa bound_ctrl:1
	ds_read_b128 v[84:87], v2 offset:17920
	ds_read_b128 v[88:91], v2 offset:18176
	v_add_f32_dpp v38, v38, v38 quad_perm:[1,0,3,2] row_mask:0xf bank_mask:0xf bound_ctrl:1
	ds_read_b128 v[92:95], v2 offset:18432
	ds_read_b64 v[96:97], v3 offset:29184
	v_add_f32_dpp v38, v38, v38 quad_perm:[2,3,0,1] row_mask:0xf bank_mask:0xf bound_ctrl:1
	ds_read_b128 v[100:103], v1 offset:30992
	v_cmp_gt_f32_e32 vcc, 0x2b8cbccc, v50
	v_fmac_f32_dpp v72, -v38, v50 row_newbcast:0 row_mask:0xf bank_mask:0xf bound_ctrl:1
	v_fmac_f32_dpp v73, -v38, v50 row_newbcast:4 row_mask:0xf bank_mask:0xf bound_ctrl:1
	v_pk_mul_f32 v[44:45], v[72:73], v[76:77] op_sel:[0,1] op_sel_hi:[1,1]
	v_pk_mul_f32 v[48:49], v[44:45], v[78:79] op_sel_hi:[1,0]
	v_rcp_f32_e32 v52, v50
	s_add_u32 s14, s14, 0x1000
	s_addc_u32 s15, s15, 0
	v_fmac_f32_dpp v48, v38, v50 row_newbcast:8 row_mask:0xf bank_mask:0xf bound_ctrl:1
	v_fmac_f32_dpp v49, v38, v50 row_newbcast:12 row_mask:0xf bank_mask:0xf bound_ctrl:1
	s_cbranch_vccnz .Lgd2_rare1_0

.Lgd2_back1_7:
	v_cvt_pk_bf16_f32 v54, v48, v49
	v_pk_mul_f32 v[46:47], v[44:45], v[52:53] op_sel_hi:[1,0]
	v_pk_fma_f32 v[6:7], v[80:81], v[46:47], v[6:7] op_sel_hi:[0,1,1]
	v_pk_fma_f32 v[8:9], v[82:83], v[46:47], v[8:9] op_sel_hi:[0,1,1]
	v_pk_fma_f32 v[10:11], v[84:85], v[46:47], v[10:11] op_sel_hi:[0,1,1]
	v_pk_fma_f32 v[12:13], v[86:87], v[46:47], v[12:13] op_sel_hi:[0,1,1]
	v_pk_fma_f32 v[14:15], v[88:89], v[46:47], v[14:15] op_sel_hi:[0,1,1]
	v_pk_fma_f32 v[16:17], v[90:91], v[46:47], v[16:17] op_sel_hi:[0,1,1]
	v_pk_fma_f32 v[18:19], v[92:93], v[46:47], v[18:19] op_sel_hi:[0,1,1]
	v_pk_fma_f32 v[20:21], v[94:95], v[46:47], v[20:21] op_sel_hi:[0,1,1]
	global_store_dword v154, v54, s[14:15] offset:-4096
	s_waitcnt vmcnt(8)
	v_lshlrev_b32_e32 v116, 16, v108
	v_lshlrev_b32_e32 v117, 16, v109
	v_and_b32_e32 v118, s17, v108
	v_and_b32_e32 v119, s17, v109
	v_lshlrev_b32_e32 v120, 16, v110
	v_and_b32_e32 v121, s17, v110
	v_lshlrev_b32_e32 v122, 16, v111
	v_and_b32_e32 v123, s17, v111
	v_lshlrev_b32_e32 v124, 16, v112
	v_and_b32_e32 v125, s17, v112
	ds_write_b128 v32, v[116:119] offset:256
	ds_write_b64 v33, v[120:121] offset:256
	ds_write_b64 v34, v[122:123] offset:256
	ds_write_b64 v34, v[124:125] offset:384
	ds_write_b32 v35, v113 offset:256
	s_add_i32 s16, s16, 8
	s_waitcnt lgkmcnt(0)
	global_load_dword v108, v36, s[8:9]
	global_load_dword v109, v36, s[8:9] offset:-2048
	global_load_dword v111, v104, s[8:9] offset:2048
	global_load_dword v110, v37, s[10:11]
	global_load_dword v112, v105, s[10:11]
	global_load_dword v113, v106, s[12:13]
	s_add_u32 s8, s8, 0xc000
	s_addc_u32 s9, s9, 0
	s_add_u32 s10, s10, 0x20000
	s_addc_u32 s11, s11, 0
	s_add_u32 s12, s12, 0x400
	s_addc_u32 s13, s13, 0
	s_barrier
	s_cmpk_lt_u32 s16, 0x800
	s_cbranch_scc0 .Lgd2_done
	s_waitcnt lgkmcnt(5)
	v_pk_mul_f32 v[38:39], v[6:7], v[56:57] op_sel_hi:[1,0]
	v_pk_mul_f32 v[40:41], v[6:7], v[56:57] op_sel:[0,1] op_sel_hi:[1,1]
	v_pk_fma_f32 v[38:39], v[8:9], v[58:59], v[38:39] op_sel_hi:[1,0,1]
	v_pk_fma_f32 v[40:41], v[8:9], v[58:59], v[40:41] op_sel:[0,1,0] op_sel_hi:[1,1,1]
	s_waitcnt lgkmcnt(4)
	v_pk_fma_f32 v[38:39], v[10:11], v[60:61], v[38:39] op_sel_hi:[1,0,1]
	v_pk_fma_f32 v[40:41], v[10:11], v[60:61], v[40:41] op_sel:[0,1,0] op_sel_hi:[1,1,1]
	v_pk_fma_f32 v[38:39], v[12:13], v[62:63], v[38:39] op_sel_hi:[1,0,1]
	v_pk_fma_f32 v[40:41], v[12:13], v[62:63], v[40:41] op_sel:[0,1,0] op_sel_hi:[1,1,1]
	s_waitcnt lgkmcnt(3)
	v_pk_fma_f32 v[38:39], v[14:15], v[64:65], v[38:39] op_sel_hi:[1,0,1]
	v_pk_fma_f32 v[40:41], v[14:15], v[64:65], v[40:41] op_sel:[0,1,0] op_sel_hi:[1,1,1]
	v_pk_fma_f32 v[38:39], v[16:17], v[66:67], v[38:39] op_sel_hi:[1,0,1]
	v_pk_fma_f32 v[40:41], v[16:17], v[66:67], v[40:41] op_sel:[0,1,0] op_sel_hi:[1,1,1]
	s_waitcnt lgkmcnt(2)
	v_pk_fma_f32 v[38:39], v[18:19], v[68:69], v[38:39] op_sel_hi:[1,0,1]
	v_pk_fma_f32 v[40:41], v[18:19], v[68:69], v[40:41] op_sel:[0,1,0] op_sel_hi:[1,1,1]
	v_pk_fma_f32 v[38:39], v[20:21], v[70:71], v[38:39] op_sel_hi:[1,0,1]
	v_pk_fma_f32 v[40:41], v[20:21], v[70:71], v[40:41] op_sel:[0,1,0] op_sel_hi:[1,1,1]
	s_waitcnt lgkmcnt(0)
	v_mul_f32_e32 v50, v76, v51
	v_add_f32_dpp v38, v38, v38 row_ror:8 row_mask:0xf bank_mask:0x3 bound_ctrl:1
	v_add_f32_dpp v39, v39, v39 row_ror:8 row_mask:0xf bank_mask:0x3 bound_ctrl:1
	v_add_f32_dpp v38, v40, v40 row_ror:8 row_mask:0xf bank_mask:0xc bound_ctrl:1
	v_add_f32_dpp v39, v41, v41 row_ror:8 row_mask:0xf bank_mask:0xc bound_ctrl:1
	ds_read_b128 v[80:83], v2 offset:34048
	v_add_f32_dpp v38, v38, v38 row_half_mirror row_mask:0xf bank_mask:0x5 bound_ctrl:1
	v_add_f32_dpp v38, v39, v39 row_half_mirror row_mask:0xf bank_mask:0xa bound_ctrl:1
	ds_read_b128 v[84:87], v2 offset:34304
	ds_read_b128 v[88:91], v2 offset:34560
	v_add_f32_dpp v38, v38, v38 quad_perm:[1,0,3,2] row_mask:0xf bank_mask:0xf bound_ctrl:1
	ds_read_b128 v[92:95], v2 offset:34816
	ds_read_b64 v[96:97], v3 offset:45568
	v_add_f32_dpp v38, v38, v38 quad_perm:[2,3,0,1] row_mask:0xf bank_mask:0xf bound_ctrl:1
	ds_read_b128 v[100:103], v1 offset:47376
	v_cmp_gt_f32_e32 vcc, 0x2b8cbccc, v50
	v_fmac_f32_dpp v72, -v38, v50 row_newbcast:0 row_mask:0xf bank_mask:0xf bound_ctrl:1
	v_fmac_f32_dpp v73, -v38, v50 row_newbcast:4 row_mask:0xf bank_mask:0xf bound_ctrl:1
	v_pk_mul_f32 v[44:45], v[72:73], v[76:77] op_sel:[0,1] op_sel_hi:[1,1]
	v_pk_mul_f32 v[48:49], v[44:45], v[78:79] op_sel_hi:[1,0]
	v_rcp_f32_e32 v52, v50
	s_add_u32 s14, s14, 0x1000
	s_addc_u32 s15, s15, 0
	v_fmac_f32_dpp v48, v38, v50 row_newbcast:8 row_mask:0xf bank_mask:0xf bound_ctrl:1
	v_fmac_f32_dpp v49, v38, v50 row_newbcast:12 row_mask:0xf bank_mask:0xf bound_ctrl:1
	s_cbranch_vccnz .Lgd2_rare2_0

.Lgd2_back2_7:
	v_cvt_pk_bf16_f32 v54, v48, v49
	v_pk_mul_f32 v[46:47], v[44:45], v[52:53] op_sel_hi:[1,0]
	v_pk_fma_f32 v[6:7], v[80:81], v[46:47], v[6:7] op_sel_hi:[0,1,1]
	v_pk_fma_f32 v[8:9], v[82:83], v[46:47], v[8:9] op_sel_hi:[0,1,1]
	v_pk_fma_f32 v[10:11], v[84:85], v[46:47], v[10:11] op_sel_hi:[0,1,1]
	v_pk_fma_f32 v[12:13], v[86:87], v[46:47], v[12:13] op_sel_hi:[0,1,1]
	v_pk_fma_f32 v[14:15], v[88:89], v[46:47], v[14:15] op_sel_hi:[0,1,1]
	v_pk_fma_f32 v[16:17], v[90:91], v[46:47], v[16:17] op_sel_hi:[0,1,1]
	v_pk_fma_f32 v[18:19], v[92:93], v[46:47], v[18:19] op_sel_hi:[0,1,1]
	v_pk_fma_f32 v[20:21], v[94:95], v[46:47], v[20:21] op_sel_hi:[0,1,1]
	global_store_dword v154, v54, s[14:15] offset:-4096
	s_waitcnt vmcnt(8)
	v_lshlrev_b32_e32 v116, 16, v108
	v_lshlrev_b32_e32 v117, 16, v109
	v_and_b32_e32 v118, s17, v108
	v_and_b32_e32 v119, s17, v109
	v_lshlrev_b32_e32 v120, 16, v110
	v_and_b32_e32 v121, s17, v110
	v_lshlrev_b32_e32 v122, 16, v111
	v_and_b32_e32 v123, s17, v111
	v_lshlrev_b32_e32 v124, 16, v112
	v_and_b32_e32 v125, s17, v112
	ds_write_b128 v32, v[116:119] offset:16640
	ds_write_b64 v33, v[120:121] offset:16640
	ds_write_b64 v34, v[122:123] offset:16640
	ds_write_b64 v34, v[124:125] offset:16768
	ds_write_b32 v35, v113 offset:16640
	s_add_i32 s16, s16, 8
	s_waitcnt lgkmcnt(0)
	global_load_dword v108, v36, s[8:9]
	global_load_dword v109, v36, s[8:9] offset:-2048
	global_load_dword v111, v104, s[8:9] offset:2048
	global_load_dword v110, v37, s[10:11]
	global_load_dword v112, v105, s[10:11]
	global_load_dword v113, v106, s[12:13]
	s_add_u32 s8, s8, 0xc000
	s_addc_u32 s9, s9, 0
	s_add_u32 s10, s10, 0x20000
	s_addc_u32 s11, s11, 0
	s_add_u32 s12, s12, 0x400
	s_addc_u32 s13, s13, 0
	s_barrier
	s_cmpk_lt_u32 s16, 0x800
	s_cbranch_scc1 .Lgd2_loop
.Lgd2_done:
	s_waitcnt vmcnt(0)
	s_setprio 0
	s_lshr_b32 s2, s27, 4
	s_lshl_b32 s4, s2, 16
	s_add_u32 s4, s4, 0x4080000
	s_add_u32 s0, s24, s4
	s_addc_u32 s1, s25, 0
	v_pk_mul_f32 v[108:109], v[6:7], v[50:51] op_sel:[0,1] op_sel_hi:[1,1]
	global_store_dwordx2 v153, v[108:109], s[0:1] offset:0
	v_pk_mul_f32 v[110:111], v[8:9], v[50:51] op_sel:[0,1] op_sel_hi:[1,1]
	global_store_dwordx2 v153, v[110:111], s[0:1] offset:512
	v_pk_mul_f32 v[108:109], v[10:11], v[50:51] op_sel:[0,1] op_sel_hi:[1,1]
	global_store_dwordx2 v153, v[108:109], s[0:1] offset:1024
	v_pk_mul_f32 v[110:111], v[12:13], v[50:51] op_sel:[0,1] op_sel_hi:[1,1]
	global_store_dwordx2 v153, v[110:111], s[0:1] offset:1536
	v_pk_mul_f32 v[108:109], v[14:15], v[50:51] op_sel:[0,1] op_sel_hi:[1,1]
	global_store_dwordx2 v153, v[108:109], s[0:1] offset:2048
	v_pk_mul_f32 v[110:111], v[16:17], v[50:51] op_sel:[0,1] op_sel_hi:[1,1]
	global_store_dwordx2 v153, v[110:111], s[0:1] offset:2560
	v_pk_mul_f32 v[108:109], v[18:19], v[50:51] op_sel:[0,1] op_sel_hi:[1,1]
	global_store_dwordx2 v153, v[108:109], s[0:1] offset:3072
	v_pk_mul_f32 v[110:111], v[20:21], v[50:51] op_sel:[0,1] op_sel_hi:[1,1]
	global_store_dwordx2 v153, v[110:111], s[0:1] offset:3584
	s_add_i32 s27, s27, s28
	s_waitcnt vmcnt(0)
	s_cmpk_lt_i32 s27, 0x400
	s_cbranch_scc1 .Lgd2_item
	s_branch .LBB0_232
